# scan inner loop: triple-buffered step operands, LDS reads two steps ahead
# baseline (speedup 1.0000x reference)
.LBB0_985:
	s_and_saveexec_b64 s[24:25], s[16:17]
	s_cbranch_execz .LBB0_988
	ds_read_b128 v[30:33], v161 offset:8192
	ds_read_b128 v[34:37], v161 offset:16384
	ds_read_b128 v[46:49], v161 offset:24576
	ds_read_b64 v[80:81], v82 offset:40960
	ds_read_b128 v[38:41], v161
	ds_read_b128 v[42:45], v161 offset:32768
	ds_read_b128 v[84:87], v161 offset:8448
	ds_read_b128 v[88:91], v161 offset:16640
	ds_read_b128 v[100:103], v161 offset:24832
	ds_read_b64 v[104:105], v82 offset:41216
	ds_read_b128 v[92:95], v161 offset:256
	ds_read_b128 v[96:99], v161 offset:33024
	s_waitcnt lgkmcnt(6)
	ds_read_b128 v[128:131], v161 offset:8704
	ds_read_b128 v[132:135], v161 offset:16896
	ds_read_b128 v[194:197], v161 offset:25088
	ds_read_b64 v[198:199], v82 offset:41472
	ds_read_b128 v[136:139], v161 offset:512
	ds_read_b128 v[140:143], v161 offset:33280
	v_pk_mul_f32 v[106:107], v[72:73], v[30:31]
	v_pk_mul_f32 v[108:109], v[76:77], v[30:31]
	v_pk_fma_f32 v[106:107], v[74:75], v[32:33], v[106:107]
	v_pk_fma_f32 v[108:109], v[78:79], v[32:33], v[108:109]
	v_add_f32_e32 v110, v106, v107
	v_add_f32_e32 v112, v108, v109
	s_nop 0
	v_add_f32_dpp v110, v110, v110 quad_perm:[1,0,3,2] row_mask:0xf bank_mask:0xf bound_ctrl:1
	v_add_f32_dpp v112, v112, v112 quad_perm:[1,0,3,2] row_mask:0xf bank_mask:0xf bound_ctrl:1
	s_nop 0
	v_add_f32_dpp v110, v110, v110 quad_perm:[2,3,0,1] row_mask:0xf bank_mask:0xf bound_ctrl:1
	v_add_f32_dpp v112, v112, v112 quad_perm:[2,3,0,1] row_mask:0xf bank_mask:0xf bound_ctrl:1
	s_nop 0
	v_add_f32_dpp v110, v110, v110 row_half_mirror row_mask:0xf bank_mask:0xf bound_ctrl:1
	v_add_f32_dpp v112, v112, v112 row_half_mirror row_mask:0xf bank_mask:0xf bound_ctrl:1
	s_nop 0
	v_add_f32_dpp v110, v110, v110 row_ror:8 row_mask:0xf bank_mask:0xf bound_ctrl:1
	v_add_f32_dpp v112, v112, v112 row_ror:8 row_mask:0xf bank_mask:0xf bound_ctrl:1
	v_pk_mul_f32 v[114:115], v[34:35], v[110:111] op_sel_hi:[1,0]
	v_pk_mul_f32 v[116:117], v[34:35], v[112:113] op_sel_hi:[1,0]
	v_pk_mul_f32 v[118:119], v[36:37], v[110:111] op_sel_hi:[1,0]
	v_pk_mul_f32 v[120:121], v[36:37], v[112:113] op_sel_hi:[1,0]
	v_pk_fma_f32 v[114:115], v[46:47], v[80:81], v[114:115] op_sel_hi:[1,0,1]
	v_pk_fma_f32 v[116:117], v[46:47], v[80:81], v[116:117] op_sel:[0,1,0]
	v_pk_fma_f32 v[118:119], v[48:49], v[80:81], v[118:119] op_sel_hi:[1,0,1]
	v_pk_fma_f32 v[120:121], v[48:49], v[80:81], v[120:121] op_sel:[0,1,0]
	v_pk_fma_f32 v[72:73], v[72:73], v[38:39], v[114:115]
	v_pk_fma_f32 v[76:77], v[76:77], v[38:39], v[116:117]
	v_pk_fma_f32 v[74:75], v[74:75], v[40:41], v[118:119]
	v_pk_fma_f32 v[78:79], v[78:79], v[40:41], v[120:121]
	v_pk_mul_f32 v[122:123], v[72:73], v[42:43]
	v_pk_mul_f32 v[124:125], v[76:77], v[42:43]
	v_pk_fma_f32 v[122:123], v[74:75], v[44:45], v[122:123]
	v_pk_fma_f32 v[124:125], v[78:79], v[44:45], v[124:125]
	v_add_f32_e32 v126, v122, v123
	v_add_f32_e32 v127, v124, v125
	ds_write_b64 v187, v[126:127]
	s_waitcnt lgkmcnt(7)
	ds_read_b128 v[30:33], v161 offset:8960
	ds_read_b128 v[34:37], v161 offset:17152
	ds_read_b128 v[46:49], v161 offset:25344
	ds_read_b64 v[80:81], v82 offset:41728
	ds_read_b128 v[38:41], v161 offset:768
	ds_read_b128 v[42:45], v161 offset:33536
	v_pk_mul_f32 v[106:107], v[72:73], v[84:85]
	v_pk_mul_f32 v[108:109], v[76:77], v[84:85]
	v_pk_fma_f32 v[106:107], v[74:75], v[86:87], v[106:107]
	v_pk_fma_f32 v[108:109], v[78:79], v[86:87], v[108:109]
	v_add_f32_e32 v110, v106, v107
	v_add_f32_e32 v112, v108, v109
	s_nop 0
	v_add_f32_dpp v110, v110, v110 quad_perm:[1,0,3,2] row_mask:0xf bank_mask:0xf bound_ctrl:1
	v_add_f32_dpp v112, v112, v112 quad_perm:[1,0,3,2] row_mask:0xf bank_mask:0xf bound_ctrl:1
	s_nop 0
	v_add_f32_dpp v110, v110, v110 quad_perm:[2,3,0,1] row_mask:0xf bank_mask:0xf bound_ctrl:1
	v_add_f32_dpp v112, v112, v112 quad_perm:[2,3,0,1] row_mask:0xf bank_mask:0xf bound_ctrl:1
	s_nop 0
	v_add_f32_dpp v110, v110, v110 row_half_mirror row_mask:0xf bank_mask:0xf bound_ctrl:1
	v_add_f32_dpp v112, v112, v112 row_half_mirror row_mask:0xf bank_mask:0xf bound_ctrl:1
	s_nop 0
	v_add_f32_dpp v110, v110, v110 row_ror:8 row_mask:0xf bank_mask:0xf bound_ctrl:1
	v_add_f32_dpp v112, v112, v112 row_ror:8 row_mask:0xf bank_mask:0xf bound_ctrl:1
	v_pk_mul_f32 v[114:115], v[88:89], v[110:111] op_sel_hi:[1,0]
	v_pk_mul_f32 v[116:117], v[88:89], v[112:113] op_sel_hi:[1,0]
	v_pk_mul_f32 v[118:119], v[90:91], v[110:111] op_sel_hi:[1,0]
	v_pk_mul_f32 v[120:121], v[90:91], v[112:113] op_sel_hi:[1,0]
	v_pk_fma_f32 v[114:115], v[100:101], v[104:105], v[114:115] op_sel_hi:[1,0,1]
	v_pk_fma_f32 v[116:117], v[100:101], v[104:105], v[116:117] op_sel:[0,1,0]
	v_pk_fma_f32 v[118:119], v[102:103], v[104:105], v[118:119] op_sel_hi:[1,0,1]
	v_pk_fma_f32 v[120:121], v[102:103], v[104:105], v[120:121] op_sel:[0,1,0]
	v_pk_fma_f32 v[72:73], v[72:73], v[92:93], v[114:115]
	v_pk_fma_f32 v[76:77], v[76:77], v[92:93], v[116:117]
	v_pk_fma_f32 v[74:75], v[74:75], v[94:95], v[118:119]
	v_pk_fma_f32 v[78:79], v[78:79], v[94:95], v[120:121]
	v_pk_mul_f32 v[122:123], v[72:73], v[96:97]
	v_pk_mul_f32 v[124:125], v[76:77], v[96:97]
	v_pk_fma_f32 v[122:123], v[74:75], v[98:99], v[122:123]
	v_pk_fma_f32 v[124:125], v[78:79], v[98:99], v[124:125]
	v_add_f32_e32 v126, v122, v123
	v_add_f32_e32 v127, v124, v125
	ds_write_b64 v187, v[126:127] offset:2048
	s_waitcnt lgkmcnt(8)
	ds_read_b128 v[84:87], v161 offset:9216
	ds_read_b128 v[88:91], v161 offset:17408
	ds_read_b128 v[100:103], v161 offset:25600
	ds_read_b64 v[104:105], v82 offset:41984
	ds_read_b128 v[92:95], v161 offset:1024
	ds_read_b128 v[96:99], v161 offset:33792
	v_pk_mul_f32 v[106:107], v[72:73], v[128:129]
	v_pk_mul_f32 v[108:109], v[76:77], v[128:129]
	v_pk_fma_f32 v[106:107], v[74:75], v[130:131], v[106:107]
	v_pk_fma_f32 v[108:109], v[78:79], v[130:131], v[108:109]
	v_add_f32_e32 v110, v106, v107
	v_add_f32_e32 v112, v108, v109
	s_nop 0
	v_add_f32_dpp v110, v110, v110 quad_perm:[1,0,3,2] row_mask:0xf bank_mask:0xf bound_ctrl:1
	v_add_f32_dpp v112, v112, v112 quad_perm:[1,0,3,2] row_mask:0xf bank_mask:0xf bound_ctrl:1
	s_nop 0
	v_add_f32_dpp v110, v110, v110 quad_perm:[2,3,0,1] row_mask:0xf bank_mask:0xf bound_ctrl:1
	v_add_f32_dpp v112, v112, v112 quad_perm:[2,3,0,1] row_mask:0xf bank_mask:0xf bound_ctrl:1
	s_nop 0
	v_add_f32_dpp v110, v110, v110 row_half_mirror row_mask:0xf bank_mask:0xf bound_ctrl:1
	v_add_f32_dpp v112, v112, v112 row_half_mirror row_mask:0xf bank_mask:0xf bound_ctrl:1
	s_nop 0
	v_add_f32_dpp v110, v110, v110 row_ror:8 row_mask:0xf bank_mask:0xf bound_ctrl:1
	v_add_f32_dpp v112, v112, v112 row_ror:8 row_mask:0xf bank_mask:0xf bound_ctrl:1
	v_pk_mul_f32 v[114:115], v[132:133], v[110:111] op_sel_hi:[1,0]
	v_pk_mul_f32 v[116:117], v[132:133], v[112:113] op_sel_hi:[1,0]
	v_pk_mul_f32 v[118:119], v[134:135], v[110:111] op_sel_hi:[1,0]
	v_pk_mul_f32 v[120:121], v[134:135], v[112:113] op_sel_hi:[1,0]
	v_pk_fma_f32 v[114:115], v[194:195], v[198:199], v[114:115] op_sel_hi:[1,0,1]
	v_pk_fma_f32 v[116:117], v[194:195], v[198:199], v[116:117] op_sel:[0,1,0]
	v_pk_fma_f32 v[118:119], v[196:197], v[198:199], v[118:119] op_sel_hi:[1,0,1]
	v_pk_fma_f32 v[120:121], v[196:197], v[198:199], v[120:121] op_sel:[0,1,0]
	v_pk_fma_f32 v[72:73], v[72:73], v[136:137], v[114:115]
	v_pk_fma_f32 v[76:77], v[76:77], v[136:137], v[116:117]
	v_pk_fma_f32 v[74:75], v[74:75], v[138:139], v[118:119]
	v_pk_fma_f32 v[78:79], v[78:79], v[138:139], v[120:121]
	v_pk_mul_f32 v[122:123], v[72:73], v[140:141]
	v_pk_mul_f32 v[124:125], v[76:77], v[140:141]
	v_pk_fma_f32 v[122:123], v[74:75], v[142:143], v[122:123]
	v_pk_fma_f32 v[124:125], v[78:79], v[142:143], v[124:125]
	v_add_f32_e32 v126, v122, v123
	v_add_f32_e32 v127, v124, v125
	ds_write_b64 v187, v[126:127] offset:4096
	s_waitcnt lgkmcnt(8)
	ds_read_b128 v[128:131], v161 offset:9472
	ds_read_b128 v[132:135], v161 offset:17664
	ds_read_b128 v[194:197], v161 offset:25856
	ds_read_b64 v[198:199], v82 offset:42240
	ds_read_b128 v[136:139], v161 offset:1280
	ds_read_b128 v[140:143], v161 offset:34048
	v_pk_mul_f32 v[106:107], v[72:73], v[30:31]
	v_pk_mul_f32 v[108:109], v[76:77], v[30:31]
	v_pk_fma_f32 v[106:107], v[74:75], v[32:33], v[106:107]
	v_pk_fma_f32 v[108:109], v[78:79], v[32:33], v[108:109]
	v_add_f32_e32 v110, v106, v107
	v_add_f32_e32 v112, v108, v109
	s_nop 0
	v_add_f32_dpp v110, v110, v110 quad_perm:[1,0,3,2] row_mask:0xf bank_mask:0xf bound_ctrl:1
	v_add_f32_dpp v112, v112, v112 quad_perm:[1,0,3,2] row_mask:0xf bank_mask:0xf bound_ctrl:1
	s_nop 0
	v_add_f32_dpp v110, v110, v110 quad_perm:[2,3,0,1] row_mask:0xf bank_mask:0xf bound_ctrl:1
	v_add_f32_dpp v112, v112, v112 quad_perm:[2,3,0,1] row_mask:0xf bank_mask:0xf bound_ctrl:1
	s_nop 0
	v_add_f32_dpp v110, v110, v110 row_half_mirror row_mask:0xf bank_mask:0xf bound_ctrl:1
	v_add_f32_dpp v112, v112, v112 row_half_mirror row_mask:0xf bank_mask:0xf bound_ctrl:1
	s_nop 0
	v_add_f32_dpp v110, v110, v110 row_ror:8 row_mask:0xf bank_mask:0xf bound_ctrl:1
	v_add_f32_dpp v112, v112, v112 row_ror:8 row_mask:0xf bank_mask:0xf bound_ctrl:1
	v_pk_mul_f32 v[114:115], v[34:35], v[110:111] op_sel_hi:[1,0]
	v_pk_mul_f32 v[116:117], v[34:35], v[112:113] op_sel_hi:[1,0]
	v_pk_mul_f32 v[118:119], v[36:37], v[110:111] op_sel_hi:[1,0]
	v_pk_mul_f32 v[120:121], v[36:37], v[112:113] op_sel_hi:[1,0]
	v_pk_fma_f32 v[114:115], v[46:47], v[80:81], v[114:115] op_sel_hi:[1,0,1]
	v_pk_fma_f32 v[116:117], v[46:47], v[80:81], v[116:117] op_sel:[0,1,0]
	v_pk_fma_f32 v[118:119], v[48:49], v[80:81], v[118:119] op_sel_hi:[1,0,1]
	v_pk_fma_f32 v[120:121], v[48:49], v[80:81], v[120:121] op_sel:[0,1,0]
	v_pk_fma_f32 v[72:73], v[72:73], v[38:39], v[114:115]
	v_pk_fma_f32 v[76:77], v[76:77], v[38:39], v[116:117]
	v_pk_fma_f32 v[74:75], v[74:75], v[40:41], v[118:119]
	v_pk_fma_f32 v[78:79], v[78:79], v[40:41], v[120:121]
	v_pk_mul_f32 v[122:123], v[72:73], v[42:43]
	v_pk_mul_f32 v[124:125], v[76:77], v[42:43]
	v_pk_fma_f32 v[122:123], v[74:75], v[44:45], v[122:123]
	v_pk_fma_f32 v[124:125], v[78:79], v[44:45], v[124:125]
	v_add_f32_e32 v126, v122, v123
	v_add_f32_e32 v127, v124, v125
	ds_write_b64 v187, v[126:127] offset:6144
	s_waitcnt lgkmcnt(8)
	ds_read_b128 v[30:33], v161 offset:9728
	ds_read_b128 v[34:37], v161 offset:17920
	ds_read_b128 v[46:49], v161 offset:26112
	ds_read_b64 v[80:81], v82 offset:42496
	ds_read_b128 v[38:41], v161 offset:1536
	ds_read_b128 v[42:45], v161 offset:34304
	v_pk_mul_f32 v[106:107], v[72:73], v[84:85]
	v_pk_mul_f32 v[108:109], v[76:77], v[84:85]
	v_pk_fma_f32 v[106:107], v[74:75], v[86:87], v[106:107]
	v_pk_fma_f32 v[108:109], v[78:79], v[86:87], v[108:109]
	v_add_f32_e32 v110, v106, v107
	v_add_f32_e32 v112, v108, v109
	s_nop 0
	v_add_f32_dpp v110, v110, v110 quad_perm:[1,0,3,2] row_mask:0xf bank_mask:0xf bound_ctrl:1
	v_add_f32_dpp v112, v112, v112 quad_perm:[1,0,3,2] row_mask:0xf bank_mask:0xf bound_ctrl:1
	s_nop 0
	v_add_f32_dpp v110, v110, v110 quad_perm:[2,3,0,1] row_mask:0xf bank_mask:0xf bound_ctrl:1
	v_add_f32_dpp v112, v112, v112 quad_perm:[2,3,0,1] row_mask:0xf bank_mask:0xf bound_ctrl:1
	s_nop 0
	v_add_f32_dpp v110, v110, v110 row_half_mirror row_mask:0xf bank_mask:0xf bound_ctrl:1
	v_add_f32_dpp v112, v112, v112 row_half_mirror row_mask:0xf bank_mask:0xf bound_ctrl:1
	s_nop 0
	v_add_f32_dpp v110, v110, v110 row_ror:8 row_mask:0xf bank_mask:0xf bound_ctrl:1
	v_add_f32_dpp v112, v112, v112 row_ror:8 row_mask:0xf bank_mask:0xf bound_ctrl:1
	v_pk_mul_f32 v[114:115], v[88:89], v[110:111] op_sel_hi:[1,0]
	v_pk_mul_f32 v[116:117], v[88:89], v[112:113] op_sel_hi:[1,0]
	v_pk_mul_f32 v[118:119], v[90:91], v[110:111] op_sel_hi:[1,0]
	v_pk_mul_f32 v[120:121], v[90:91], v[112:113] op_sel_hi:[1,0]
	v_pk_fma_f32 v[114:115], v[100:101], v[104:105], v[114:115] op_sel_hi:[1,0,1]
	v_pk_fma_f32 v[116:117], v[100:101], v[104:105], v[116:117] op_sel:[0,1,0]
	v_pk_fma_f32 v[118:119], v[102:103], v[104:105], v[118:119] op_sel_hi:[1,0,1]
	v_pk_fma_f32 v[120:121], v[102:103], v[104:105], v[120:121] op_sel:[0,1,0]
	v_pk_fma_f32 v[72:73], v[72:73], v[92:93], v[114:115]
	v_pk_fma_f32 v[76:77], v[76:77], v[92:93], v[116:117]
	v_pk_fma_f32 v[74:75], v[74:75], v[94:95], v[118:119]
	v_pk_fma_f32 v[78:79], v[78:79], v[94:95], v[120:121]
	v_pk_mul_f32 v[122:123], v[72:73], v[96:97]
	v_pk_mul_f32 v[124:125], v[76:77], v[96:97]
	v_pk_fma_f32 v[122:123], v[74:75], v[98:99], v[122:123]
	v_pk_fma_f32 v[124:125], v[78:79], v[98:99], v[124:125]
	v_add_f32_e32 v126, v122, v123
	v_add_f32_e32 v127, v124, v125
	ds_write_b64 v187, v[126:127] offset:8192
	s_waitcnt lgkmcnt(8)
	ds_read_b128 v[84:87], v161 offset:9984
	ds_read_b128 v[88:91], v161 offset:18176
	ds_read_b128 v[100:103], v161 offset:26368
	ds_read_b64 v[104:105], v82 offset:42752
	ds_read_b128 v[92:95], v161 offset:1792
	ds_read_b128 v[96:99], v161 offset:34560
	v_pk_mul_f32 v[106:107], v[72:73], v[128:129]
	v_pk_mul_f32 v[108:109], v[76:77], v[128:129]
	v_pk_fma_f32 v[106:107], v[74:75], v[130:131], v[106:107]
	v_pk_fma_f32 v[108:109], v[78:79], v[130:131], v[108:109]
	v_add_f32_e32 v110, v106, v107
	v_add_f32_e32 v112, v108, v109
	s_nop 0
	v_add_f32_dpp v110, v110, v110 quad_perm:[1,0,3,2] row_mask:0xf bank_mask:0xf bound_ctrl:1
	v_add_f32_dpp v112, v112, v112 quad_perm:[1,0,3,2] row_mask:0xf bank_mask:0xf bound_ctrl:1
	s_nop 0
	v_add_f32_dpp v110, v110, v110 quad_perm:[2,3,0,1] row_mask:0xf bank_mask:0xf bound_ctrl:1
	v_add_f32_dpp v112, v112, v112 quad_perm:[2,3,0,1] row_mask:0xf bank_mask:0xf bound_ctrl:1
	s_nop 0
	v_add_f32_dpp v110, v110, v110 row_half_mirror row_mask:0xf bank_mask:0xf bound_ctrl:1
	v_add_f32_dpp v112, v112, v112 row_half_mirror row_mask:0xf bank_mask:0xf bound_ctrl:1
	s_nop 0
	v_add_f32_dpp v110, v110, v110 row_ror:8 row_mask:0xf bank_mask:0xf bound_ctrl:1
	v_add_f32_dpp v112, v112, v112 row_ror:8 row_mask:0xf bank_mask:0xf bound_ctrl:1
	v_pk_mul_f32 v[114:115], v[132:133], v[110:111] op_sel_hi:[1,0]
	v_pk_mul_f32 v[116:117], v[132:133], v[112:113] op_sel_hi:[1,0]
	v_pk_mul_f32 v[118:119], v[134:135], v[110:111] op_sel_hi:[1,0]
	v_pk_mul_f32 v[120:121], v[134:135], v[112:113] op_sel_hi:[1,0]
	v_pk_fma_f32 v[114:115], v[194:195], v[198:199], v[114:115] op_sel_hi:[1,0,1]
	v_pk_fma_f32 v[116:117], v[194:195], v[198:199], v[116:117] op_sel:[0,1,0]
	v_pk_fma_f32 v[118:119], v[196:197], v[198:199], v[118:119] op_sel_hi:[1,0,1]
	v_pk_fma_f32 v[120:121], v[196:197], v[198:199], v[120:121] op_sel:[0,1,0]
	v_pk_fma_f32 v[72:73], v[72:73], v[136:137], v[114:115]
	v_pk_fma_f32 v[76:77], v[76:77], v[136:137], v[116:117]
	v_pk_fma_f32 v[74:75], v[74:75], v[138:139], v[118:119]
	v_pk_fma_f32 v[78:79], v[78:79], v[138:139], v[120:121]
	v_pk_mul_f32 v[122:123], v[72:73], v[140:141]
	v_pk_mul_f32 v[124:125], v[76:77], v[140:141]
	v_pk_fma_f32 v[122:123], v[74:75], v[142:143], v[122:123]
	v_pk_fma_f32 v[124:125], v[78:79], v[142:143], v[124:125]
	v_add_f32_e32 v126, v122, v123
	v_add_f32_e32 v127, v124, v125
	ds_write_b64 v187, v[126:127] offset:10240
	s_waitcnt lgkmcnt(8)
	ds_read_b128 v[128:131], v161 offset:10240
	ds_read_b128 v[132:135], v161 offset:18432
	ds_read_b128 v[194:197], v161 offset:26624
	ds_read_b64 v[198:199], v82 offset:43008
	ds_read_b128 v[136:139], v161 offset:2048
	ds_read_b128 v[140:143], v161 offset:34816
	v_pk_mul_f32 v[106:107], v[72:73], v[30:31]
	v_pk_mul_f32 v[108:109], v[76:77], v[30:31]
	v_pk_fma_f32 v[106:107], v[74:75], v[32:33], v[106:107]
	v_pk_fma_f32 v[108:109], v[78:79], v[32:33], v[108:109]
	v_add_f32_e32 v110, v106, v107
	v_add_f32_e32 v112, v108, v109
	s_nop 0
	v_add_f32_dpp v110, v110, v110 quad_perm:[1,0,3,2] row_mask:0xf bank_mask:0xf bound_ctrl:1
	v_add_f32_dpp v112, v112, v112 quad_perm:[1,0,3,2] row_mask:0xf bank_mask:0xf bound_ctrl:1
	s_nop 0
	v_add_f32_dpp v110, v110, v110 quad_perm:[2,3,0,1] row_mask:0xf bank_mask:0xf bound_ctrl:1
	v_add_f32_dpp v112, v112, v112 quad_perm:[2,3,0,1] row_mask:0xf bank_mask:0xf bound_ctrl:1
	s_nop 0
	v_add_f32_dpp v110, v110, v110 row_half_mirror row_mask:0xf bank_mask:0xf bound_ctrl:1
	v_add_f32_dpp v112, v112, v112 row_half_mirror row_mask:0xf bank_mask:0xf bound_ctrl:1
	s_nop 0
	v_add_f32_dpp v110, v110, v110 row_ror:8 row_mask:0xf bank_mask:0xf bound_ctrl:1
	v_add_f32_dpp v112, v112, v112 row_ror:8 row_mask:0xf bank_mask:0xf bound_ctrl:1
	v_pk_mul_f32 v[114:115], v[34:35], v[110:111] op_sel_hi:[1,0]
	v_pk_mul_f32 v[116:117], v[34:35], v[112:113] op_sel_hi:[1,0]
	v_pk_mul_f32 v[118:119], v[36:37], v[110:111] op_sel_hi:[1,0]
	v_pk_mul_f32 v[120:121], v[36:37], v[112:113] op_sel_hi:[1,0]
	v_pk_fma_f32 v[114:115], v[46:47], v[80:81], v[114:115] op_sel_hi:[1,0,1]
	v_pk_fma_f32 v[116:117], v[46:47], v[80:81], v[116:117] op_sel:[0,1,0]
	v_pk_fma_f32 v[118:119], v[48:49], v[80:81], v[118:119] op_sel_hi:[1,0,1]
	v_pk_fma_f32 v[120:121], v[48:49], v[80:81], v[120:121] op_sel:[0,1,0]
	v_pk_fma_f32 v[72:73], v[72:73], v[38:39], v[114:115]
	v_pk_fma_f32 v[76:77], v[76:77], v[38:39], v[116:117]
	v_pk_fma_f32 v[74:75], v[74:75], v[40:41], v[118:119]
	v_pk_fma_f32 v[78:79], v[78:79], v[40:41], v[120:121]
	v_pk_mul_f32 v[122:123], v[72:73], v[42:43]
	v_pk_mul_f32 v[124:125], v[76:77], v[42:43]
	v_pk_fma_f32 v[122:123], v[74:75], v[44:45], v[122:123]
	v_pk_fma_f32 v[124:125], v[78:79], v[44:45], v[124:125]
	v_add_f32_e32 v126, v122, v123
	v_add_f32_e32 v127, v124, v125
	ds_write_b64 v187, v[126:127] offset:12288
	s_waitcnt lgkmcnt(8)
	ds_read_b128 v[30:33], v161 offset:10496
	ds_read_b128 v[34:37], v161 offset:18688
	ds_read_b128 v[46:49], v161 offset:26880
	ds_read_b64 v[80:81], v82 offset:43264
	ds_read_b128 v[38:41], v161 offset:2304
	ds_read_b128 v[42:45], v161 offset:35072
	v_pk_mul_f32 v[106:107], v[72:73], v[84:85]
	v_pk_mul_f32 v[108:109], v[76:77], v[84:85]
	v_pk_fma_f32 v[106:107], v[74:75], v[86:87], v[106:107]
	v_pk_fma_f32 v[108:109], v[78:79], v[86:87], v[108:109]
	v_add_f32_e32 v110, v106, v107
	v_add_f32_e32 v112, v108, v109
	s_nop 0
	v_add_f32_dpp v110, v110, v110 quad_perm:[1,0,3,2] row_mask:0xf bank_mask:0xf bound_ctrl:1
	v_add_f32_dpp v112, v112, v112 quad_perm:[1,0,3,2] row_mask:0xf bank_mask:0xf bound_ctrl:1
	s_nop 0
	v_add_f32_dpp v110, v110, v110 quad_perm:[2,3,0,1] row_mask:0xf bank_mask:0xf bound_ctrl:1
	v_add_f32_dpp v112, v112, v112 quad_perm:[2,3,0,1] row_mask:0xf bank_mask:0xf bound_ctrl:1
	s_nop 0
	v_add_f32_dpp v110, v110, v110 row_half_mirror row_mask:0xf bank_mask:0xf bound_ctrl:1
	v_add_f32_dpp v112, v112, v112 row_half_mirror row_mask:0xf bank_mask:0xf bound_ctrl:1
	s_nop 0
	v_add_f32_dpp v110, v110, v110 row_ror:8 row_mask:0xf bank_mask:0xf bound_ctrl:1
	v_add_f32_dpp v112, v112, v112 row_ror:8 row_mask:0xf bank_mask:0xf bound_ctrl:1
	v_pk_mul_f32 v[114:115], v[88:89], v[110:111] op_sel_hi:[1,0]
	v_pk_mul_f32 v[116:117], v[88:89], v[112:113] op_sel_hi:[1,0]
	v_pk_mul_f32 v[118:119], v[90:91], v[110:111] op_sel_hi:[1,0]
	v_pk_mul_f32 v[120:121], v[90:91], v[112:113] op_sel_hi:[1,0]
	v_pk_fma_f32 v[114:115], v[100:101], v[104:105], v[114:115] op_sel_hi:[1,0,1]
	v_pk_fma_f32 v[116:117], v[100:101], v[104:105], v[116:117] op_sel:[0,1,0]
	v_pk_fma_f32 v[118:119], v[102:103], v[104:105], v[118:119] op_sel_hi:[1,0,1]
	v_pk_fma_f32 v[120:121], v[102:103], v[104:105], v[120:121] op_sel:[0,1,0]
	v_pk_fma_f32 v[72:73], v[72:73], v[92:93], v[114:115]
	v_pk_fma_f32 v[76:77], v[76:77], v[92:93], v[116:117]
	v_pk_fma_f32 v[74:75], v[74:75], v[94:95], v[118:119]
	v_pk_fma_f32 v[78:79], v[78:79], v[94:95], v[120:121]
	v_pk_mul_f32 v[122:123], v[72:73], v[96:97]
	v_pk_mul_f32 v[124:125], v[76:77], v[96:97]
	v_pk_fma_f32 v[122:123], v[74:75], v[98:99], v[122:123]
	v_pk_fma_f32 v[124:125], v[78:79], v[98:99], v[124:125]
	v_add_f32_e32 v126, v122, v123
	v_add_f32_e32 v127, v124, v125
	ds_write_b64 v187, v[126:127] offset:14336
	s_waitcnt lgkmcnt(8)
	ds_read_b128 v[84:87], v161 offset:10752
	ds_read_b128 v[88:91], v161 offset:18944
	ds_read_b128 v[100:103], v161 offset:27136
	ds_read_b64 v[104:105], v82 offset:43520
	ds_read_b128 v[92:95], v161 offset:2560
	ds_read_b128 v[96:99], v161 offset:35328
	v_pk_mul_f32 v[106:107], v[72:73], v[128:129]
	v_pk_mul_f32 v[108:109], v[76:77], v[128:129]
	v_pk_fma_f32 v[106:107], v[74:75], v[130:131], v[106:107]
	v_pk_fma_f32 v[108:109], v[78:79], v[130:131], v[108:109]
	v_add_f32_e32 v110, v106, v107
	v_add_f32_e32 v112, v108, v109
	s_nop 0
	v_add_f32_dpp v110, v110, v110 quad_perm:[1,0,3,2] row_mask:0xf bank_mask:0xf bound_ctrl:1
	v_add_f32_dpp v112, v112, v112 quad_perm:[1,0,3,2] row_mask:0xf bank_mask:0xf bound_ctrl:1
	s_nop 0
	v_add_f32_dpp v110, v110, v110 quad_perm:[2,3,0,1] row_mask:0xf bank_mask:0xf bound_ctrl:1
	v_add_f32_dpp v112, v112, v112 quad_perm:[2,3,0,1] row_mask:0xf bank_mask:0xf bound_ctrl:1
	s_nop 0
	v_add_f32_dpp v110, v110, v110 row_half_mirror row_mask:0xf bank_mask:0xf bound_ctrl:1
	v_add_f32_dpp v112, v112, v112 row_half_mirror row_mask:0xf bank_mask:0xf bound_ctrl:1
	s_nop 0
	v_add_f32_dpp v110, v110, v110 row_ror:8 row_mask:0xf bank_mask:0xf bound_ctrl:1
	v_add_f32_dpp v112, v112, v112 row_ror:8 row_mask:0xf bank_mask:0xf bound_ctrl:1
	v_pk_mul_f32 v[114:115], v[132:133], v[110:111] op_sel_hi:[1,0]
	v_pk_mul_f32 v[116:117], v[132:133], v[112:113] op_sel_hi:[1,0]
	v_pk_mul_f32 v[118:119], v[134:135], v[110:111] op_sel_hi:[1,0]
	v_pk_mul_f32 v[120:121], v[134:135], v[112:113] op_sel_hi:[1,0]
	v_pk_fma_f32 v[114:115], v[194:195], v[198:199], v[114:115] op_sel_hi:[1,0,1]
	v_pk_fma_f32 v[116:117], v[194:195], v[198:199], v[116:117] op_sel:[0,1,0]
	v_pk_fma_f32 v[118:119], v[196:197], v[198:199], v[118:119] op_sel_hi:[1,0,1]
	v_pk_fma_f32 v[120:121], v[196:197], v[198:199], v[120:121] op_sel:[0,1,0]
	v_pk_fma_f32 v[72:73], v[72:73], v[136:137], v[114:115]
	v_pk_fma_f32 v[76:77], v[76:77], v[136:137], v[116:117]
	v_pk_fma_f32 v[74:75], v[74:75], v[138:139], v[118:119]
	v_pk_fma_f32 v[78:79], v[78:79], v[138:139], v[120:121]
	v_pk_mul_f32 v[122:123], v[72:73], v[140:141]
	v_pk_mul_f32 v[124:125], v[76:77], v[140:141]
	v_pk_fma_f32 v[122:123], v[74:75], v[142:143], v[122:123]
	v_pk_fma_f32 v[124:125], v[78:79], v[142:143], v[124:125]
	v_add_f32_e32 v126, v122, v123
	v_add_f32_e32 v127, v124, v125
	ds_write_b64 v187, v[126:127] offset:16384
	s_waitcnt lgkmcnt(8)
	ds_read_b128 v[128:131], v161 offset:11008
	ds_read_b128 v[132:135], v161 offset:19200
	ds_read_b128 v[194:197], v161 offset:27392
	ds_read_b64 v[198:199], v82 offset:43776
	ds_read_b128 v[136:139], v161 offset:2816
	ds_read_b128 v[140:143], v161 offset:35584
	v_pk_mul_f32 v[106:107], v[72:73], v[30:31]
	v_pk_mul_f32 v[108:109], v[76:77], v[30:31]
	v_pk_fma_f32 v[106:107], v[74:75], v[32:33], v[106:107]
	v_pk_fma_f32 v[108:109], v[78:79], v[32:33], v[108:109]
	v_add_f32_e32 v110, v106, v107
	v_add_f32_e32 v112, v108, v109
	s_nop 0
	v_add_f32_dpp v110, v110, v110 quad_perm:[1,0,3,2] row_mask:0xf bank_mask:0xf bound_ctrl:1
	v_add_f32_dpp v112, v112, v112 quad_perm:[1,0,3,2] row_mask:0xf bank_mask:0xf bound_ctrl:1
	s_nop 0
	v_add_f32_dpp v110, v110, v110 quad_perm:[2,3,0,1] row_mask:0xf bank_mask:0xf bound_ctrl:1
	v_add_f32_dpp v112, v112, v112 quad_perm:[2,3,0,1] row_mask:0xf bank_mask:0xf bound_ctrl:1
	s_nop 0
	v_add_f32_dpp v110, v110, v110 row_half_mirror row_mask:0xf bank_mask:0xf bound_ctrl:1
	v_add_f32_dpp v112, v112, v112 row_half_mirror row_mask:0xf bank_mask:0xf bound_ctrl:1
	s_nop 0
	v_add_f32_dpp v110, v110, v110 row_ror:8 row_mask:0xf bank_mask:0xf bound_ctrl:1
	v_add_f32_dpp v112, v112, v112 row_ror:8 row_mask:0xf bank_mask:0xf bound_ctrl:1
	v_pk_mul_f32 v[114:115], v[34:35], v[110:111] op_sel_hi:[1,0]
	v_pk_mul_f32 v[116:117], v[34:35], v[112:113] op_sel_hi:[1,0]
	v_pk_mul_f32 v[118:119], v[36:37], v[110:111] op_sel_hi:[1,0]
	v_pk_mul_f32 v[120:121], v[36:37], v[112:113] op_sel_hi:[1,0]
	v_pk_fma_f32 v[114:115], v[46:47], v[80:81], v[114:115] op_sel_hi:[1,0,1]
	v_pk_fma_f32 v[116:117], v[46:47], v[80:81], v[116:117] op_sel:[0,1,0]
	v_pk_fma_f32 v[118:119], v[48:49], v[80:81], v[118:119] op_sel_hi:[1,0,1]
	v_pk_fma_f32 v[120:121], v[48:49], v[80:81], v[120:121] op_sel:[0,1,0]
	v_pk_fma_f32 v[72:73], v[72:73], v[38:39], v[114:115]
	v_pk_fma_f32 v[76:77], v[76:77], v[38:39], v[116:117]
	v_pk_fma_f32 v[74:75], v[74:75], v[40:41], v[118:119]
	v_pk_fma_f32 v[78:79], v[78:79], v[40:41], v[120:121]
	v_pk_mul_f32 v[122:123], v[72:73], v[42:43]
	v_pk_mul_f32 v[124:125], v[76:77], v[42:43]
	v_pk_fma_f32 v[122:123], v[74:75], v[44:45], v[122:123]
	v_pk_fma_f32 v[124:125], v[78:79], v[44:45], v[124:125]
	v_add_f32_e32 v126, v122, v123
	v_add_f32_e32 v127, v124, v125
	ds_write_b64 v187, v[126:127] offset:18432
	s_waitcnt lgkmcnt(8)
	ds_read_b128 v[30:33], v161 offset:11264
	ds_read_b128 v[34:37], v161 offset:19456
	ds_read_b128 v[46:49], v161 offset:27648
	ds_read_b64 v[80:81], v82 offset:44032
	ds_read_b128 v[38:41], v161 offset:3072
	ds_read_b128 v[42:45], v161 offset:35840
	v_pk_mul_f32 v[106:107], v[72:73], v[84:85]
	v_pk_mul_f32 v[108:109], v[76:77], v[84:85]
	v_pk_fma_f32 v[106:107], v[74:75], v[86:87], v[106:107]
	v_pk_fma_f32 v[108:109], v[78:79], v[86:87], v[108:109]
	v_add_f32_e32 v110, v106, v107
	v_add_f32_e32 v112, v108, v109
	s_nop 0
	v_add_f32_dpp v110, v110, v110 quad_perm:[1,0,3,2] row_mask:0xf bank_mask:0xf bound_ctrl:1
	v_add_f32_dpp v112, v112, v112 quad_perm:[1,0,3,2] row_mask:0xf bank_mask:0xf bound_ctrl:1
	s_nop 0
	v_add_f32_dpp v110, v110, v110 quad_perm:[2,3,0,1] row_mask:0xf bank_mask:0xf bound_ctrl:1
	v_add_f32_dpp v112, v112, v112 quad_perm:[2,3,0,1] row_mask:0xf bank_mask:0xf bound_ctrl:1
	s_nop 0
	v_add_f32_dpp v110, v110, v110 row_half_mirror row_mask:0xf bank_mask:0xf bound_ctrl:1
	v_add_f32_dpp v112, v112, v112 row_half_mirror row_mask:0xf bank_mask:0xf bound_ctrl:1
	s_nop 0
	v_add_f32_dpp v110, v110, v110 row_ror:8 row_mask:0xf bank_mask:0xf bound_ctrl:1
	v_add_f32_dpp v112, v112, v112 row_ror:8 row_mask:0xf bank_mask:0xf bound_ctrl:1
	v_pk_mul_f32 v[114:115], v[88:89], v[110:111] op_sel_hi:[1,0]
	v_pk_mul_f32 v[116:117], v[88:89], v[112:113] op_sel_hi:[1,0]
	v_pk_mul_f32 v[118:119], v[90:91], v[110:111] op_sel_hi:[1,0]
	v_pk_mul_f32 v[120:121], v[90:91], v[112:113] op_sel_hi:[1,0]
	v_pk_fma_f32 v[114:115], v[100:101], v[104:105], v[114:115] op_sel_hi:[1,0,1]
	v_pk_fma_f32 v[116:117], v[100:101], v[104:105], v[116:117] op_sel:[0,1,0]
	v_pk_fma_f32 v[118:119], v[102:103], v[104:105], v[118:119] op_sel_hi:[1,0,1]
	v_pk_fma_f32 v[120:121], v[102:103], v[104:105], v[120:121] op_sel:[0,1,0]
	v_pk_fma_f32 v[72:73], v[72:73], v[92:93], v[114:115]
	v_pk_fma_f32 v[76:77], v[76:77], v[92:93], v[116:117]
	v_pk_fma_f32 v[74:75], v[74:75], v[94:95], v[118:119]
	v_pk_fma_f32 v[78:79], v[78:79], v[94:95], v[120:121]
	v_pk_mul_f32 v[122:123], v[72:73], v[96:97]
	v_pk_mul_f32 v[124:125], v[76:77], v[96:97]
	v_pk_fma_f32 v[122:123], v[74:75], v[98:99], v[122:123]
	v_pk_fma_f32 v[124:125], v[78:79], v[98:99], v[124:125]
	v_add_f32_e32 v126, v122, v123
	v_add_f32_e32 v127, v124, v125
	ds_write_b64 v187, v[126:127] offset:20480
	s_waitcnt lgkmcnt(8)
	ds_read_b128 v[84:87], v161 offset:11520
	ds_read_b128 v[88:91], v161 offset:19712
	ds_read_b128 v[100:103], v161 offset:27904
	ds_read_b64 v[104:105], v82 offset:44288
	ds_read_b128 v[92:95], v161 offset:3328
	ds_read_b128 v[96:99], v161 offset:36096
	v_pk_mul_f32 v[106:107], v[72:73], v[128:129]
	v_pk_mul_f32 v[108:109], v[76:77], v[128:129]
	v_pk_fma_f32 v[106:107], v[74:75], v[130:131], v[106:107]
	v_pk_fma_f32 v[108:109], v[78:79], v[130:131], v[108:109]
	v_add_f32_e32 v110, v106, v107
	v_add_f32_e32 v112, v108, v109
	s_nop 0
	v_add_f32_dpp v110, v110, v110 quad_perm:[1,0,3,2] row_mask:0xf bank_mask:0xf bound_ctrl:1
	v_add_f32_dpp v112, v112, v112 quad_perm:[1,0,3,2] row_mask:0xf bank_mask:0xf bound_ctrl:1
	s_nop 0
	v_add_f32_dpp v110, v110, v110 quad_perm:[2,3,0,1] row_mask:0xf bank_mask:0xf bound_ctrl:1
	v_add_f32_dpp v112, v112, v112 quad_perm:[2,3,0,1] row_mask:0xf bank_mask:0xf bound_ctrl:1
	s_nop 0
	v_add_f32_dpp v110, v110, v110 row_half_mirror row_mask:0xf bank_mask:0xf bound_ctrl:1
	v_add_f32_dpp v112, v112, v112 row_half_mirror row_mask:0xf bank_mask:0xf bound_ctrl:1
	s_nop 0
	v_add_f32_dpp v110, v110, v110 row_ror:8 row_mask:0xf bank_mask:0xf bound_ctrl:1
	v_add_f32_dpp v112, v112, v112 row_ror:8 row_mask:0xf bank_mask:0xf bound_ctrl:1
	v_pk_mul_f32 v[114:115], v[132:133], v[110:111] op_sel_hi:[1,0]
	v_pk_mul_f32 v[116:117], v[132:133], v[112:113] op_sel_hi:[1,0]
	v_pk_mul_f32 v[118:119], v[134:135], v[110:111] op_sel_hi:[1,0]
	v_pk_mul_f32 v[120:121], v[134:135], v[112:113] op_sel_hi:[1,0]
	v_pk_fma_f32 v[114:115], v[194:195], v[198:199], v[114:115] op_sel_hi:[1,0,1]
	v_pk_fma_f32 v[116:117], v[194:195], v[198:199], v[116:117] op_sel:[0,1,0]
	v_pk_fma_f32 v[118:119], v[196:197], v[198:199], v[118:119] op_sel_hi:[1,0,1]
	v_pk_fma_f32 v[120:121], v[196:197], v[198:199], v[120:121] op_sel:[0,1,0]
	v_pk_fma_f32 v[72:73], v[72:73], v[136:137], v[114:115]
	v_pk_fma_f32 v[76:77], v[76:77], v[136:137], v[116:117]
	v_pk_fma_f32 v[74:75], v[74:75], v[138:139], v[118:119]
	v_pk_fma_f32 v[78:79], v[78:79], v[138:139], v[120:121]
	v_pk_mul_f32 v[122:123], v[72:73], v[140:141]
	v_pk_mul_f32 v[124:125], v[76:77], v[140:141]
	v_pk_fma_f32 v[122:123], v[74:75], v[142:143], v[122:123]
	v_pk_fma_f32 v[124:125], v[78:79], v[142:143], v[124:125]
	v_add_f32_e32 v126, v122, v123
	v_add_f32_e32 v127, v124, v125
	ds_write_b64 v187, v[126:127] offset:22528
	s_waitcnt lgkmcnt(8)
	ds_read_b128 v[128:131], v161 offset:11776
	ds_read_b128 v[132:135], v161 offset:19968
	ds_read_b128 v[194:197], v161 offset:28160
	ds_read_b64 v[198:199], v82 offset:44544
	ds_read_b128 v[136:139], v161 offset:3584
	ds_read_b128 v[140:143], v161 offset:36352
	v_pk_mul_f32 v[106:107], v[72:73], v[30:31]
	v_pk_mul_f32 v[108:109], v[76:77], v[30:31]
	v_pk_fma_f32 v[106:107], v[74:75], v[32:33], v[106:107]
	v_pk_fma_f32 v[108:109], v[78:79], v[32:33], v[108:109]
	v_add_f32_e32 v110, v106, v107
	v_add_f32_e32 v112, v108, v109
	s_nop 0
	v_add_f32_dpp v110, v110, v110 quad_perm:[1,0,3,2] row_mask:0xf bank_mask:0xf bound_ctrl:1
	v_add_f32_dpp v112, v112, v112 quad_perm:[1,0,3,2] row_mask:0xf bank_mask:0xf bound_ctrl:1
	s_nop 0
	v_add_f32_dpp v110, v110, v110 quad_perm:[2,3,0,1] row_mask:0xf bank_mask:0xf bound_ctrl:1
	v_add_f32_dpp v112, v112, v112 quad_perm:[2,3,0,1] row_mask:0xf bank_mask:0xf bound_ctrl:1
	s_nop 0
	v_add_f32_dpp v110, v110, v110 row_half_mirror row_mask:0xf bank_mask:0xf bound_ctrl:1
	v_add_f32_dpp v112, v112, v112 row_half_mirror row_mask:0xf bank_mask:0xf bound_ctrl:1
	s_nop 0
	v_add_f32_dpp v110, v110, v110 row_ror:8 row_mask:0xf bank_mask:0xf bound_ctrl:1
	v_add_f32_dpp v112, v112, v112 row_ror:8 row_mask:0xf bank_mask:0xf bound_ctrl:1
	v_pk_mul_f32 v[114:115], v[34:35], v[110:111] op_sel_hi:[1,0]
	v_pk_mul_f32 v[116:117], v[34:35], v[112:113] op_sel_hi:[1,0]
	v_pk_mul_f32 v[118:119], v[36:37], v[110:111] op_sel_hi:[1,0]
	v_pk_mul_f32 v[120:121], v[36:37], v[112:113] op_sel_hi:[1,0]
	v_pk_fma_f32 v[114:115], v[46:47], v[80:81], v[114:115] op_sel_hi:[1,0,1]
	v_pk_fma_f32 v[116:117], v[46:47], v[80:81], v[116:117] op_sel:[0,1,0]
	v_pk_fma_f32 v[118:119], v[48:49], v[80:81], v[118:119] op_sel_hi:[1,0,1]
	v_pk_fma_f32 v[120:121], v[48:49], v[80:81], v[120:121] op_sel:[0,1,0]
	v_pk_fma_f32 v[72:73], v[72:73], v[38:39], v[114:115]
	v_pk_fma_f32 v[76:77], v[76:77], v[38:39], v[116:117]
	v_pk_fma_f32 v[74:75], v[74:75], v[40:41], v[118:119]
	v_pk_fma_f32 v[78:79], v[78:79], v[40:41], v[120:121]
	v_pk_mul_f32 v[122:123], v[72:73], v[42:43]
	v_pk_mul_f32 v[124:125], v[76:77], v[42:43]
	v_pk_fma_f32 v[122:123], v[74:75], v[44:45], v[122:123]
	v_pk_fma_f32 v[124:125], v[78:79], v[44:45], v[124:125]
	v_add_f32_e32 v126, v122, v123
	v_add_f32_e32 v127, v124, v125
	ds_write_b64 v187, v[126:127] offset:24576
	s_waitcnt lgkmcnt(8)
	ds_read_b128 v[30:33], v161 offset:12032
	ds_read_b128 v[34:37], v161 offset:20224
	ds_read_b128 v[46:49], v161 offset:28416
	ds_read_b64 v[80:81], v82 offset:44800
	ds_read_b128 v[38:41], v161 offset:3840
	ds_read_b128 v[42:45], v161 offset:36608
	v_pk_mul_f32 v[106:107], v[72:73], v[84:85]
	v_pk_mul_f32 v[108:109], v[76:77], v[84:85]
	v_pk_fma_f32 v[106:107], v[74:75], v[86:87], v[106:107]
	v_pk_fma_f32 v[108:109], v[78:79], v[86:87], v[108:109]
	v_add_f32_e32 v110, v106, v107
	v_add_f32_e32 v112, v108, v109
	s_nop 0
	v_add_f32_dpp v110, v110, v110 quad_perm:[1,0,3,2] row_mask:0xf bank_mask:0xf bound_ctrl:1
	v_add_f32_dpp v112, v112, v112 quad_perm:[1,0,3,2] row_mask:0xf bank_mask:0xf bound_ctrl:1
	s_nop 0
	v_add_f32_dpp v110, v110, v110 quad_perm:[2,3,0,1] row_mask:0xf bank_mask:0xf bound_ctrl:1
	v_add_f32_dpp v112, v112, v112 quad_perm:[2,3,0,1] row_mask:0xf bank_mask:0xf bound_ctrl:1
	s_nop 0
	v_add_f32_dpp v110, v110, v110 row_half_mirror row_mask:0xf bank_mask:0xf bound_ctrl:1
	v_add_f32_dpp v112, v112, v112 row_half_mirror row_mask:0xf bank_mask:0xf bound_ctrl:1
	s_nop 0
	v_add_f32_dpp v110, v110, v110 row_ror:8 row_mask:0xf bank_mask:0xf bound_ctrl:1
	v_add_f32_dpp v112, v112, v112 row_ror:8 row_mask:0xf bank_mask:0xf bound_ctrl:1
	v_pk_mul_f32 v[114:115], v[88:89], v[110:111] op_sel_hi:[1,0]
	v_pk_mul_f32 v[116:117], v[88:89], v[112:113] op_sel_hi:[1,0]
	v_pk_mul_f32 v[118:119], v[90:91], v[110:111] op_sel_hi:[1,0]
	v_pk_mul_f32 v[120:121], v[90:91], v[112:113] op_sel_hi:[1,0]
	v_pk_fma_f32 v[114:115], v[100:101], v[104:105], v[114:115] op_sel_hi:[1,0,1]
	v_pk_fma_f32 v[116:117], v[100:101], v[104:105], v[116:117] op_sel:[0,1,0]
	v_pk_fma_f32 v[118:119], v[102:103], v[104:105], v[118:119] op_sel_hi:[1,0,1]
	v_pk_fma_f32 v[120:121], v[102:103], v[104:105], v[120:121] op_sel:[0,1,0]
	v_pk_fma_f32 v[72:73], v[72:73], v[92:93], v[114:115]
	v_pk_fma_f32 v[76:77], v[76:77], v[92:93], v[116:117]
	v_pk_fma_f32 v[74:75], v[74:75], v[94:95], v[118:119]
	v_pk_fma_f32 v[78:79], v[78:79], v[94:95], v[120:121]
	v_pk_mul_f32 v[122:123], v[72:73], v[96:97]
	v_pk_mul_f32 v[124:125], v[76:77], v[96:97]
	v_pk_fma_f32 v[122:123], v[74:75], v[98:99], v[122:123]
	v_pk_fma_f32 v[124:125], v[78:79], v[98:99], v[124:125]
	v_add_f32_e32 v126, v122, v123
	v_add_f32_e32 v127, v124, v125
	ds_write_b64 v187, v[126:127] offset:26624
	s_waitcnt lgkmcnt(8)
	ds_read_b128 v[84:87], v161 offset:12288
	ds_read_b128 v[88:91], v161 offset:20480
	ds_read_b128 v[100:103], v161 offset:28672
	ds_read_b64 v[104:105], v82 offset:45056
	ds_read_b128 v[92:95], v161 offset:4096
	ds_read_b128 v[96:99], v161 offset:36864
	v_pk_mul_f32 v[106:107], v[72:73], v[128:129]
	v_pk_mul_f32 v[108:109], v[76:77], v[128:129]
	v_pk_fma_f32 v[106:107], v[74:75], v[130:131], v[106:107]
	v_pk_fma_f32 v[108:109], v[78:79], v[130:131], v[108:109]
	v_add_f32_e32 v110, v106, v107
	v_add_f32_e32 v112, v108, v109
	s_nop 0
	v_add_f32_dpp v110, v110, v110 quad_perm:[1,0,3,2] row_mask:0xf bank_mask:0xf bound_ctrl:1
	v_add_f32_dpp v112, v112, v112 quad_perm:[1,0,3,2] row_mask:0xf bank_mask:0xf bound_ctrl:1
	s_nop 0
	v_add_f32_dpp v110, v110, v110 quad_perm:[2,3,0,1] row_mask:0xf bank_mask:0xf bound_ctrl:1
	v_add_f32_dpp v112, v112, v112 quad_perm:[2,3,0,1] row_mask:0xf bank_mask:0xf bound_ctrl:1
	s_nop 0
	v_add_f32_dpp v110, v110, v110 row_half_mirror row_mask:0xf bank_mask:0xf bound_ctrl:1
	v_add_f32_dpp v112, v112, v112 row_half_mirror row_mask:0xf bank_mask:0xf bound_ctrl:1
	s_nop 0
	v_add_f32_dpp v110, v110, v110 row_ror:8 row_mask:0xf bank_mask:0xf bound_ctrl:1
	v_add_f32_dpp v112, v112, v112 row_ror:8 row_mask:0xf bank_mask:0xf bound_ctrl:1
	v_pk_mul_f32 v[114:115], v[132:133], v[110:111] op_sel_hi:[1,0]
	v_pk_mul_f32 v[116:117], v[132:133], v[112:113] op_sel_hi:[1,0]
	v_pk_mul_f32 v[118:119], v[134:135], v[110:111] op_sel_hi:[1,0]
	v_pk_mul_f32 v[120:121], v[134:135], v[112:113] op_sel_hi:[1,0]
	v_pk_fma_f32 v[114:115], v[194:195], v[198:199], v[114:115] op_sel_hi:[1,0,1]
	v_pk_fma_f32 v[116:117], v[194:195], v[198:199], v[116:117] op_sel:[0,1,0]
	v_pk_fma_f32 v[118:119], v[196:197], v[198:199], v[118:119] op_sel_hi:[1,0,1]
	v_pk_fma_f32 v[120:121], v[196:197], v[198:199], v[120:121] op_sel:[0,1,0]
	v_pk_fma_f32 v[72:73], v[72:73], v[136:137], v[114:115]
	v_pk_fma_f32 v[76:77], v[76:77], v[136:137], v[116:117]
	v_pk_fma_f32 v[74:75], v[74:75], v[138:139], v[118:119]
	v_pk_fma_f32 v[78:79], v[78:79], v[138:139], v[120:121]
	v_pk_mul_f32 v[122:123], v[72:73], v[140:141]
	v_pk_mul_f32 v[124:125], v[76:77], v[140:141]
	v_pk_fma_f32 v[122:123], v[74:75], v[142:143], v[122:123]
	v_pk_fma_f32 v[124:125], v[78:79], v[142:143], v[124:125]
	v_add_f32_e32 v126, v122, v123
	v_add_f32_e32 v127, v124, v125
	ds_write_b64 v187, v[126:127] offset:28672
	s_waitcnt lgkmcnt(8)
	ds_read_b128 v[128:131], v161 offset:12544
	ds_read_b128 v[132:135], v161 offset:20736
	ds_read_b128 v[194:197], v161 offset:28928
	ds_read_b64 v[198:199], v82 offset:45312
	ds_read_b128 v[136:139], v161 offset:4352
	ds_read_b128 v[140:143], v161 offset:37120
	v_pk_mul_f32 v[106:107], v[72:73], v[30:31]
	v_pk_mul_f32 v[108:109], v[76:77], v[30:31]
	v_pk_fma_f32 v[106:107], v[74:75], v[32:33], v[106:107]
	v_pk_fma_f32 v[108:109], v[78:79], v[32:33], v[108:109]
	v_add_f32_e32 v110, v106, v107
	v_add_f32_e32 v112, v108, v109
	s_nop 0
	v_add_f32_dpp v110, v110, v110 quad_perm:[1,0,3,2] row_mask:0xf bank_mask:0xf bound_ctrl:1
	v_add_f32_dpp v112, v112, v112 quad_perm:[1,0,3,2] row_mask:0xf bank_mask:0xf bound_ctrl:1
	s_nop 0
	v_add_f32_dpp v110, v110, v110 quad_perm:[2,3,0,1] row_mask:0xf bank_mask:0xf bound_ctrl:1
	v_add_f32_dpp v112, v112, v112 quad_perm:[2,3,0,1] row_mask:0xf bank_mask:0xf bound_ctrl:1
	s_nop 0
	v_add_f32_dpp v110, v110, v110 row_half_mirror row_mask:0xf bank_mask:0xf bound_ctrl:1
	v_add_f32_dpp v112, v112, v112 row_half_mirror row_mask:0xf bank_mask:0xf bound_ctrl:1
	s_nop 0
	v_add_f32_dpp v110, v110, v110 row_ror:8 row_mask:0xf bank_mask:0xf bound_ctrl:1
	v_add_f32_dpp v112, v112, v112 row_ror:8 row_mask:0xf bank_mask:0xf bound_ctrl:1
	v_pk_mul_f32 v[114:115], v[34:35], v[110:111] op_sel_hi:[1,0]
	v_pk_mul_f32 v[116:117], v[34:35], v[112:113] op_sel_hi:[1,0]
	v_pk_mul_f32 v[118:119], v[36:37], v[110:111] op_sel_hi:[1,0]
	v_pk_mul_f32 v[120:121], v[36:37], v[112:113] op_sel_hi:[1,0]
	v_pk_fma_f32 v[114:115], v[46:47], v[80:81], v[114:115] op_sel_hi:[1,0,1]
	v_pk_fma_f32 v[116:117], v[46:47], v[80:81], v[116:117] op_sel:[0,1,0]
	v_pk_fma_f32 v[118:119], v[48:49], v[80:81], v[118:119] op_sel_hi:[1,0,1]
	v_pk_fma_f32 v[120:121], v[48:49], v[80:81], v[120:121] op_sel:[0,1,0]
	v_pk_fma_f32 v[72:73], v[72:73], v[38:39], v[114:115]
	v_pk_fma_f32 v[76:77], v[76:77], v[38:39], v[116:117]
	v_pk_fma_f32 v[74:75], v[74:75], v[40:41], v[118:119]
	v_pk_fma_f32 v[78:79], v[78:79], v[40:41], v[120:121]
	v_pk_mul_f32 v[122:123], v[72:73], v[42:43]
	v_pk_mul_f32 v[124:125], v[76:77], v[42:43]
	v_pk_fma_f32 v[122:123], v[74:75], v[44:45], v[122:123]
	v_pk_fma_f32 v[124:125], v[78:79], v[44:45], v[124:125]
	v_add_f32_e32 v126, v122, v123
	v_add_f32_e32 v127, v124, v125
	ds_write_b64 v187, v[126:127] offset:30720
	s_waitcnt lgkmcnt(8)
	ds_read_b128 v[30:33], v161 offset:12800
	ds_read_b128 v[34:37], v161 offset:20992
	ds_read_b128 v[46:49], v161 offset:29184
	ds_read_b64 v[80:81], v82 offset:45568
	ds_read_b128 v[38:41], v161 offset:4608
	ds_read_b128 v[42:45], v161 offset:37376
	v_pk_mul_f32 v[106:107], v[72:73], v[84:85]
	v_pk_mul_f32 v[108:109], v[76:77], v[84:85]
	v_pk_fma_f32 v[106:107], v[74:75], v[86:87], v[106:107]
	v_pk_fma_f32 v[108:109], v[78:79], v[86:87], v[108:109]
	v_add_f32_e32 v110, v106, v107
	v_add_f32_e32 v112, v108, v109
	s_nop 0
	v_add_f32_dpp v110, v110, v110 quad_perm:[1,0,3,2] row_mask:0xf bank_mask:0xf bound_ctrl:1
	v_add_f32_dpp v112, v112, v112 quad_perm:[1,0,3,2] row_mask:0xf bank_mask:0xf bound_ctrl:1
	s_nop 0
	v_add_f32_dpp v110, v110, v110 quad_perm:[2,3,0,1] row_mask:0xf bank_mask:0xf bound_ctrl:1
	v_add_f32_dpp v112, v112, v112 quad_perm:[2,3,0,1] row_mask:0xf bank_mask:0xf bound_ctrl:1
	s_nop 0
	v_add_f32_dpp v110, v110, v110 row_half_mirror row_mask:0xf bank_mask:0xf bound_ctrl:1
	v_add_f32_dpp v112, v112, v112 row_half_mirror row_mask:0xf bank_mask:0xf bound_ctrl:1
	s_nop 0
	v_add_f32_dpp v110, v110, v110 row_ror:8 row_mask:0xf bank_mask:0xf bound_ctrl:1
	v_add_f32_dpp v112, v112, v112 row_ror:8 row_mask:0xf bank_mask:0xf bound_ctrl:1
	v_pk_mul_f32 v[114:115], v[88:89], v[110:111] op_sel_hi:[1,0]
	v_pk_mul_f32 v[116:117], v[88:89], v[112:113] op_sel_hi:[1,0]
	v_pk_mul_f32 v[118:119], v[90:91], v[110:111] op_sel_hi:[1,0]
	v_pk_mul_f32 v[120:121], v[90:91], v[112:113] op_sel_hi:[1,0]
	v_pk_fma_f32 v[114:115], v[100:101], v[104:105], v[114:115] op_sel_hi:[1,0,1]
	v_pk_fma_f32 v[116:117], v[100:101], v[104:105], v[116:117] op_sel:[0,1,0]
	v_pk_fma_f32 v[118:119], v[102:103], v[104:105], v[118:119] op_sel_hi:[1,0,1]
	v_pk_fma_f32 v[120:121], v[102:103], v[104:105], v[120:121] op_sel:[0,1,0]
	v_pk_fma_f32 v[72:73], v[72:73], v[92:93], v[114:115]
	v_pk_fma_f32 v[76:77], v[76:77], v[92:93], v[116:117]
	v_pk_fma_f32 v[74:75], v[74:75], v[94:95], v[118:119]
	v_pk_fma_f32 v[78:79], v[78:79], v[94:95], v[120:121]
	v_pk_mul_f32 v[122:123], v[72:73], v[96:97]
	v_pk_mul_f32 v[124:125], v[76:77], v[96:97]
	v_pk_fma_f32 v[122:123], v[74:75], v[98:99], v[122:123]
	v_pk_fma_f32 v[124:125], v[78:79], v[98:99], v[124:125]
	v_add_f32_e32 v126, v122, v123
	v_add_f32_e32 v127, v124, v125
	ds_write_b64 v187, v[126:127] offset:32768
	s_waitcnt lgkmcnt(8)
	ds_read_b128 v[84:87], v161 offset:13056
	ds_read_b128 v[88:91], v161 offset:21248
	ds_read_b128 v[100:103], v161 offset:29440
	ds_read_b64 v[104:105], v82 offset:45824
	ds_read_b128 v[92:95], v161 offset:4864
	ds_read_b128 v[96:99], v161 offset:37632
	v_pk_mul_f32 v[106:107], v[72:73], v[128:129]
	v_pk_mul_f32 v[108:109], v[76:77], v[128:129]
	v_pk_fma_f32 v[106:107], v[74:75], v[130:131], v[106:107]
	v_pk_fma_f32 v[108:109], v[78:79], v[130:131], v[108:109]
	v_add_f32_e32 v110, v106, v107
	v_add_f32_e32 v112, v108, v109
	s_nop 0
	v_add_f32_dpp v110, v110, v110 quad_perm:[1,0,3,2] row_mask:0xf bank_mask:0xf bound_ctrl:1
	v_add_f32_dpp v112, v112, v112 quad_perm:[1,0,3,2] row_mask:0xf bank_mask:0xf bound_ctrl:1
	s_nop 0
	v_add_f32_dpp v110, v110, v110 quad_perm:[2,3,0,1] row_mask:0xf bank_mask:0xf bound_ctrl:1
	v_add_f32_dpp v112, v112, v112 quad_perm:[2,3,0,1] row_mask:0xf bank_mask:0xf bound_ctrl:1
	s_nop 0
	v_add_f32_dpp v110, v110, v110 row_half_mirror row_mask:0xf bank_mask:0xf bound_ctrl:1
	v_add_f32_dpp v112, v112, v112 row_half_mirror row_mask:0xf bank_mask:0xf bound_ctrl:1
	s_nop 0
	v_add_f32_dpp v110, v110, v110 row_ror:8 row_mask:0xf bank_mask:0xf bound_ctrl:1
	v_add_f32_dpp v112, v112, v112 row_ror:8 row_mask:0xf bank_mask:0xf bound_ctrl:1
	v_pk_mul_f32 v[114:115], v[132:133], v[110:111] op_sel_hi:[1,0]
	v_pk_mul_f32 v[116:117], v[132:133], v[112:113] op_sel_hi:[1,0]
	v_pk_mul_f32 v[118:119], v[134:135], v[110:111] op_sel_hi:[1,0]
	v_pk_mul_f32 v[120:121], v[134:135], v[112:113] op_sel_hi:[1,0]
	v_pk_fma_f32 v[114:115], v[194:195], v[198:199], v[114:115] op_sel_hi:[1,0,1]
	v_pk_fma_f32 v[116:117], v[194:195], v[198:199], v[116:117] op_sel:[0,1,0]
	v_pk_fma_f32 v[118:119], v[196:197], v[198:199], v[118:119] op_sel_hi:[1,0,1]
	v_pk_fma_f32 v[120:121], v[196:197], v[198:199], v[120:121] op_sel:[0,1,0]
	v_pk_fma_f32 v[72:73], v[72:73], v[136:137], v[114:115]
	v_pk_fma_f32 v[76:77], v[76:77], v[136:137], v[116:117]
	v_pk_fma_f32 v[74:75], v[74:75], v[138:139], v[118:119]
	v_pk_fma_f32 v[78:79], v[78:79], v[138:139], v[120:121]
	v_pk_mul_f32 v[122:123], v[72:73], v[140:141]
	v_pk_mul_f32 v[124:125], v[76:77], v[140:141]
	v_pk_fma_f32 v[122:123], v[74:75], v[142:143], v[122:123]
	v_pk_fma_f32 v[124:125], v[78:79], v[142:143], v[124:125]
	v_add_f32_e32 v126, v122, v123
	v_add_f32_e32 v127, v124, v125
	ds_write_b64 v187, v[126:127] offset:34816
	s_waitcnt lgkmcnt(8)
	ds_read_b128 v[128:131], v161 offset:13312
	ds_read_b128 v[132:135], v161 offset:21504
	ds_read_b128 v[194:197], v161 offset:29696
	ds_read_b64 v[198:199], v82 offset:46080
	ds_read_b128 v[136:139], v161 offset:5120
	ds_read_b128 v[140:143], v161 offset:37888
	v_pk_mul_f32 v[106:107], v[72:73], v[30:31]
	v_pk_mul_f32 v[108:109], v[76:77], v[30:31]
	v_pk_fma_f32 v[106:107], v[74:75], v[32:33], v[106:107]
	v_pk_fma_f32 v[108:109], v[78:79], v[32:33], v[108:109]
	v_add_f32_e32 v110, v106, v107
	v_add_f32_e32 v112, v108, v109
	s_nop 0
	v_add_f32_dpp v110, v110, v110 quad_perm:[1,0,3,2] row_mask:0xf bank_mask:0xf bound_ctrl:1
	v_add_f32_dpp v112, v112, v112 quad_perm:[1,0,3,2] row_mask:0xf bank_mask:0xf bound_ctrl:1
	s_nop 0
	v_add_f32_dpp v110, v110, v110 quad_perm:[2,3,0,1] row_mask:0xf bank_mask:0xf bound_ctrl:1
	v_add_f32_dpp v112, v112, v112 quad_perm:[2,3,0,1] row_mask:0xf bank_mask:0xf bound_ctrl:1
	s_nop 0
	v_add_f32_dpp v110, v110, v110 row_half_mirror row_mask:0xf bank_mask:0xf bound_ctrl:1
	v_add_f32_dpp v112, v112, v112 row_half_mirror row_mask:0xf bank_mask:0xf bound_ctrl:1
	s_nop 0
	v_add_f32_dpp v110, v110, v110 row_ror:8 row_mask:0xf bank_mask:0xf bound_ctrl:1
	v_add_f32_dpp v112, v112, v112 row_ror:8 row_mask:0xf bank_mask:0xf bound_ctrl:1
	v_pk_mul_f32 v[114:115], v[34:35], v[110:111] op_sel_hi:[1,0]
	v_pk_mul_f32 v[116:117], v[34:35], v[112:113] op_sel_hi:[1,0]
	v_pk_mul_f32 v[118:119], v[36:37], v[110:111] op_sel_hi:[1,0]
	v_pk_mul_f32 v[120:121], v[36:37], v[112:113] op_sel_hi:[1,0]
	v_pk_fma_f32 v[114:115], v[46:47], v[80:81], v[114:115] op_sel_hi:[1,0,1]
	v_pk_fma_f32 v[116:117], v[46:47], v[80:81], v[116:117] op_sel:[0,1,0]
	v_pk_fma_f32 v[118:119], v[48:49], v[80:81], v[118:119] op_sel_hi:[1,0,1]
	v_pk_fma_f32 v[120:121], v[48:49], v[80:81], v[120:121] op_sel:[0,1,0]
	v_pk_fma_f32 v[72:73], v[72:73], v[38:39], v[114:115]
	v_pk_fma_f32 v[76:77], v[76:77], v[38:39], v[116:117]
	v_pk_fma_f32 v[74:75], v[74:75], v[40:41], v[118:119]
	v_pk_fma_f32 v[78:79], v[78:79], v[40:41], v[120:121]
	v_pk_mul_f32 v[122:123], v[72:73], v[42:43]
	v_pk_mul_f32 v[124:125], v[76:77], v[42:43]
	v_pk_fma_f32 v[122:123], v[74:75], v[44:45], v[122:123]
	v_pk_fma_f32 v[124:125], v[78:79], v[44:45], v[124:125]
	v_add_f32_e32 v126, v122, v123
	v_add_f32_e32 v127, v124, v125
	ds_write_b64 v187, v[126:127] offset:36864
	s_waitcnt lgkmcnt(8)
	ds_read_b128 v[30:33], v161 offset:13568
	ds_read_b128 v[34:37], v161 offset:21760
	ds_read_b128 v[46:49], v161 offset:29952
	ds_read_b64 v[80:81], v82 offset:46336
	ds_read_b128 v[38:41], v161 offset:5376
	ds_read_b128 v[42:45], v161 offset:38144
	v_pk_mul_f32 v[106:107], v[72:73], v[84:85]
	v_pk_mul_f32 v[108:109], v[76:77], v[84:85]
	v_pk_fma_f32 v[106:107], v[74:75], v[86:87], v[106:107]
	v_pk_fma_f32 v[108:109], v[78:79], v[86:87], v[108:109]
	v_add_f32_e32 v110, v106, v107
	v_add_f32_e32 v112, v108, v109
	s_nop 0
	v_add_f32_dpp v110, v110, v110 quad_perm:[1,0,3,2] row_mask:0xf bank_mask:0xf bound_ctrl:1
	v_add_f32_dpp v112, v112, v112 quad_perm:[1,0,3,2] row_mask:0xf bank_mask:0xf bound_ctrl:1
	s_nop 0
	v_add_f32_dpp v110, v110, v110 quad_perm:[2,3,0,1] row_mask:0xf bank_mask:0xf bound_ctrl:1
	v_add_f32_dpp v112, v112, v112 quad_perm:[2,3,0,1] row_mask:0xf bank_mask:0xf bound_ctrl:1
	s_nop 0
	v_add_f32_dpp v110, v110, v110 row_half_mirror row_mask:0xf bank_mask:0xf bound_ctrl:1
	v_add_f32_dpp v112, v112, v112 row_half_mirror row_mask:0xf bank_mask:0xf bound_ctrl:1
	s_nop 0
	v_add_f32_dpp v110, v110, v110 row_ror:8 row_mask:0xf bank_mask:0xf bound_ctrl:1
	v_add_f32_dpp v112, v112, v112 row_ror:8 row_mask:0xf bank_mask:0xf bound_ctrl:1
	v_pk_mul_f32 v[114:115], v[88:89], v[110:111] op_sel_hi:[1,0]
	v_pk_mul_f32 v[116:117], v[88:89], v[112:113] op_sel_hi:[1,0]
	v_pk_mul_f32 v[118:119], v[90:91], v[110:111] op_sel_hi:[1,0]
	v_pk_mul_f32 v[120:121], v[90:91], v[112:113] op_sel_hi:[1,0]
	v_pk_fma_f32 v[114:115], v[100:101], v[104:105], v[114:115] op_sel_hi:[1,0,1]
	v_pk_fma_f32 v[116:117], v[100:101], v[104:105], v[116:117] op_sel:[0,1,0]
	v_pk_fma_f32 v[118:119], v[102:103], v[104:105], v[118:119] op_sel_hi:[1,0,1]
	v_pk_fma_f32 v[120:121], v[102:103], v[104:105], v[120:121] op_sel:[0,1,0]
	v_pk_fma_f32 v[72:73], v[72:73], v[92:93], v[114:115]
	v_pk_fma_f32 v[76:77], v[76:77], v[92:93], v[116:117]
	v_pk_fma_f32 v[74:75], v[74:75], v[94:95], v[118:119]
	v_pk_fma_f32 v[78:79], v[78:79], v[94:95], v[120:121]
	v_pk_mul_f32 v[122:123], v[72:73], v[96:97]
	v_pk_mul_f32 v[124:125], v[76:77], v[96:97]
	v_pk_fma_f32 v[122:123], v[74:75], v[98:99], v[122:123]
	v_pk_fma_f32 v[124:125], v[78:79], v[98:99], v[124:125]
	v_add_f32_e32 v126, v122, v123
	v_add_f32_e32 v127, v124, v125
	ds_write_b64 v187, v[126:127] offset:38912
	s_waitcnt lgkmcnt(8)
	ds_read_b128 v[84:87], v161 offset:13824
	ds_read_b128 v[88:91], v161 offset:22016
	ds_read_b128 v[100:103], v161 offset:30208
	ds_read_b64 v[104:105], v82 offset:46592
	ds_read_b128 v[92:95], v161 offset:5632
	ds_read_b128 v[96:99], v161 offset:38400
	v_pk_mul_f32 v[106:107], v[72:73], v[128:129]
	v_pk_mul_f32 v[108:109], v[76:77], v[128:129]
	v_pk_fma_f32 v[106:107], v[74:75], v[130:131], v[106:107]
	v_pk_fma_f32 v[108:109], v[78:79], v[130:131], v[108:109]
	v_add_f32_e32 v110, v106, v107
	v_add_f32_e32 v112, v108, v109
	s_nop 0
	v_add_f32_dpp v110, v110, v110 quad_perm:[1,0,3,2] row_mask:0xf bank_mask:0xf bound_ctrl:1
	v_add_f32_dpp v112, v112, v112 quad_perm:[1,0,3,2] row_mask:0xf bank_mask:0xf bound_ctrl:1
	s_nop 0
	v_add_f32_dpp v110, v110, v110 quad_perm:[2,3,0,1] row_mask:0xf bank_mask:0xf bound_ctrl:1
	v_add_f32_dpp v112, v112, v112 quad_perm:[2,3,0,1] row_mask:0xf bank_mask:0xf bound_ctrl:1
	s_nop 0
	v_add_f32_dpp v110, v110, v110 row_half_mirror row_mask:0xf bank_mask:0xf bound_ctrl:1
	v_add_f32_dpp v112, v112, v112 row_half_mirror row_mask:0xf bank_mask:0xf bound_ctrl:1
	s_nop 0
	v_add_f32_dpp v110, v110, v110 row_ror:8 row_mask:0xf bank_mask:0xf bound_ctrl:1
	v_add_f32_dpp v112, v112, v112 row_ror:8 row_mask:0xf bank_mask:0xf bound_ctrl:1
	v_pk_mul_f32 v[114:115], v[132:133], v[110:111] op_sel_hi:[1,0]
	v_pk_mul_f32 v[116:117], v[132:133], v[112:113] op_sel_hi:[1,0]
	v_pk_mul_f32 v[118:119], v[134:135], v[110:111] op_sel_hi:[1,0]
	v_pk_mul_f32 v[120:121], v[134:135], v[112:113] op_sel_hi:[1,0]
	v_pk_fma_f32 v[114:115], v[194:195], v[198:199], v[114:115] op_sel_hi:[1,0,1]
	v_pk_fma_f32 v[116:117], v[194:195], v[198:199], v[116:117] op_sel:[0,1,0]
	v_pk_fma_f32 v[118:119], v[196:197], v[198:199], v[118:119] op_sel_hi:[1,0,1]
	v_pk_fma_f32 v[120:121], v[196:197], v[198:199], v[120:121] op_sel:[0,1,0]
	v_pk_fma_f32 v[72:73], v[72:73], v[136:137], v[114:115]
	v_pk_fma_f32 v[76:77], v[76:77], v[136:137], v[116:117]
	v_pk_fma_f32 v[74:75], v[74:75], v[138:139], v[118:119]
	v_pk_fma_f32 v[78:79], v[78:79], v[138:139], v[120:121]
	v_pk_mul_f32 v[122:123], v[72:73], v[140:141]
	v_pk_mul_f32 v[124:125], v[76:77], v[140:141]
	v_pk_fma_f32 v[122:123], v[74:75], v[142:143], v[122:123]
	v_pk_fma_f32 v[124:125], v[78:79], v[142:143], v[124:125]
	v_add_f32_e32 v126, v122, v123
	v_add_f32_e32 v127, v124, v125
	ds_write_b64 v187, v[126:127] offset:40960
	s_waitcnt lgkmcnt(8)
	ds_read_b128 v[128:131], v161 offset:14080
	ds_read_b128 v[132:135], v161 offset:22272
	ds_read_b128 v[194:197], v161 offset:30464
	ds_read_b64 v[198:199], v82 offset:46848
	ds_read_b128 v[136:139], v161 offset:5888
	ds_read_b128 v[140:143], v161 offset:38656
	v_pk_mul_f32 v[106:107], v[72:73], v[30:31]
	v_pk_mul_f32 v[108:109], v[76:77], v[30:31]
	v_pk_fma_f32 v[106:107], v[74:75], v[32:33], v[106:107]
	v_pk_fma_f32 v[108:109], v[78:79], v[32:33], v[108:109]
	v_add_f32_e32 v110, v106, v107
	v_add_f32_e32 v112, v108, v109
	s_nop 0
	v_add_f32_dpp v110, v110, v110 quad_perm:[1,0,3,2] row_mask:0xf bank_mask:0xf bound_ctrl:1
	v_add_f32_dpp v112, v112, v112 quad_perm:[1,0,3,2] row_mask:0xf bank_mask:0xf bound_ctrl:1
	s_nop 0
	v_add_f32_dpp v110, v110, v110 quad_perm:[2,3,0,1] row_mask:0xf bank_mask:0xf bound_ctrl:1
	v_add_f32_dpp v112, v112, v112 quad_perm:[2,3,0,1] row_mask:0xf bank_mask:0xf bound_ctrl:1
	s_nop 0
	v_add_f32_dpp v110, v110, v110 row_half_mirror row_mask:0xf bank_mask:0xf bound_ctrl:1
	v_add_f32_dpp v112, v112, v112 row_half_mirror row_mask:0xf bank_mask:0xf bound_ctrl:1
	s_nop 0
	v_add_f32_dpp v110, v110, v110 row_ror:8 row_mask:0xf bank_mask:0xf bound_ctrl:1
	v_add_f32_dpp v112, v112, v112 row_ror:8 row_mask:0xf bank_mask:0xf bound_ctrl:1
	v_pk_mul_f32 v[114:115], v[34:35], v[110:111] op_sel_hi:[1,0]
	v_pk_mul_f32 v[116:117], v[34:35], v[112:113] op_sel_hi:[1,0]
	v_pk_mul_f32 v[118:119], v[36:37], v[110:111] op_sel_hi:[1,0]
	v_pk_mul_f32 v[120:121], v[36:37], v[112:113] op_sel_hi:[1,0]
	v_pk_fma_f32 v[114:115], v[46:47], v[80:81], v[114:115] op_sel_hi:[1,0,1]
	v_pk_fma_f32 v[116:117], v[46:47], v[80:81], v[116:117] op_sel:[0,1,0]
	v_pk_fma_f32 v[118:119], v[48:49], v[80:81], v[118:119] op_sel_hi:[1,0,1]
	v_pk_fma_f32 v[120:121], v[48:49], v[80:81], v[120:121] op_sel:[0,1,0]
	v_pk_fma_f32 v[72:73], v[72:73], v[38:39], v[114:115]
	v_pk_fma_f32 v[76:77], v[76:77], v[38:39], v[116:117]
	v_pk_fma_f32 v[74:75], v[74:75], v[40:41], v[118:119]
	v_pk_fma_f32 v[78:79], v[78:79], v[40:41], v[120:121]
	v_pk_mul_f32 v[122:123], v[72:73], v[42:43]
	v_pk_mul_f32 v[124:125], v[76:77], v[42:43]
	v_pk_fma_f32 v[122:123], v[74:75], v[44:45], v[122:123]
	v_pk_fma_f32 v[124:125], v[78:79], v[44:45], v[124:125]
	v_add_f32_e32 v126, v122, v123
	v_add_f32_e32 v127, v124, v125
	ds_write_b64 v187, v[126:127] offset:43008
	s_waitcnt lgkmcnt(8)
	ds_read_b128 v[30:33], v161 offset:14336
	ds_read_b128 v[34:37], v161 offset:22528
	ds_read_b128 v[46:49], v161 offset:30720
	ds_read_b64 v[80:81], v82 offset:47104
	ds_read_b128 v[38:41], v161 offset:6144
	ds_read_b128 v[42:45], v161 offset:38912
	v_pk_mul_f32 v[106:107], v[72:73], v[84:85]
	v_pk_mul_f32 v[108:109], v[76:77], v[84:85]
	v_pk_fma_f32 v[106:107], v[74:75], v[86:87], v[106:107]
	v_pk_fma_f32 v[108:109], v[78:79], v[86:87], v[108:109]
	v_add_f32_e32 v110, v106, v107
	v_add_f32_e32 v112, v108, v109
	s_nop 0
	v_add_f32_dpp v110, v110, v110 quad_perm:[1,0,3,2] row_mask:0xf bank_mask:0xf bound_ctrl:1
	v_add_f32_dpp v112, v112, v112 quad_perm:[1,0,3,2] row_mask:0xf bank_mask:0xf bound_ctrl:1
	s_nop 0
	v_add_f32_dpp v110, v110, v110 quad_perm:[2,3,0,1] row_mask:0xf bank_mask:0xf bound_ctrl:1
	v_add_f32_dpp v112, v112, v112 quad_perm:[2,3,0,1] row_mask:0xf bank_mask:0xf bound_ctrl:1
	s_nop 0
	v_add_f32_dpp v110, v110, v110 row_half_mirror row_mask:0xf bank_mask:0xf bound_ctrl:1
	v_add_f32_dpp v112, v112, v112 row_half_mirror row_mask:0xf bank_mask:0xf bound_ctrl:1
	s_nop 0
	v_add_f32_dpp v110, v110, v110 row_ror:8 row_mask:0xf bank_mask:0xf bound_ctrl:1
	v_add_f32_dpp v112, v112, v112 row_ror:8 row_mask:0xf bank_mask:0xf bound_ctrl:1
	v_pk_mul_f32 v[114:115], v[88:89], v[110:111] op_sel_hi:[1,0]
	v_pk_mul_f32 v[116:117], v[88:89], v[112:113] op_sel_hi:[1,0]
	v_pk_mul_f32 v[118:119], v[90:91], v[110:111] op_sel_hi:[1,0]
	v_pk_mul_f32 v[120:121], v[90:91], v[112:113] op_sel_hi:[1,0]
	v_pk_fma_f32 v[114:115], v[100:101], v[104:105], v[114:115] op_sel_hi:[1,0,1]
	v_pk_fma_f32 v[116:117], v[100:101], v[104:105], v[116:117] op_sel:[0,1,0]
	v_pk_fma_f32 v[118:119], v[102:103], v[104:105], v[118:119] op_sel_hi:[1,0,1]
	v_pk_fma_f32 v[120:121], v[102:103], v[104:105], v[120:121] op_sel:[0,1,0]
	v_pk_fma_f32 v[72:73], v[72:73], v[92:93], v[114:115]
	v_pk_fma_f32 v[76:77], v[76:77], v[92:93], v[116:117]
	v_pk_fma_f32 v[74:75], v[74:75], v[94:95], v[118:119]
	v_pk_fma_f32 v[78:79], v[78:79], v[94:95], v[120:121]
	v_pk_mul_f32 v[122:123], v[72:73], v[96:97]
	v_pk_mul_f32 v[124:125], v[76:77], v[96:97]
	v_pk_fma_f32 v[122:123], v[74:75], v[98:99], v[122:123]
	v_pk_fma_f32 v[124:125], v[78:79], v[98:99], v[124:125]
	v_add_f32_e32 v126, v122, v123
	v_add_f32_e32 v127, v124, v125
	ds_write_b64 v187, v[126:127] offset:45056
	s_waitcnt lgkmcnt(8)
	ds_read_b128 v[84:87], v161 offset:14592
	ds_read_b128 v[88:91], v161 offset:22784
	ds_read_b128 v[100:103], v161 offset:30976
	ds_read_b64 v[104:105], v82 offset:47360
	ds_read_b128 v[92:95], v161 offset:6400
	ds_read_b128 v[96:99], v161 offset:39168
	v_pk_mul_f32 v[106:107], v[72:73], v[128:129]
	v_pk_mul_f32 v[108:109], v[76:77], v[128:129]
	v_pk_fma_f32 v[106:107], v[74:75], v[130:131], v[106:107]
	v_pk_fma_f32 v[108:109], v[78:79], v[130:131], v[108:109]
	v_add_f32_e32 v110, v106, v107
	v_add_f32_e32 v112, v108, v109
	s_nop 0
	v_add_f32_dpp v110, v110, v110 quad_perm:[1,0,3,2] row_mask:0xf bank_mask:0xf bound_ctrl:1
	v_add_f32_dpp v112, v112, v112 quad_perm:[1,0,3,2] row_mask:0xf bank_mask:0xf bound_ctrl:1
	s_nop 0
	v_add_f32_dpp v110, v110, v110 quad_perm:[2,3,0,1] row_mask:0xf bank_mask:0xf bound_ctrl:1
	v_add_f32_dpp v112, v112, v112 quad_perm:[2,3,0,1] row_mask:0xf bank_mask:0xf bound_ctrl:1
	s_nop 0
	v_add_f32_dpp v110, v110, v110 row_half_mirror row_mask:0xf bank_mask:0xf bound_ctrl:1
	v_add_f32_dpp v112, v112, v112 row_half_mirror row_mask:0xf bank_mask:0xf bound_ctrl:1
	s_nop 0
	v_add_f32_dpp v110, v110, v110 row_ror:8 row_mask:0xf bank_mask:0xf bound_ctrl:1
	v_add_f32_dpp v112, v112, v112 row_ror:8 row_mask:0xf bank_mask:0xf bound_ctrl:1
	v_pk_mul_f32 v[114:115], v[132:133], v[110:111] op_sel_hi:[1,0]
	v_pk_mul_f32 v[116:117], v[132:133], v[112:113] op_sel_hi:[1,0]
	v_pk_mul_f32 v[118:119], v[134:135], v[110:111] op_sel_hi:[1,0]
	v_pk_mul_f32 v[120:121], v[134:135], v[112:113] op_sel_hi:[1,0]
	v_pk_fma_f32 v[114:115], v[194:195], v[198:199], v[114:115] op_sel_hi:[1,0,1]
	v_pk_fma_f32 v[116:117], v[194:195], v[198:199], v[116:117] op_sel:[0,1,0]
	v_pk_fma_f32 v[118:119], v[196:197], v[198:199], v[118:119] op_sel_hi:[1,0,1]
	v_pk_fma_f32 v[120:121], v[196:197], v[198:199], v[120:121] op_sel:[0,1,0]
	v_pk_fma_f32 v[72:73], v[72:73], v[136:137], v[114:115]
	v_pk_fma_f32 v[76:77], v[76:77], v[136:137], v[116:117]
	v_pk_fma_f32 v[74:75], v[74:75], v[138:139], v[118:119]
	v_pk_fma_f32 v[78:79], v[78:79], v[138:139], v[120:121]
	v_pk_mul_f32 v[122:123], v[72:73], v[140:141]
	v_pk_mul_f32 v[124:125], v[76:77], v[140:141]
	v_pk_fma_f32 v[122:123], v[74:75], v[142:143], v[122:123]
	v_pk_fma_f32 v[124:125], v[78:79], v[142:143], v[124:125]
	v_add_f32_e32 v126, v122, v123
	v_add_f32_e32 v127, v124, v125
	ds_write_b64 v187, v[126:127] offset:47104
	s_waitcnt lgkmcnt(8)
	ds_read_b128 v[128:131], v161 offset:14848
	ds_read_b128 v[132:135], v161 offset:23040
	ds_read_b128 v[194:197], v161 offset:31232
	ds_read_b64 v[198:199], v82 offset:47616
	ds_read_b128 v[136:139], v161 offset:6656
	ds_read_b128 v[140:143], v161 offset:39424
	v_pk_mul_f32 v[106:107], v[72:73], v[30:31]
	v_pk_mul_f32 v[108:109], v[76:77], v[30:31]
	v_pk_fma_f32 v[106:107], v[74:75], v[32:33], v[106:107]
	v_pk_fma_f32 v[108:109], v[78:79], v[32:33], v[108:109]
	v_add_f32_e32 v110, v106, v107
	v_add_f32_e32 v112, v108, v109
	s_nop 0
	v_add_f32_dpp v110, v110, v110 quad_perm:[1,0,3,2] row_mask:0xf bank_mask:0xf bound_ctrl:1
	v_add_f32_dpp v112, v112, v112 quad_perm:[1,0,3,2] row_mask:0xf bank_mask:0xf bound_ctrl:1
	s_nop 0
	v_add_f32_dpp v110, v110, v110 quad_perm:[2,3,0,1] row_mask:0xf bank_mask:0xf bound_ctrl:1
	v_add_f32_dpp v112, v112, v112 quad_perm:[2,3,0,1] row_mask:0xf bank_mask:0xf bound_ctrl:1
	s_nop 0
	v_add_f32_dpp v110, v110, v110 row_half_mirror row_mask:0xf bank_mask:0xf bound_ctrl:1
	v_add_f32_dpp v112, v112, v112 row_half_mirror row_mask:0xf bank_mask:0xf bound_ctrl:1
	s_nop 0
	v_add_f32_dpp v110, v110, v110 row_ror:8 row_mask:0xf bank_mask:0xf bound_ctrl:1
	v_add_f32_dpp v112, v112, v112 row_ror:8 row_mask:0xf bank_mask:0xf bound_ctrl:1
	v_pk_mul_f32 v[114:115], v[34:35], v[110:111] op_sel_hi:[1,0]
	v_pk_mul_f32 v[116:117], v[34:35], v[112:113] op_sel_hi:[1,0]
	v_pk_mul_f32 v[118:119], v[36:37], v[110:111] op_sel_hi:[1,0]
	v_pk_mul_f32 v[120:121], v[36:37], v[112:113] op_sel_hi:[1,0]
	v_pk_fma_f32 v[114:115], v[46:47], v[80:81], v[114:115] op_sel_hi:[1,0,1]
	v_pk_fma_f32 v[116:117], v[46:47], v[80:81], v[116:117] op_sel:[0,1,0]
	v_pk_fma_f32 v[118:119], v[48:49], v[80:81], v[118:119] op_sel_hi:[1,0,1]
	v_pk_fma_f32 v[120:121], v[48:49], v[80:81], v[120:121] op_sel:[0,1,0]
	v_pk_fma_f32 v[72:73], v[72:73], v[38:39], v[114:115]
	v_pk_fma_f32 v[76:77], v[76:77], v[38:39], v[116:117]
	v_pk_fma_f32 v[74:75], v[74:75], v[40:41], v[118:119]
	v_pk_fma_f32 v[78:79], v[78:79], v[40:41], v[120:121]
	v_pk_mul_f32 v[122:123], v[72:73], v[42:43]
	v_pk_mul_f32 v[124:125], v[76:77], v[42:43]
	v_pk_fma_f32 v[122:123], v[74:75], v[44:45], v[122:123]
	v_pk_fma_f32 v[124:125], v[78:79], v[44:45], v[124:125]
	v_add_f32_e32 v126, v122, v123
	v_add_f32_e32 v127, v124, v125
	ds_write_b64 v187, v[126:127] offset:49152
	s_waitcnt lgkmcnt(8)
	ds_read_b128 v[30:33], v161 offset:15104
	ds_read_b128 v[34:37], v161 offset:23296
	ds_read_b128 v[46:49], v161 offset:31488
	ds_read_b64 v[80:81], v82 offset:47872
	ds_read_b128 v[38:41], v161 offset:6912
	ds_read_b128 v[42:45], v161 offset:39680
	v_pk_mul_f32 v[106:107], v[72:73], v[84:85]
	v_pk_mul_f32 v[108:109], v[76:77], v[84:85]
	v_pk_fma_f32 v[106:107], v[74:75], v[86:87], v[106:107]
	v_pk_fma_f32 v[108:109], v[78:79], v[86:87], v[108:109]
	v_add_f32_e32 v110, v106, v107
	v_add_f32_e32 v112, v108, v109
	s_nop 0
	v_add_f32_dpp v110, v110, v110 quad_perm:[1,0,3,2] row_mask:0xf bank_mask:0xf bound_ctrl:1
	v_add_f32_dpp v112, v112, v112 quad_perm:[1,0,3,2] row_mask:0xf bank_mask:0xf bound_ctrl:1
	s_nop 0
	v_add_f32_dpp v110, v110, v110 quad_perm:[2,3,0,1] row_mask:0xf bank_mask:0xf bound_ctrl:1
	v_add_f32_dpp v112, v112, v112 quad_perm:[2,3,0,1] row_mask:0xf bank_mask:0xf bound_ctrl:1
	s_nop 0
	v_add_f32_dpp v110, v110, v110 row_half_mirror row_mask:0xf bank_mask:0xf bound_ctrl:1
	v_add_f32_dpp v112, v112, v112 row_half_mirror row_mask:0xf bank_mask:0xf bound_ctrl:1
	s_nop 0
	v_add_f32_dpp v110, v110, v110 row_ror:8 row_mask:0xf bank_mask:0xf bound_ctrl:1
	v_add_f32_dpp v112, v112, v112 row_ror:8 row_mask:0xf bank_mask:0xf bound_ctrl:1
	v_pk_mul_f32 v[114:115], v[88:89], v[110:111] op_sel_hi:[1,0]
	v_pk_mul_f32 v[116:117], v[88:89], v[112:113] op_sel_hi:[1,0]
	v_pk_mul_f32 v[118:119], v[90:91], v[110:111] op_sel_hi:[1,0]
	v_pk_mul_f32 v[120:121], v[90:91], v[112:113] op_sel_hi:[1,0]
	v_pk_fma_f32 v[114:115], v[100:101], v[104:105], v[114:115] op_sel_hi:[1,0,1]
	v_pk_fma_f32 v[116:117], v[100:101], v[104:105], v[116:117] op_sel:[0,1,0]
	v_pk_fma_f32 v[118:119], v[102:103], v[104:105], v[118:119] op_sel_hi:[1,0,1]
	v_pk_fma_f32 v[120:121], v[102:103], v[104:105], v[120:121] op_sel:[0,1,0]
	v_pk_fma_f32 v[72:73], v[72:73], v[92:93], v[114:115]
	v_pk_fma_f32 v[76:77], v[76:77], v[92:93], v[116:117]
	v_pk_fma_f32 v[74:75], v[74:75], v[94:95], v[118:119]
	v_pk_fma_f32 v[78:79], v[78:79], v[94:95], v[120:121]
	v_pk_mul_f32 v[122:123], v[72:73], v[96:97]
	v_pk_mul_f32 v[124:125], v[76:77], v[96:97]
	v_pk_fma_f32 v[122:123], v[74:75], v[98:99], v[122:123]
	v_pk_fma_f32 v[124:125], v[78:79], v[98:99], v[124:125]
	v_add_f32_e32 v126, v122, v123
	v_add_f32_e32 v127, v124, v125
	ds_write_b64 v187, v[126:127] offset:51200
	s_waitcnt lgkmcnt(8)
	ds_read_b128 v[84:87], v161 offset:15360
	ds_read_b128 v[88:91], v161 offset:23552
	ds_read_b128 v[100:103], v161 offset:31744
	ds_read_b64 v[104:105], v82 offset:48128
	ds_read_b128 v[92:95], v161 offset:7168
	ds_read_b128 v[96:99], v161 offset:39936
	v_pk_mul_f32 v[106:107], v[72:73], v[128:129]
	v_pk_mul_f32 v[108:109], v[76:77], v[128:129]
	v_pk_fma_f32 v[106:107], v[74:75], v[130:131], v[106:107]
	v_pk_fma_f32 v[108:109], v[78:79], v[130:131], v[108:109]
	v_add_f32_e32 v110, v106, v107
	v_add_f32_e32 v112, v108, v109
	s_nop 0
	v_add_f32_dpp v110, v110, v110 quad_perm:[1,0,3,2] row_mask:0xf bank_mask:0xf bound_ctrl:1
	v_add_f32_dpp v112, v112, v112 quad_perm:[1,0,3,2] row_mask:0xf bank_mask:0xf bound_ctrl:1
	s_nop 0
	v_add_f32_dpp v110, v110, v110 quad_perm:[2,3,0,1] row_mask:0xf bank_mask:0xf bound_ctrl:1
	v_add_f32_dpp v112, v112, v112 quad_perm:[2,3,0,1] row_mask:0xf bank_mask:0xf bound_ctrl:1
	s_nop 0
	v_add_f32_dpp v110, v110, v110 row_half_mirror row_mask:0xf bank_mask:0xf bound_ctrl:1
	v_add_f32_dpp v112, v112, v112 row_half_mirror row_mask:0xf bank_mask:0xf bound_ctrl:1
	s_nop 0
	v_add_f32_dpp v110, v110, v110 row_ror:8 row_mask:0xf bank_mask:0xf bound_ctrl:1
	v_add_f32_dpp v112, v112, v112 row_ror:8 row_mask:0xf bank_mask:0xf bound_ctrl:1
	v_pk_mul_f32 v[114:115], v[132:133], v[110:111] op_sel_hi:[1,0]
	v_pk_mul_f32 v[116:117], v[132:133], v[112:113] op_sel_hi:[1,0]
	v_pk_mul_f32 v[118:119], v[134:135], v[110:111] op_sel_hi:[1,0]
	v_pk_mul_f32 v[120:121], v[134:135], v[112:113] op_sel_hi:[1,0]
	v_pk_fma_f32 v[114:115], v[194:195], v[198:199], v[114:115] op_sel_hi:[1,0,1]
	v_pk_fma_f32 v[116:117], v[194:195], v[198:199], v[116:117] op_sel:[0,1,0]
	v_pk_fma_f32 v[118:119], v[196:197], v[198:199], v[118:119] op_sel_hi:[1,0,1]
	v_pk_fma_f32 v[120:121], v[196:197], v[198:199], v[120:121] op_sel:[0,1,0]
	v_pk_fma_f32 v[72:73], v[72:73], v[136:137], v[114:115]
	v_pk_fma_f32 v[76:77], v[76:77], v[136:137], v[116:117]
	v_pk_fma_f32 v[74:75], v[74:75], v[138:139], v[118:119]
	v_pk_fma_f32 v[78:79], v[78:79], v[138:139], v[120:121]
	v_pk_mul_f32 v[122:123], v[72:73], v[140:141]
	v_pk_mul_f32 v[124:125], v[76:77], v[140:141]
	v_pk_fma_f32 v[122:123], v[74:75], v[142:143], v[122:123]
	v_pk_fma_f32 v[124:125], v[78:79], v[142:143], v[124:125]
	v_add_f32_e32 v126, v122, v123
	v_add_f32_e32 v127, v124, v125
	ds_write_b64 v187, v[126:127] offset:53248
	s_waitcnt lgkmcnt(8)
	ds_read_b128 v[128:131], v161 offset:15616
	ds_read_b128 v[132:135], v161 offset:23808
	ds_read_b128 v[194:197], v161 offset:32000
	ds_read_b64 v[198:199], v82 offset:48384
	ds_read_b128 v[136:139], v161 offset:7424
	ds_read_b128 v[140:143], v161 offset:40192
	v_pk_mul_f32 v[106:107], v[72:73], v[30:31]
	v_pk_mul_f32 v[108:109], v[76:77], v[30:31]
	v_pk_fma_f32 v[106:107], v[74:75], v[32:33], v[106:107]
	v_pk_fma_f32 v[108:109], v[78:79], v[32:33], v[108:109]
	v_add_f32_e32 v110, v106, v107
	v_add_f32_e32 v112, v108, v109
	s_nop 0
	v_add_f32_dpp v110, v110, v110 quad_perm:[1,0,3,2] row_mask:0xf bank_mask:0xf bound_ctrl:1
	v_add_f32_dpp v112, v112, v112 quad_perm:[1,0,3,2] row_mask:0xf bank_mask:0xf bound_ctrl:1
	s_nop 0
	v_add_f32_dpp v110, v110, v110 quad_perm:[2,3,0,1] row_mask:0xf bank_mask:0xf bound_ctrl:1
	v_add_f32_dpp v112, v112, v112 quad_perm:[2,3,0,1] row_mask:0xf bank_mask:0xf bound_ctrl:1
	s_nop 0
	v_add_f32_dpp v110, v110, v110 row_half_mirror row_mask:0xf bank_mask:0xf bound_ctrl:1
	v_add_f32_dpp v112, v112, v112 row_half_mirror row_mask:0xf bank_mask:0xf bound_ctrl:1
	s_nop 0
	v_add_f32_dpp v110, v110, v110 row_ror:8 row_mask:0xf bank_mask:0xf bound_ctrl:1
	v_add_f32_dpp v112, v112, v112 row_ror:8 row_mask:0xf bank_mask:0xf bound_ctrl:1
	v_pk_mul_f32 v[114:115], v[34:35], v[110:111] op_sel_hi:[1,0]
	v_pk_mul_f32 v[116:117], v[34:35], v[112:113] op_sel_hi:[1,0]
	v_pk_mul_f32 v[118:119], v[36:37], v[110:111] op_sel_hi:[1,0]
	v_pk_mul_f32 v[120:121], v[36:37], v[112:113] op_sel_hi:[1,0]
	v_pk_fma_f32 v[114:115], v[46:47], v[80:81], v[114:115] op_sel_hi:[1,0,1]
	v_pk_fma_f32 v[116:117], v[46:47], v[80:81], v[116:117] op_sel:[0,1,0]
	v_pk_fma_f32 v[118:119], v[48:49], v[80:81], v[118:119] op_sel_hi:[1,0,1]
	v_pk_fma_f32 v[120:121], v[48:49], v[80:81], v[120:121] op_sel:[0,1,0]
	v_pk_fma_f32 v[72:73], v[72:73], v[38:39], v[114:115]
	v_pk_fma_f32 v[76:77], v[76:77], v[38:39], v[116:117]
	v_pk_fma_f32 v[74:75], v[74:75], v[40:41], v[118:119]
	v_pk_fma_f32 v[78:79], v[78:79], v[40:41], v[120:121]
	v_pk_mul_f32 v[122:123], v[72:73], v[42:43]
	v_pk_mul_f32 v[124:125], v[76:77], v[42:43]
	v_pk_fma_f32 v[122:123], v[74:75], v[44:45], v[122:123]
	v_pk_fma_f32 v[124:125], v[78:79], v[44:45], v[124:125]
	v_add_f32_e32 v126, v122, v123
	v_add_f32_e32 v127, v124, v125
	ds_write_b64 v187, v[126:127] offset:55296
	s_waitcnt lgkmcnt(8)
	ds_read_b128 v[30:33], v161 offset:15872
	ds_read_b128 v[34:37], v161 offset:24064
	ds_read_b128 v[46:49], v161 offset:32256
	ds_read_b64 v[80:81], v82 offset:48640
	ds_read_b128 v[38:41], v161 offset:7680
	ds_read_b128 v[42:45], v161 offset:40448
	v_pk_mul_f32 v[106:107], v[72:73], v[84:85]
	v_pk_mul_f32 v[108:109], v[76:77], v[84:85]
	v_pk_fma_f32 v[106:107], v[74:75], v[86:87], v[106:107]
	v_pk_fma_f32 v[108:109], v[78:79], v[86:87], v[108:109]
	v_add_f32_e32 v110, v106, v107
	v_add_f32_e32 v112, v108, v109
	s_nop 0
	v_add_f32_dpp v110, v110, v110 quad_perm:[1,0,3,2] row_mask:0xf bank_mask:0xf bound_ctrl:1
	v_add_f32_dpp v112, v112, v112 quad_perm:[1,0,3,2] row_mask:0xf bank_mask:0xf bound_ctrl:1
	s_nop 0
	v_add_f32_dpp v110, v110, v110 quad_perm:[2,3,0,1] row_mask:0xf bank_mask:0xf bound_ctrl:1
	v_add_f32_dpp v112, v112, v112 quad_perm:[2,3,0,1] row_mask:0xf bank_mask:0xf bound_ctrl:1
	s_nop 0
	v_add_f32_dpp v110, v110, v110 row_half_mirror row_mask:0xf bank_mask:0xf bound_ctrl:1
	v_add_f32_dpp v112, v112, v112 row_half_mirror row_mask:0xf bank_mask:0xf bound_ctrl:1
	s_nop 0
	v_add_f32_dpp v110, v110, v110 row_ror:8 row_mask:0xf bank_mask:0xf bound_ctrl:1
	v_add_f32_dpp v112, v112, v112 row_ror:8 row_mask:0xf bank_mask:0xf bound_ctrl:1
	v_pk_mul_f32 v[114:115], v[88:89], v[110:111] op_sel_hi:[1,0]
	v_pk_mul_f32 v[116:117], v[88:89], v[112:113] op_sel_hi:[1,0]
	v_pk_mul_f32 v[118:119], v[90:91], v[110:111] op_sel_hi:[1,0]
	v_pk_mul_f32 v[120:121], v[90:91], v[112:113] op_sel_hi:[1,0]
	v_pk_fma_f32 v[114:115], v[100:101], v[104:105], v[114:115] op_sel_hi:[1,0,1]
	v_pk_fma_f32 v[116:117], v[100:101], v[104:105], v[116:117] op_sel:[0,1,0]
	v_pk_fma_f32 v[118:119], v[102:103], v[104:105], v[118:119] op_sel_hi:[1,0,1]
	v_pk_fma_f32 v[120:121], v[102:103], v[104:105], v[120:121] op_sel:[0,1,0]
	v_pk_fma_f32 v[72:73], v[72:73], v[92:93], v[114:115]
	v_pk_fma_f32 v[76:77], v[76:77], v[92:93], v[116:117]
	v_pk_fma_f32 v[74:75], v[74:75], v[94:95], v[118:119]
	v_pk_fma_f32 v[78:79], v[78:79], v[94:95], v[120:121]
	v_pk_mul_f32 v[122:123], v[72:73], v[96:97]
	v_pk_mul_f32 v[124:125], v[76:77], v[96:97]
	v_pk_fma_f32 v[122:123], v[74:75], v[98:99], v[122:123]
	v_pk_fma_f32 v[124:125], v[78:79], v[98:99], v[124:125]
	v_add_f32_e32 v126, v122, v123
	v_add_f32_e32 v127, v124, v125
	ds_write_b64 v187, v[126:127] offset:57344
	s_waitcnt lgkmcnt(8)
	ds_read_b128 v[84:87], v161 offset:16128
	ds_read_b128 v[88:91], v161 offset:24320
	ds_read_b128 v[100:103], v161 offset:32512
	ds_read_b64 v[104:105], v82 offset:48896
	ds_read_b128 v[92:95], v161 offset:7936
	ds_read_b128 v[96:99], v161 offset:40704
	v_pk_mul_f32 v[106:107], v[72:73], v[128:129]
	v_pk_mul_f32 v[108:109], v[76:77], v[128:129]
	v_pk_fma_f32 v[106:107], v[74:75], v[130:131], v[106:107]
	v_pk_fma_f32 v[108:109], v[78:79], v[130:131], v[108:109]
	v_add_f32_e32 v110, v106, v107
	v_add_f32_e32 v112, v108, v109
	s_nop 0
	v_add_f32_dpp v110, v110, v110 quad_perm:[1,0,3,2] row_mask:0xf bank_mask:0xf bound_ctrl:1
	v_add_f32_dpp v112, v112, v112 quad_perm:[1,0,3,2] row_mask:0xf bank_mask:0xf bound_ctrl:1
	s_nop 0
	v_add_f32_dpp v110, v110, v110 quad_perm:[2,3,0,1] row_mask:0xf bank_mask:0xf bound_ctrl:1
	v_add_f32_dpp v112, v112, v112 quad_perm:[2,3,0,1] row_mask:0xf bank_mask:0xf bound_ctrl:1
	s_nop 0
	v_add_f32_dpp v110, v110, v110 row_half_mirror row_mask:0xf bank_mask:0xf bound_ctrl:1
	v_add_f32_dpp v112, v112, v112 row_half_mirror row_mask:0xf bank_mask:0xf bound_ctrl:1
	s_nop 0
	v_add_f32_dpp v110, v110, v110 row_ror:8 row_mask:0xf bank_mask:0xf bound_ctrl:1
	v_add_f32_dpp v112, v112, v112 row_ror:8 row_mask:0xf bank_mask:0xf bound_ctrl:1
	v_pk_mul_f32 v[114:115], v[132:133], v[110:111] op_sel_hi:[1,0]
	v_pk_mul_f32 v[116:117], v[132:133], v[112:113] op_sel_hi:[1,0]
	v_pk_mul_f32 v[118:119], v[134:135], v[110:111] op_sel_hi:[1,0]
	v_pk_mul_f32 v[120:121], v[134:135], v[112:113] op_sel_hi:[1,0]
	v_pk_fma_f32 v[114:115], v[194:195], v[198:199], v[114:115] op_sel_hi:[1,0,1]
	v_pk_fma_f32 v[116:117], v[194:195], v[198:199], v[116:117] op_sel:[0,1,0]
	v_pk_fma_f32 v[118:119], v[196:197], v[198:199], v[118:119] op_sel_hi:[1,0,1]
	v_pk_fma_f32 v[120:121], v[196:197], v[198:199], v[120:121] op_sel:[0,1,0]
	v_pk_fma_f32 v[72:73], v[72:73], v[136:137], v[114:115]
	v_pk_fma_f32 v[76:77], v[76:77], v[136:137], v[116:117]
	v_pk_fma_f32 v[74:75], v[74:75], v[138:139], v[118:119]
	v_pk_fma_f32 v[78:79], v[78:79], v[138:139], v[120:121]
	v_pk_mul_f32 v[122:123], v[72:73], v[140:141]
	v_pk_mul_f32 v[124:125], v[76:77], v[140:141]
	v_pk_fma_f32 v[122:123], v[74:75], v[142:143], v[122:123]
	v_pk_fma_f32 v[124:125], v[78:79], v[142:143], v[124:125]
	v_add_f32_e32 v126, v122, v123
	v_add_f32_e32 v127, v124, v125
	ds_write_b64 v187, v[126:127] offset:59392
	s_waitcnt lgkmcnt(8)
	v_pk_mul_f32 v[106:107], v[72:73], v[30:31]
	v_pk_mul_f32 v[108:109], v[76:77], v[30:31]
	v_pk_fma_f32 v[106:107], v[74:75], v[32:33], v[106:107]
	v_pk_fma_f32 v[108:109], v[78:79], v[32:33], v[108:109]
	v_add_f32_e32 v110, v106, v107
	v_add_f32_e32 v112, v108, v109
	s_nop 0
	v_add_f32_dpp v110, v110, v110 quad_perm:[1,0,3,2] row_mask:0xf bank_mask:0xf bound_ctrl:1
	v_add_f32_dpp v112, v112, v112 quad_perm:[1,0,3,2] row_mask:0xf bank_mask:0xf bound_ctrl:1
	s_nop 0
	v_add_f32_dpp v110, v110, v110 quad_perm:[2,3,0,1] row_mask:0xf bank_mask:0xf bound_ctrl:1
	v_add_f32_dpp v112, v112, v112 quad_perm:[2,3,0,1] row_mask:0xf bank_mask:0xf bound_ctrl:1
	s_nop 0
	v_add_f32_dpp v110, v110, v110 row_half_mirror row_mask:0xf bank_mask:0xf bound_ctrl:1
	v_add_f32_dpp v112, v112, v112 row_half_mirror row_mask:0xf bank_mask:0xf bound_ctrl:1
	s_nop 0
	v_add_f32_dpp v110, v110, v110 row_ror:8 row_mask:0xf bank_mask:0xf bound_ctrl:1
	v_add_f32_dpp v112, v112, v112 row_ror:8 row_mask:0xf bank_mask:0xf bound_ctrl:1
	v_pk_mul_f32 v[114:115], v[34:35], v[110:111] op_sel_hi:[1,0]
	v_pk_mul_f32 v[116:117], v[34:35], v[112:113] op_sel_hi:[1,0]
	v_pk_mul_f32 v[118:119], v[36:37], v[110:111] op_sel_hi:[1,0]
	v_pk_mul_f32 v[120:121], v[36:37], v[112:113] op_sel_hi:[1,0]
	v_pk_fma_f32 v[114:115], v[46:47], v[80:81], v[114:115] op_sel_hi:[1,0,1]
	v_pk_fma_f32 v[116:117], v[46:47], v[80:81], v[116:117] op_sel:[0,1,0]
	v_pk_fma_f32 v[118:119], v[48:49], v[80:81], v[118:119] op_sel_hi:[1,0,1]
	v_pk_fma_f32 v[120:121], v[48:49], v[80:81], v[120:121] op_sel:[0,1,0]
	v_pk_fma_f32 v[72:73], v[72:73], v[38:39], v[114:115]
	v_pk_fma_f32 v[76:77], v[76:77], v[38:39], v[116:117]
	v_pk_fma_f32 v[74:75], v[74:75], v[40:41], v[118:119]
	v_pk_fma_f32 v[78:79], v[78:79], v[40:41], v[120:121]
	v_pk_mul_f32 v[122:123], v[72:73], v[42:43]
	v_pk_mul_f32 v[124:125], v[76:77], v[42:43]
	v_pk_fma_f32 v[122:123], v[74:75], v[44:45], v[122:123]
	v_pk_fma_f32 v[124:125], v[78:79], v[44:45], v[124:125]
	v_add_f32_e32 v126, v122, v123
	v_add_f32_e32 v127, v124, v125
	ds_write_b64 v187, v[126:127] offset:61440
	s_waitcnt lgkmcnt(2)
	v_pk_mul_f32 v[106:107], v[72:73], v[84:85]
	v_pk_mul_f32 v[108:109], v[76:77], v[84:85]
	v_pk_fma_f32 v[106:107], v[74:75], v[86:87], v[106:107]
	v_pk_fma_f32 v[108:109], v[78:79], v[86:87], v[108:109]
	v_add_f32_e32 v110, v106, v107
	v_add_f32_e32 v112, v108, v109
	s_nop 0
	v_add_f32_dpp v110, v110, v110 quad_perm:[1,0,3,2] row_mask:0xf bank_mask:0xf bound_ctrl:1
	v_add_f32_dpp v112, v112, v112 quad_perm:[1,0,3,2] row_mask:0xf bank_mask:0xf bound_ctrl:1
	s_nop 0
	v_add_f32_dpp v110, v110, v110 quad_perm:[2,3,0,1] row_mask:0xf bank_mask:0xf bound_ctrl:1
	v_add_f32_dpp v112, v112, v112 quad_perm:[2,3,0,1] row_mask:0xf bank_mask:0xf bound_ctrl:1
	s_nop 0
	v_add_f32_dpp v110, v110, v110 row_half_mirror row_mask:0xf bank_mask:0xf bound_ctrl:1
	v_add_f32_dpp v112, v112, v112 row_half_mirror row_mask:0xf bank_mask:0xf bound_ctrl:1
	s_nop 0
	v_add_f32_dpp v110, v110, v110 row_ror:8 row_mask:0xf bank_mask:0xf bound_ctrl:1
	v_add_f32_dpp v112, v112, v112 row_ror:8 row_mask:0xf bank_mask:0xf bound_ctrl:1
	v_pk_mul_f32 v[114:115], v[88:89], v[110:111] op_sel_hi:[1,0]
	v_pk_mul_f32 v[116:117], v[88:89], v[112:113] op_sel_hi:[1,0]
	v_pk_mul_f32 v[118:119], v[90:91], v[110:111] op_sel_hi:[1,0]
	v_pk_mul_f32 v[120:121], v[90:91], v[112:113] op_sel_hi:[1,0]
	v_pk_fma_f32 v[114:115], v[100:101], v[104:105], v[114:115] op_sel_hi:[1,0,1]
	v_pk_fma_f32 v[116:117], v[100:101], v[104:105], v[116:117] op_sel:[0,1,0]
	v_pk_fma_f32 v[118:119], v[102:103], v[104:105], v[118:119] op_sel_hi:[1,0,1]
	v_pk_fma_f32 v[120:121], v[102:103], v[104:105], v[120:121] op_sel:[0,1,0]
	v_pk_fma_f32 v[72:73], v[72:73], v[92:93], v[114:115]
	v_pk_fma_f32 v[76:77], v[76:77], v[92:93], v[116:117]
	v_pk_fma_f32 v[74:75], v[74:75], v[94:95], v[118:119]
	v_pk_fma_f32 v[78:79], v[78:79], v[94:95], v[120:121]
	v_pk_mul_f32 v[122:123], v[72:73], v[96:97]
	v_pk_mul_f32 v[124:125], v[76:77], v[96:97]
	v_pk_fma_f32 v[122:123], v[74:75], v[98:99], v[122:123]
	v_pk_fma_f32 v[124:125], v[78:79], v[98:99], v[124:125]
	v_add_f32_e32 v126, v122, v123
	v_add_f32_e32 v127, v124, v125
	ds_write_b64 v187, v[126:127] offset:63488

.LBB0_3086:
	s_and_saveexec_b64 s[30:31], s[22:23]
	s_cbranch_execz .LBB0_3089
	ds_read_b128 v[30:33], v161 offset:8192
	ds_read_b128 v[34:37], v161 offset:16384
	ds_read_b128 v[46:49], v161 offset:24576
	ds_read_b64 v[80:81], v82 offset:40960
	ds_read_b128 v[38:41], v161
	ds_read_b128 v[42:45], v161 offset:32768
	ds_read_b128 v[84:87], v161 offset:8448
	ds_read_b128 v[88:91], v161 offset:16640
	ds_read_b128 v[100:103], v161 offset:24832
	ds_read_b64 v[104:105], v82 offset:41216
	ds_read_b128 v[92:95], v161 offset:256
	ds_read_b128 v[96:99], v161 offset:33024
	s_waitcnt lgkmcnt(6)
	ds_read_b128 v[128:131], v161 offset:8704
	ds_read_b128 v[132:135], v161 offset:16896
	ds_read_b128 v[194:197], v161 offset:25088
	ds_read_b64 v[198:199], v82 offset:41472
	ds_read_b128 v[136:139], v161 offset:512
	ds_read_b128 v[140:143], v161 offset:33280
	v_pk_mul_f32 v[106:107], v[72:73], v[30:31]
	v_pk_mul_f32 v[108:109], v[76:77], v[30:31]
	v_pk_fma_f32 v[106:107], v[74:75], v[32:33], v[106:107]
	v_pk_fma_f32 v[108:109], v[78:79], v[32:33], v[108:109]
	v_add_f32_e32 v110, v106, v107
	v_add_f32_e32 v112, v108, v109
	s_nop 0
	v_add_f32_dpp v110, v110, v110 quad_perm:[1,0,3,2] row_mask:0xf bank_mask:0xf bound_ctrl:1
	v_add_f32_dpp v112, v112, v112 quad_perm:[1,0,3,2] row_mask:0xf bank_mask:0xf bound_ctrl:1
	s_nop 0
	v_add_f32_dpp v110, v110, v110 quad_perm:[2,3,0,1] row_mask:0xf bank_mask:0xf bound_ctrl:1
	v_add_f32_dpp v112, v112, v112 quad_perm:[2,3,0,1] row_mask:0xf bank_mask:0xf bound_ctrl:1
	s_nop 0
	v_add_f32_dpp v110, v110, v110 row_half_mirror row_mask:0xf bank_mask:0xf bound_ctrl:1
	v_add_f32_dpp v112, v112, v112 row_half_mirror row_mask:0xf bank_mask:0xf bound_ctrl:1
	s_nop 0
	v_add_f32_dpp v110, v110, v110 row_ror:8 row_mask:0xf bank_mask:0xf bound_ctrl:1
	v_add_f32_dpp v112, v112, v112 row_ror:8 row_mask:0xf bank_mask:0xf bound_ctrl:1
	v_pk_mul_f32 v[114:115], v[34:35], v[110:111] op_sel_hi:[1,0]
	v_pk_mul_f32 v[116:117], v[34:35], v[112:113] op_sel_hi:[1,0]
	v_pk_mul_f32 v[118:119], v[36:37], v[110:111] op_sel_hi:[1,0]
	v_pk_mul_f32 v[120:121], v[36:37], v[112:113] op_sel_hi:[1,0]
	v_pk_fma_f32 v[114:115], v[46:47], v[80:81], v[114:115] op_sel_hi:[1,0,1]
	v_pk_fma_f32 v[116:117], v[46:47], v[80:81], v[116:117] op_sel:[0,1,0]
	v_pk_fma_f32 v[118:119], v[48:49], v[80:81], v[118:119] op_sel_hi:[1,0,1]
	v_pk_fma_f32 v[120:121], v[48:49], v[80:81], v[120:121] op_sel:[0,1,0]
	v_pk_fma_f32 v[72:73], v[72:73], v[38:39], v[114:115]
	v_pk_fma_f32 v[76:77], v[76:77], v[38:39], v[116:117]
	v_pk_fma_f32 v[74:75], v[74:75], v[40:41], v[118:119]
	v_pk_fma_f32 v[78:79], v[78:79], v[40:41], v[120:121]
	v_pk_mul_f32 v[122:123], v[72:73], v[42:43]
	v_pk_mul_f32 v[124:125], v[76:77], v[42:43]
	v_pk_fma_f32 v[122:123], v[74:75], v[44:45], v[122:123]
	v_pk_fma_f32 v[124:125], v[78:79], v[44:45], v[124:125]
	v_add_f32_e32 v126, v122, v123
	v_add_f32_e32 v127, v124, v125
	ds_write_b64 v187, v[126:127]
	s_waitcnt lgkmcnt(7)
	ds_read_b128 v[30:33], v161 offset:8960
	ds_read_b128 v[34:37], v161 offset:17152
	ds_read_b128 v[46:49], v161 offset:25344
	ds_read_b64 v[80:81], v82 offset:41728
	ds_read_b128 v[38:41], v161 offset:768
	ds_read_b128 v[42:45], v161 offset:33536
	v_pk_mul_f32 v[106:107], v[72:73], v[84:85]
	v_pk_mul_f32 v[108:109], v[76:77], v[84:85]
	v_pk_fma_f32 v[106:107], v[74:75], v[86:87], v[106:107]
	v_pk_fma_f32 v[108:109], v[78:79], v[86:87], v[108:109]
	v_add_f32_e32 v110, v106, v107
	v_add_f32_e32 v112, v108, v109
	s_nop 0
	v_add_f32_dpp v110, v110, v110 quad_perm:[1,0,3,2] row_mask:0xf bank_mask:0xf bound_ctrl:1
	v_add_f32_dpp v112, v112, v112 quad_perm:[1,0,3,2] row_mask:0xf bank_mask:0xf bound_ctrl:1
	s_nop 0
	v_add_f32_dpp v110, v110, v110 quad_perm:[2,3,0,1] row_mask:0xf bank_mask:0xf bound_ctrl:1
	v_add_f32_dpp v112, v112, v112 quad_perm:[2,3,0,1] row_mask:0xf bank_mask:0xf bound_ctrl:1
	s_nop 0
	v_add_f32_dpp v110, v110, v110 row_half_mirror row_mask:0xf bank_mask:0xf bound_ctrl:1
	v_add_f32_dpp v112, v112, v112 row_half_mirror row_mask:0xf bank_mask:0xf bound_ctrl:1
	s_nop 0
	v_add_f32_dpp v110, v110, v110 row_ror:8 row_mask:0xf bank_mask:0xf bound_ctrl:1
	v_add_f32_dpp v112, v112, v112 row_ror:8 row_mask:0xf bank_mask:0xf bound_ctrl:1
	v_pk_mul_f32 v[114:115], v[88:89], v[110:111] op_sel_hi:[1,0]
	v_pk_mul_f32 v[116:117], v[88:89], v[112:113] op_sel_hi:[1,0]
	v_pk_mul_f32 v[118:119], v[90:91], v[110:111] op_sel_hi:[1,0]
	v_pk_mul_f32 v[120:121], v[90:91], v[112:113] op_sel_hi:[1,0]
	v_pk_fma_f32 v[114:115], v[100:101], v[104:105], v[114:115] op_sel_hi:[1,0,1]
	v_pk_fma_f32 v[116:117], v[100:101], v[104:105], v[116:117] op_sel:[0,1,0]
	v_pk_fma_f32 v[118:119], v[102:103], v[104:105], v[118:119] op_sel_hi:[1,0,1]
	v_pk_fma_f32 v[120:121], v[102:103], v[104:105], v[120:121] op_sel:[0,1,0]
	v_pk_fma_f32 v[72:73], v[72:73], v[92:93], v[114:115]
	v_pk_fma_f32 v[76:77], v[76:77], v[92:93], v[116:117]
	v_pk_fma_f32 v[74:75], v[74:75], v[94:95], v[118:119]
	v_pk_fma_f32 v[78:79], v[78:79], v[94:95], v[120:121]
	v_pk_mul_f32 v[122:123], v[72:73], v[96:97]
	v_pk_mul_f32 v[124:125], v[76:77], v[96:97]
	v_pk_fma_f32 v[122:123], v[74:75], v[98:99], v[122:123]
	v_pk_fma_f32 v[124:125], v[78:79], v[98:99], v[124:125]
	v_add_f32_e32 v126, v122, v123
	v_add_f32_e32 v127, v124, v125
	ds_write_b64 v187, v[126:127] offset:2048
	s_waitcnt lgkmcnt(8)
	ds_read_b128 v[84:87], v161 offset:9216
	ds_read_b128 v[88:91], v161 offset:17408
	ds_read_b128 v[100:103], v161 offset:25600
	ds_read_b64 v[104:105], v82 offset:41984
	ds_read_b128 v[92:95], v161 offset:1024
	ds_read_b128 v[96:99], v161 offset:33792
	v_pk_mul_f32 v[106:107], v[72:73], v[128:129]
	v_pk_mul_f32 v[108:109], v[76:77], v[128:129]
	v_pk_fma_f32 v[106:107], v[74:75], v[130:131], v[106:107]
	v_pk_fma_f32 v[108:109], v[78:79], v[130:131], v[108:109]
	v_add_f32_e32 v110, v106, v107
	v_add_f32_e32 v112, v108, v109
	s_nop 0
	v_add_f32_dpp v110, v110, v110 quad_perm:[1,0,3,2] row_mask:0xf bank_mask:0xf bound_ctrl:1
	v_add_f32_dpp v112, v112, v112 quad_perm:[1,0,3,2] row_mask:0xf bank_mask:0xf bound_ctrl:1
	s_nop 0
	v_add_f32_dpp v110, v110, v110 quad_perm:[2,3,0,1] row_mask:0xf bank_mask:0xf bound_ctrl:1
	v_add_f32_dpp v112, v112, v112 quad_perm:[2,3,0,1] row_mask:0xf bank_mask:0xf bound_ctrl:1
	s_nop 0
	v_add_f32_dpp v110, v110, v110 row_half_mirror row_mask:0xf bank_mask:0xf bound_ctrl:1
	v_add_f32_dpp v112, v112, v112 row_half_mirror row_mask:0xf bank_mask:0xf bound_ctrl:1
	s_nop 0
	v_add_f32_dpp v110, v110, v110 row_ror:8 row_mask:0xf bank_mask:0xf bound_ctrl:1
	v_add_f32_dpp v112, v112, v112 row_ror:8 row_mask:0xf bank_mask:0xf bound_ctrl:1
	v_pk_mul_f32 v[114:115], v[132:133], v[110:111] op_sel_hi:[1,0]
	v_pk_mul_f32 v[116:117], v[132:133], v[112:113] op_sel_hi:[1,0]
	v_pk_mul_f32 v[118:119], v[134:135], v[110:111] op_sel_hi:[1,0]
	v_pk_mul_f32 v[120:121], v[134:135], v[112:113] op_sel_hi:[1,0]
	v_pk_fma_f32 v[114:115], v[194:195], v[198:199], v[114:115] op_sel_hi:[1,0,1]
	v_pk_fma_f32 v[116:117], v[194:195], v[198:199], v[116:117] op_sel:[0,1,0]
	v_pk_fma_f32 v[118:119], v[196:197], v[198:199], v[118:119] op_sel_hi:[1,0,1]
	v_pk_fma_f32 v[120:121], v[196:197], v[198:199], v[120:121] op_sel:[0,1,0]
	v_pk_fma_f32 v[72:73], v[72:73], v[136:137], v[114:115]
	v_pk_fma_f32 v[76:77], v[76:77], v[136:137], v[116:117]
	v_pk_fma_f32 v[74:75], v[74:75], v[138:139], v[118:119]
	v_pk_fma_f32 v[78:79], v[78:79], v[138:139], v[120:121]
	v_pk_mul_f32 v[122:123], v[72:73], v[140:141]
	v_pk_mul_f32 v[124:125], v[76:77], v[140:141]
	v_pk_fma_f32 v[122:123], v[74:75], v[142:143], v[122:123]
	v_pk_fma_f32 v[124:125], v[78:79], v[142:143], v[124:125]
	v_add_f32_e32 v126, v122, v123
	v_add_f32_e32 v127, v124, v125
	ds_write_b64 v187, v[126:127] offset:4096
	s_waitcnt lgkmcnt(8)
	ds_read_b128 v[128:131], v161 offset:9472
	ds_read_b128 v[132:135], v161 offset:17664
	ds_read_b128 v[194:197], v161 offset:25856
	ds_read_b64 v[198:199], v82 offset:42240
	ds_read_b128 v[136:139], v161 offset:1280
	ds_read_b128 v[140:143], v161 offset:34048
	v_pk_mul_f32 v[106:107], v[72:73], v[30:31]
	v_pk_mul_f32 v[108:109], v[76:77], v[30:31]
	v_pk_fma_f32 v[106:107], v[74:75], v[32:33], v[106:107]
	v_pk_fma_f32 v[108:109], v[78:79], v[32:33], v[108:109]
	v_add_f32_e32 v110, v106, v107
	v_add_f32_e32 v112, v108, v109
	s_nop 0
	v_add_f32_dpp v110, v110, v110 quad_perm:[1,0,3,2] row_mask:0xf bank_mask:0xf bound_ctrl:1
	v_add_f32_dpp v112, v112, v112 quad_perm:[1,0,3,2] row_mask:0xf bank_mask:0xf bound_ctrl:1
	s_nop 0
	v_add_f32_dpp v110, v110, v110 quad_perm:[2,3,0,1] row_mask:0xf bank_mask:0xf bound_ctrl:1
	v_add_f32_dpp v112, v112, v112 quad_perm:[2,3,0,1] row_mask:0xf bank_mask:0xf bound_ctrl:1
	s_nop 0
	v_add_f32_dpp v110, v110, v110 row_half_mirror row_mask:0xf bank_mask:0xf bound_ctrl:1
	v_add_f32_dpp v112, v112, v112 row_half_mirror row_mask:0xf bank_mask:0xf bound_ctrl:1
	s_nop 0
	v_add_f32_dpp v110, v110, v110 row_ror:8 row_mask:0xf bank_mask:0xf bound_ctrl:1
	v_add_f32_dpp v112, v112, v112 row_ror:8 row_mask:0xf bank_mask:0xf bound_ctrl:1
	v_pk_mul_f32 v[114:115], v[34:35], v[110:111] op_sel_hi:[1,0]
	v_pk_mul_f32 v[116:117], v[34:35], v[112:113] op_sel_hi:[1,0]
	v_pk_mul_f32 v[118:119], v[36:37], v[110:111] op_sel_hi:[1,0]
	v_pk_mul_f32 v[120:121], v[36:37], v[112:113] op_sel_hi:[1,0]
	v_pk_fma_f32 v[114:115], v[46:47], v[80:81], v[114:115] op_sel_hi:[1,0,1]
	v_pk_fma_f32 v[116:117], v[46:47], v[80:81], v[116:117] op_sel:[0,1,0]
	v_pk_fma_f32 v[118:119], v[48:49], v[80:81], v[118:119] op_sel_hi:[1,0,1]
	v_pk_fma_f32 v[120:121], v[48:49], v[80:81], v[120:121] op_sel:[0,1,0]
	v_pk_fma_f32 v[72:73], v[72:73], v[38:39], v[114:115]
	v_pk_fma_f32 v[76:77], v[76:77], v[38:39], v[116:117]
	v_pk_fma_f32 v[74:75], v[74:75], v[40:41], v[118:119]
	v_pk_fma_f32 v[78:79], v[78:79], v[40:41], v[120:121]
	v_pk_mul_f32 v[122:123], v[72:73], v[42:43]
	v_pk_mul_f32 v[124:125], v[76:77], v[42:43]
	v_pk_fma_f32 v[122:123], v[74:75], v[44:45], v[122:123]
	v_pk_fma_f32 v[124:125], v[78:79], v[44:45], v[124:125]
	v_add_f32_e32 v126, v122, v123
	v_add_f32_e32 v127, v124, v125
	ds_write_b64 v187, v[126:127] offset:6144
	s_waitcnt lgkmcnt(8)
	ds_read_b128 v[30:33], v161 offset:9728
	ds_read_b128 v[34:37], v161 offset:17920
	ds_read_b128 v[46:49], v161 offset:26112
	ds_read_b64 v[80:81], v82 offset:42496
	ds_read_b128 v[38:41], v161 offset:1536
	ds_read_b128 v[42:45], v161 offset:34304
	v_pk_mul_f32 v[106:107], v[72:73], v[84:85]
	v_pk_mul_f32 v[108:109], v[76:77], v[84:85]
	v_pk_fma_f32 v[106:107], v[74:75], v[86:87], v[106:107]
	v_pk_fma_f32 v[108:109], v[78:79], v[86:87], v[108:109]
	v_add_f32_e32 v110, v106, v107
	v_add_f32_e32 v112, v108, v109
	s_nop 0
	v_add_f32_dpp v110, v110, v110 quad_perm:[1,0,3,2] row_mask:0xf bank_mask:0xf bound_ctrl:1
	v_add_f32_dpp v112, v112, v112 quad_perm:[1,0,3,2] row_mask:0xf bank_mask:0xf bound_ctrl:1
	s_nop 0
	v_add_f32_dpp v110, v110, v110 quad_perm:[2,3,0,1] row_mask:0xf bank_mask:0xf bound_ctrl:1
	v_add_f32_dpp v112, v112, v112 quad_perm:[2,3,0,1] row_mask:0xf bank_mask:0xf bound_ctrl:1
	s_nop 0
	v_add_f32_dpp v110, v110, v110 row_half_mirror row_mask:0xf bank_mask:0xf bound_ctrl:1
	v_add_f32_dpp v112, v112, v112 row_half_mirror row_mask:0xf bank_mask:0xf bound_ctrl:1
	s_nop 0
	v_add_f32_dpp v110, v110, v110 row_ror:8 row_mask:0xf bank_mask:0xf bound_ctrl:1
	v_add_f32_dpp v112, v112, v112 row_ror:8 row_mask:0xf bank_mask:0xf bound_ctrl:1
	v_pk_mul_f32 v[114:115], v[88:89], v[110:111] op_sel_hi:[1,0]
	v_pk_mul_f32 v[116:117], v[88:89], v[112:113] op_sel_hi:[1,0]
	v_pk_mul_f32 v[118:119], v[90:91], v[110:111] op_sel_hi:[1,0]
	v_pk_mul_f32 v[120:121], v[90:91], v[112:113] op_sel_hi:[1,0]
	v_pk_fma_f32 v[114:115], v[100:101], v[104:105], v[114:115] op_sel_hi:[1,0,1]
	v_pk_fma_f32 v[116:117], v[100:101], v[104:105], v[116:117] op_sel:[0,1,0]
	v_pk_fma_f32 v[118:119], v[102:103], v[104:105], v[118:119] op_sel_hi:[1,0,1]
	v_pk_fma_f32 v[120:121], v[102:103], v[104:105], v[120:121] op_sel:[0,1,0]
	v_pk_fma_f32 v[72:73], v[72:73], v[92:93], v[114:115]
	v_pk_fma_f32 v[76:77], v[76:77], v[92:93], v[116:117]
	v_pk_fma_f32 v[74:75], v[74:75], v[94:95], v[118:119]
	v_pk_fma_f32 v[78:79], v[78:79], v[94:95], v[120:121]
	v_pk_mul_f32 v[122:123], v[72:73], v[96:97]
	v_pk_mul_f32 v[124:125], v[76:77], v[96:97]
	v_pk_fma_f32 v[122:123], v[74:75], v[98:99], v[122:123]
	v_pk_fma_f32 v[124:125], v[78:79], v[98:99], v[124:125]
	v_add_f32_e32 v126, v122, v123
	v_add_f32_e32 v127, v124, v125
	ds_write_b64 v187, v[126:127] offset:8192
	s_waitcnt lgkmcnt(8)
	ds_read_b128 v[84:87], v161 offset:9984
	ds_read_b128 v[88:91], v161 offset:18176
	ds_read_b128 v[100:103], v161 offset:26368
	ds_read_b64 v[104:105], v82 offset:42752
	ds_read_b128 v[92:95], v161 offset:1792
	ds_read_b128 v[96:99], v161 offset:34560
	v_pk_mul_f32 v[106:107], v[72:73], v[128:129]
	v_pk_mul_f32 v[108:109], v[76:77], v[128:129]
	v_pk_fma_f32 v[106:107], v[74:75], v[130:131], v[106:107]
	v_pk_fma_f32 v[108:109], v[78:79], v[130:131], v[108:109]
	v_add_f32_e32 v110, v106, v107
	v_add_f32_e32 v112, v108, v109
	s_nop 0
	v_add_f32_dpp v110, v110, v110 quad_perm:[1,0,3,2] row_mask:0xf bank_mask:0xf bound_ctrl:1
	v_add_f32_dpp v112, v112, v112 quad_perm:[1,0,3,2] row_mask:0xf bank_mask:0xf bound_ctrl:1
	s_nop 0
	v_add_f32_dpp v110, v110, v110 quad_perm:[2,3,0,1] row_mask:0xf bank_mask:0xf bound_ctrl:1
	v_add_f32_dpp v112, v112, v112 quad_perm:[2,3,0,1] row_mask:0xf bank_mask:0xf bound_ctrl:1
	s_nop 0
	v_add_f32_dpp v110, v110, v110 row_half_mirror row_mask:0xf bank_mask:0xf bound_ctrl:1
	v_add_f32_dpp v112, v112, v112 row_half_mirror row_mask:0xf bank_mask:0xf bound_ctrl:1
	s_nop 0
	v_add_f32_dpp v110, v110, v110 row_ror:8 row_mask:0xf bank_mask:0xf bound_ctrl:1
	v_add_f32_dpp v112, v112, v112 row_ror:8 row_mask:0xf bank_mask:0xf bound_ctrl:1
	v_pk_mul_f32 v[114:115], v[132:133], v[110:111] op_sel_hi:[1,0]
	v_pk_mul_f32 v[116:117], v[132:133], v[112:113] op_sel_hi:[1,0]
	v_pk_mul_f32 v[118:119], v[134:135], v[110:111] op_sel_hi:[1,0]
	v_pk_mul_f32 v[120:121], v[134:135], v[112:113] op_sel_hi:[1,0]
	v_pk_fma_f32 v[114:115], v[194:195], v[198:199], v[114:115] op_sel_hi:[1,0,1]
	v_pk_fma_f32 v[116:117], v[194:195], v[198:199], v[116:117] op_sel:[0,1,0]
	v_pk_fma_f32 v[118:119], v[196:197], v[198:199], v[118:119] op_sel_hi:[1,0,1]
	v_pk_fma_f32 v[120:121], v[196:197], v[198:199], v[120:121] op_sel:[0,1,0]
	v_pk_fma_f32 v[72:73], v[72:73], v[136:137], v[114:115]
	v_pk_fma_f32 v[76:77], v[76:77], v[136:137], v[116:117]
	v_pk_fma_f32 v[74:75], v[74:75], v[138:139], v[118:119]
	v_pk_fma_f32 v[78:79], v[78:79], v[138:139], v[120:121]
	v_pk_mul_f32 v[122:123], v[72:73], v[140:141]
	v_pk_mul_f32 v[124:125], v[76:77], v[140:141]
	v_pk_fma_f32 v[122:123], v[74:75], v[142:143], v[122:123]
	v_pk_fma_f32 v[124:125], v[78:79], v[142:143], v[124:125]
	v_add_f32_e32 v126, v122, v123
	v_add_f32_e32 v127, v124, v125
	ds_write_b64 v187, v[126:127] offset:10240
	s_waitcnt lgkmcnt(8)
	ds_read_b128 v[128:131], v161 offset:10240
	ds_read_b128 v[132:135], v161 offset:18432
	ds_read_b128 v[194:197], v161 offset:26624
	ds_read_b64 v[198:199], v82 offset:43008
	ds_read_b128 v[136:139], v161 offset:2048
	ds_read_b128 v[140:143], v161 offset:34816
	v_pk_mul_f32 v[106:107], v[72:73], v[30:31]
	v_pk_mul_f32 v[108:109], v[76:77], v[30:31]
	v_pk_fma_f32 v[106:107], v[74:75], v[32:33], v[106:107]
	v_pk_fma_f32 v[108:109], v[78:79], v[32:33], v[108:109]
	v_add_f32_e32 v110, v106, v107
	v_add_f32_e32 v112, v108, v109
	s_nop 0
	v_add_f32_dpp v110, v110, v110 quad_perm:[1,0,3,2] row_mask:0xf bank_mask:0xf bound_ctrl:1
	v_add_f32_dpp v112, v112, v112 quad_perm:[1,0,3,2] row_mask:0xf bank_mask:0xf bound_ctrl:1
	s_nop 0
	v_add_f32_dpp v110, v110, v110 quad_perm:[2,3,0,1] row_mask:0xf bank_mask:0xf bound_ctrl:1
	v_add_f32_dpp v112, v112, v112 quad_perm:[2,3,0,1] row_mask:0xf bank_mask:0xf bound_ctrl:1
	s_nop 0
	v_add_f32_dpp v110, v110, v110 row_half_mirror row_mask:0xf bank_mask:0xf bound_ctrl:1
	v_add_f32_dpp v112, v112, v112 row_half_mirror row_mask:0xf bank_mask:0xf bound_ctrl:1
	s_nop 0
	v_add_f32_dpp v110, v110, v110 row_ror:8 row_mask:0xf bank_mask:0xf bound_ctrl:1
	v_add_f32_dpp v112, v112, v112 row_ror:8 row_mask:0xf bank_mask:0xf bound_ctrl:1
	v_pk_mul_f32 v[114:115], v[34:35], v[110:111] op_sel_hi:[1,0]
	v_pk_mul_f32 v[116:117], v[34:35], v[112:113] op_sel_hi:[1,0]
	v_pk_mul_f32 v[118:119], v[36:37], v[110:111] op_sel_hi:[1,0]
	v_pk_mul_f32 v[120:121], v[36:37], v[112:113] op_sel_hi:[1,0]
	v_pk_fma_f32 v[114:115], v[46:47], v[80:81], v[114:115] op_sel_hi:[1,0,1]
	v_pk_fma_f32 v[116:117], v[46:47], v[80:81], v[116:117] op_sel:[0,1,0]
	v_pk_fma_f32 v[118:119], v[48:49], v[80:81], v[118:119] op_sel_hi:[1,0,1]
	v_pk_fma_f32 v[120:121], v[48:49], v[80:81], v[120:121] op_sel:[0,1,0]
	v_pk_fma_f32 v[72:73], v[72:73], v[38:39], v[114:115]
	v_pk_fma_f32 v[76:77], v[76:77], v[38:39], v[116:117]
	v_pk_fma_f32 v[74:75], v[74:75], v[40:41], v[118:119]
	v_pk_fma_f32 v[78:79], v[78:79], v[40:41], v[120:121]
	v_pk_mul_f32 v[122:123], v[72:73], v[42:43]
	v_pk_mul_f32 v[124:125], v[76:77], v[42:43]
	v_pk_fma_f32 v[122:123], v[74:75], v[44:45], v[122:123]
	v_pk_fma_f32 v[124:125], v[78:79], v[44:45], v[124:125]
	v_add_f32_e32 v126, v122, v123
	v_add_f32_e32 v127, v124, v125
	ds_write_b64 v187, v[126:127] offset:12288
	s_waitcnt lgkmcnt(8)
	ds_read_b128 v[30:33], v161 offset:10496
	ds_read_b128 v[34:37], v161 offset:18688
	ds_read_b128 v[46:49], v161 offset:26880
	ds_read_b64 v[80:81], v82 offset:43264
	ds_read_b128 v[38:41], v161 offset:2304
	ds_read_b128 v[42:45], v161 offset:35072
	v_pk_mul_f32 v[106:107], v[72:73], v[84:85]
	v_pk_mul_f32 v[108:109], v[76:77], v[84:85]
	v_pk_fma_f32 v[106:107], v[74:75], v[86:87], v[106:107]
	v_pk_fma_f32 v[108:109], v[78:79], v[86:87], v[108:109]
	v_add_f32_e32 v110, v106, v107
	v_add_f32_e32 v112, v108, v109
	s_nop 0
	v_add_f32_dpp v110, v110, v110 quad_perm:[1,0,3,2] row_mask:0xf bank_mask:0xf bound_ctrl:1
	v_add_f32_dpp v112, v112, v112 quad_perm:[1,0,3,2] row_mask:0xf bank_mask:0xf bound_ctrl:1
	s_nop 0
	v_add_f32_dpp v110, v110, v110 quad_perm:[2,3,0,1] row_mask:0xf bank_mask:0xf bound_ctrl:1
	v_add_f32_dpp v112, v112, v112 quad_perm:[2,3,0,1] row_mask:0xf bank_mask:0xf bound_ctrl:1
	s_nop 0
	v_add_f32_dpp v110, v110, v110 row_half_mirror row_mask:0xf bank_mask:0xf bound_ctrl:1
	v_add_f32_dpp v112, v112, v112 row_half_mirror row_mask:0xf bank_mask:0xf bound_ctrl:1
	s_nop 0
	v_add_f32_dpp v110, v110, v110 row_ror:8 row_mask:0xf bank_mask:0xf bound_ctrl:1
	v_add_f32_dpp v112, v112, v112 row_ror:8 row_mask:0xf bank_mask:0xf bound_ctrl:1
	v_pk_mul_f32 v[114:115], v[88:89], v[110:111] op_sel_hi:[1,0]
	v_pk_mul_f32 v[116:117], v[88:89], v[112:113] op_sel_hi:[1,0]
	v_pk_mul_f32 v[118:119], v[90:91], v[110:111] op_sel_hi:[1,0]
	v_pk_mul_f32 v[120:121], v[90:91], v[112:113] op_sel_hi:[1,0]
	v_pk_fma_f32 v[114:115], v[100:101], v[104:105], v[114:115] op_sel_hi:[1,0,1]
	v_pk_fma_f32 v[116:117], v[100:101], v[104:105], v[116:117] op_sel:[0,1,0]
	v_pk_fma_f32 v[118:119], v[102:103], v[104:105], v[118:119] op_sel_hi:[1,0,1]
	v_pk_fma_f32 v[120:121], v[102:103], v[104:105], v[120:121] op_sel:[0,1,0]
	v_pk_fma_f32 v[72:73], v[72:73], v[92:93], v[114:115]
	v_pk_fma_f32 v[76:77], v[76:77], v[92:93], v[116:117]
	v_pk_fma_f32 v[74:75], v[74:75], v[94:95], v[118:119]
	v_pk_fma_f32 v[78:79], v[78:79], v[94:95], v[120:121]
	v_pk_mul_f32 v[122:123], v[72:73], v[96:97]
	v_pk_mul_f32 v[124:125], v[76:77], v[96:97]
	v_pk_fma_f32 v[122:123], v[74:75], v[98:99], v[122:123]
	v_pk_fma_f32 v[124:125], v[78:79], v[98:99], v[124:125]
	v_add_f32_e32 v126, v122, v123
	v_add_f32_e32 v127, v124, v125
	ds_write_b64 v187, v[126:127] offset:14336
	s_waitcnt lgkmcnt(8)
	ds_read_b128 v[84:87], v161 offset:10752
	ds_read_b128 v[88:91], v161 offset:18944
	ds_read_b128 v[100:103], v161 offset:27136
	ds_read_b64 v[104:105], v82 offset:43520
	ds_read_b128 v[92:95], v161 offset:2560
	ds_read_b128 v[96:99], v161 offset:35328
	v_pk_mul_f32 v[106:107], v[72:73], v[128:129]
	v_pk_mul_f32 v[108:109], v[76:77], v[128:129]
	v_pk_fma_f32 v[106:107], v[74:75], v[130:131], v[106:107]
	v_pk_fma_f32 v[108:109], v[78:79], v[130:131], v[108:109]
	v_add_f32_e32 v110, v106, v107
	v_add_f32_e32 v112, v108, v109
	s_nop 0
	v_add_f32_dpp v110, v110, v110 quad_perm:[1,0,3,2] row_mask:0xf bank_mask:0xf bound_ctrl:1
	v_add_f32_dpp v112, v112, v112 quad_perm:[1,0,3,2] row_mask:0xf bank_mask:0xf bound_ctrl:1
	s_nop 0
	v_add_f32_dpp v110, v110, v110 quad_perm:[2,3,0,1] row_mask:0xf bank_mask:0xf bound_ctrl:1
	v_add_f32_dpp v112, v112, v112 quad_perm:[2,3,0,1] row_mask:0xf bank_mask:0xf bound_ctrl:1
	s_nop 0
	v_add_f32_dpp v110, v110, v110 row_half_mirror row_mask:0xf bank_mask:0xf bound_ctrl:1
	v_add_f32_dpp v112, v112, v112 row_half_mirror row_mask:0xf bank_mask:0xf bound_ctrl:1
	s_nop 0
	v_add_f32_dpp v110, v110, v110 row_ror:8 row_mask:0xf bank_mask:0xf bound_ctrl:1
	v_add_f32_dpp v112, v112, v112 row_ror:8 row_mask:0xf bank_mask:0xf bound_ctrl:1
	v_pk_mul_f32 v[114:115], v[132:133], v[110:111] op_sel_hi:[1,0]
	v_pk_mul_f32 v[116:117], v[132:133], v[112:113] op_sel_hi:[1,0]
	v_pk_mul_f32 v[118:119], v[134:135], v[110:111] op_sel_hi:[1,0]
	v_pk_mul_f32 v[120:121], v[134:135], v[112:113] op_sel_hi:[1,0]
	v_pk_fma_f32 v[114:115], v[194:195], v[198:199], v[114:115] op_sel_hi:[1,0,1]
	v_pk_fma_f32 v[116:117], v[194:195], v[198:199], v[116:117] op_sel:[0,1,0]
	v_pk_fma_f32 v[118:119], v[196:197], v[198:199], v[118:119] op_sel_hi:[1,0,1]
	v_pk_fma_f32 v[120:121], v[196:197], v[198:199], v[120:121] op_sel:[0,1,0]
	v_pk_fma_f32 v[72:73], v[72:73], v[136:137], v[114:115]
	v_pk_fma_f32 v[76:77], v[76:77], v[136:137], v[116:117]
	v_pk_fma_f32 v[74:75], v[74:75], v[138:139], v[118:119]
	v_pk_fma_f32 v[78:79], v[78:79], v[138:139], v[120:121]
	v_pk_mul_f32 v[122:123], v[72:73], v[140:141]
	v_pk_mul_f32 v[124:125], v[76:77], v[140:141]
	v_pk_fma_f32 v[122:123], v[74:75], v[142:143], v[122:123]
	v_pk_fma_f32 v[124:125], v[78:79], v[142:143], v[124:125]
	v_add_f32_e32 v126, v122, v123
	v_add_f32_e32 v127, v124, v125
	ds_write_b64 v187, v[126:127] offset:16384
	s_waitcnt lgkmcnt(8)
	ds_read_b128 v[128:131], v161 offset:11008
	ds_read_b128 v[132:135], v161 offset:19200
	ds_read_b128 v[194:197], v161 offset:27392
	ds_read_b64 v[198:199], v82 offset:43776
	ds_read_b128 v[136:139], v161 offset:2816
	ds_read_b128 v[140:143], v161 offset:35584
	v_pk_mul_f32 v[106:107], v[72:73], v[30:31]
	v_pk_mul_f32 v[108:109], v[76:77], v[30:31]
	v_pk_fma_f32 v[106:107], v[74:75], v[32:33], v[106:107]
	v_pk_fma_f32 v[108:109], v[78:79], v[32:33], v[108:109]
	v_add_f32_e32 v110, v106, v107
	v_add_f32_e32 v112, v108, v109
	s_nop 0
	v_add_f32_dpp v110, v110, v110 quad_perm:[1,0,3,2] row_mask:0xf bank_mask:0xf bound_ctrl:1
	v_add_f32_dpp v112, v112, v112 quad_perm:[1,0,3,2] row_mask:0xf bank_mask:0xf bound_ctrl:1
	s_nop 0
	v_add_f32_dpp v110, v110, v110 quad_perm:[2,3,0,1] row_mask:0xf bank_mask:0xf bound_ctrl:1
	v_add_f32_dpp v112, v112, v112 quad_perm:[2,3,0,1] row_mask:0xf bank_mask:0xf bound_ctrl:1
	s_nop 0
	v_add_f32_dpp v110, v110, v110 row_half_mirror row_mask:0xf bank_mask:0xf bound_ctrl:1
	v_add_f32_dpp v112, v112, v112 row_half_mirror row_mask:0xf bank_mask:0xf bound_ctrl:1
	s_nop 0
	v_add_f32_dpp v110, v110, v110 row_ror:8 row_mask:0xf bank_mask:0xf bound_ctrl:1
	v_add_f32_dpp v112, v112, v112 row_ror:8 row_mask:0xf bank_mask:0xf bound_ctrl:1
	v_pk_mul_f32 v[114:115], v[34:35], v[110:111] op_sel_hi:[1,0]
	v_pk_mul_f32 v[116:117], v[34:35], v[112:113] op_sel_hi:[1,0]
	v_pk_mul_f32 v[118:119], v[36:37], v[110:111] op_sel_hi:[1,0]
	v_pk_mul_f32 v[120:121], v[36:37], v[112:113] op_sel_hi:[1,0]
	v_pk_fma_f32 v[114:115], v[46:47], v[80:81], v[114:115] op_sel_hi:[1,0,1]
	v_pk_fma_f32 v[116:117], v[46:47], v[80:81], v[116:117] op_sel:[0,1,0]
	v_pk_fma_f32 v[118:119], v[48:49], v[80:81], v[118:119] op_sel_hi:[1,0,1]
	v_pk_fma_f32 v[120:121], v[48:49], v[80:81], v[120:121] op_sel:[0,1,0]
	v_pk_fma_f32 v[72:73], v[72:73], v[38:39], v[114:115]
	v_pk_fma_f32 v[76:77], v[76:77], v[38:39], v[116:117]
	v_pk_fma_f32 v[74:75], v[74:75], v[40:41], v[118:119]
	v_pk_fma_f32 v[78:79], v[78:79], v[40:41], v[120:121]
	v_pk_mul_f32 v[122:123], v[72:73], v[42:43]
	v_pk_mul_f32 v[124:125], v[76:77], v[42:43]
	v_pk_fma_f32 v[122:123], v[74:75], v[44:45], v[122:123]
	v_pk_fma_f32 v[124:125], v[78:79], v[44:45], v[124:125]
	v_add_f32_e32 v126, v122, v123
	v_add_f32_e32 v127, v124, v125
	ds_write_b64 v187, v[126:127] offset:18432
	s_waitcnt lgkmcnt(8)
	ds_read_b128 v[30:33], v161 offset:11264
	ds_read_b128 v[34:37], v161 offset:19456
	ds_read_b128 v[46:49], v161 offset:27648
	ds_read_b64 v[80:81], v82 offset:44032
	ds_read_b128 v[38:41], v161 offset:3072
	ds_read_b128 v[42:45], v161 offset:35840
	v_pk_mul_f32 v[106:107], v[72:73], v[84:85]
	v_pk_mul_f32 v[108:109], v[76:77], v[84:85]
	v_pk_fma_f32 v[106:107], v[74:75], v[86:87], v[106:107]
	v_pk_fma_f32 v[108:109], v[78:79], v[86:87], v[108:109]
	v_add_f32_e32 v110, v106, v107
	v_add_f32_e32 v112, v108, v109
	s_nop 0
	v_add_f32_dpp v110, v110, v110 quad_perm:[1,0,3,2] row_mask:0xf bank_mask:0xf bound_ctrl:1
	v_add_f32_dpp v112, v112, v112 quad_perm:[1,0,3,2] row_mask:0xf bank_mask:0xf bound_ctrl:1
	s_nop 0
	v_add_f32_dpp v110, v110, v110 quad_perm:[2,3,0,1] row_mask:0xf bank_mask:0xf bound_ctrl:1
	v_add_f32_dpp v112, v112, v112 quad_perm:[2,3,0,1] row_mask:0xf bank_mask:0xf bound_ctrl:1
	s_nop 0
	v_add_f32_dpp v110, v110, v110 row_half_mirror row_mask:0xf bank_mask:0xf bound_ctrl:1
	v_add_f32_dpp v112, v112, v112 row_half_mirror row_mask:0xf bank_mask:0xf bound_ctrl:1
	s_nop 0
	v_add_f32_dpp v110, v110, v110 row_ror:8 row_mask:0xf bank_mask:0xf bound_ctrl:1
	v_add_f32_dpp v112, v112, v112 row_ror:8 row_mask:0xf bank_mask:0xf bound_ctrl:1
	v_pk_mul_f32 v[114:115], v[88:89], v[110:111] op_sel_hi:[1,0]
	v_pk_mul_f32 v[116:117], v[88:89], v[112:113] op_sel_hi:[1,0]
	v_pk_mul_f32 v[118:119], v[90:91], v[110:111] op_sel_hi:[1,0]
	v_pk_mul_f32 v[120:121], v[90:91], v[112:113] op_sel_hi:[1,0]
	v_pk_fma_f32 v[114:115], v[100:101], v[104:105], v[114:115] op_sel_hi:[1,0,1]
	v_pk_fma_f32 v[116:117], v[100:101], v[104:105], v[116:117] op_sel:[0,1,0]
	v_pk_fma_f32 v[118:119], v[102:103], v[104:105], v[118:119] op_sel_hi:[1,0,1]
	v_pk_fma_f32 v[120:121], v[102:103], v[104:105], v[120:121] op_sel:[0,1,0]
	v_pk_fma_f32 v[72:73], v[72:73], v[92:93], v[114:115]
	v_pk_fma_f32 v[76:77], v[76:77], v[92:93], v[116:117]
	v_pk_fma_f32 v[74:75], v[74:75], v[94:95], v[118:119]
	v_pk_fma_f32 v[78:79], v[78:79], v[94:95], v[120:121]
	v_pk_mul_f32 v[122:123], v[72:73], v[96:97]
	v_pk_mul_f32 v[124:125], v[76:77], v[96:97]
	v_pk_fma_f32 v[122:123], v[74:75], v[98:99], v[122:123]
	v_pk_fma_f32 v[124:125], v[78:79], v[98:99], v[124:125]
	v_add_f32_e32 v126, v122, v123
	v_add_f32_e32 v127, v124, v125
	ds_write_b64 v187, v[126:127] offset:20480
	s_waitcnt lgkmcnt(8)
	ds_read_b128 v[84:87], v161 offset:11520
	ds_read_b128 v[88:91], v161 offset:19712
	ds_read_b128 v[100:103], v161 offset:27904
	ds_read_b64 v[104:105], v82 offset:44288
	ds_read_b128 v[92:95], v161 offset:3328
	ds_read_b128 v[96:99], v161 offset:36096
	v_pk_mul_f32 v[106:107], v[72:73], v[128:129]
	v_pk_mul_f32 v[108:109], v[76:77], v[128:129]
	v_pk_fma_f32 v[106:107], v[74:75], v[130:131], v[106:107]
	v_pk_fma_f32 v[108:109], v[78:79], v[130:131], v[108:109]
	v_add_f32_e32 v110, v106, v107
	v_add_f32_e32 v112, v108, v109
	s_nop 0
	v_add_f32_dpp v110, v110, v110 quad_perm:[1,0,3,2] row_mask:0xf bank_mask:0xf bound_ctrl:1
	v_add_f32_dpp v112, v112, v112 quad_perm:[1,0,3,2] row_mask:0xf bank_mask:0xf bound_ctrl:1
	s_nop 0
	v_add_f32_dpp v110, v110, v110 quad_perm:[2,3,0,1] row_mask:0xf bank_mask:0xf bound_ctrl:1
	v_add_f32_dpp v112, v112, v112 quad_perm:[2,3,0,1] row_mask:0xf bank_mask:0xf bound_ctrl:1
	s_nop 0
	v_add_f32_dpp v110, v110, v110 row_half_mirror row_mask:0xf bank_mask:0xf bound_ctrl:1
	v_add_f32_dpp v112, v112, v112 row_half_mirror row_mask:0xf bank_mask:0xf bound_ctrl:1
	s_nop 0
	v_add_f32_dpp v110, v110, v110 row_ror:8 row_mask:0xf bank_mask:0xf bound_ctrl:1
	v_add_f32_dpp v112, v112, v112 row_ror:8 row_mask:0xf bank_mask:0xf bound_ctrl:1
	v_pk_mul_f32 v[114:115], v[132:133], v[110:111] op_sel_hi:[1,0]
	v_pk_mul_f32 v[116:117], v[132:133], v[112:113] op_sel_hi:[1,0]
	v_pk_mul_f32 v[118:119], v[134:135], v[110:111] op_sel_hi:[1,0]
	v_pk_mul_f32 v[120:121], v[134:135], v[112:113] op_sel_hi:[1,0]
	v_pk_fma_f32 v[114:115], v[194:195], v[198:199], v[114:115] op_sel_hi:[1,0,1]
	v_pk_fma_f32 v[116:117], v[194:195], v[198:199], v[116:117] op_sel:[0,1,0]
	v_pk_fma_f32 v[118:119], v[196:197], v[198:199], v[118:119] op_sel_hi:[1,0,1]
	v_pk_fma_f32 v[120:121], v[196:197], v[198:199], v[120:121] op_sel:[0,1,0]
	v_pk_fma_f32 v[72:73], v[72:73], v[136:137], v[114:115]
	v_pk_fma_f32 v[76:77], v[76:77], v[136:137], v[116:117]
	v_pk_fma_f32 v[74:75], v[74:75], v[138:139], v[118:119]
	v_pk_fma_f32 v[78:79], v[78:79], v[138:139], v[120:121]
	v_pk_mul_f32 v[122:123], v[72:73], v[140:141]
	v_pk_mul_f32 v[124:125], v[76:77], v[140:141]
	v_pk_fma_f32 v[122:123], v[74:75], v[142:143], v[122:123]
	v_pk_fma_f32 v[124:125], v[78:79], v[142:143], v[124:125]
	v_add_f32_e32 v126, v122, v123
	v_add_f32_e32 v127, v124, v125
	ds_write_b64 v187, v[126:127] offset:22528
	s_waitcnt lgkmcnt(8)
	ds_read_b128 v[128:131], v161 offset:11776
	ds_read_b128 v[132:135], v161 offset:19968
	ds_read_b128 v[194:197], v161 offset:28160
	ds_read_b64 v[198:199], v82 offset:44544
	ds_read_b128 v[136:139], v161 offset:3584
	ds_read_b128 v[140:143], v161 offset:36352
	v_pk_mul_f32 v[106:107], v[72:73], v[30:31]
	v_pk_mul_f32 v[108:109], v[76:77], v[30:31]
	v_pk_fma_f32 v[106:107], v[74:75], v[32:33], v[106:107]
	v_pk_fma_f32 v[108:109], v[78:79], v[32:33], v[108:109]
	v_add_f32_e32 v110, v106, v107
	v_add_f32_e32 v112, v108, v109
	s_nop 0
	v_add_f32_dpp v110, v110, v110 quad_perm:[1,0,3,2] row_mask:0xf bank_mask:0xf bound_ctrl:1
	v_add_f32_dpp v112, v112, v112 quad_perm:[1,0,3,2] row_mask:0xf bank_mask:0xf bound_ctrl:1
	s_nop 0
	v_add_f32_dpp v110, v110, v110 quad_perm:[2,3,0,1] row_mask:0xf bank_mask:0xf bound_ctrl:1
	v_add_f32_dpp v112, v112, v112 quad_perm:[2,3,0,1] row_mask:0xf bank_mask:0xf bound_ctrl:1
	s_nop 0
	v_add_f32_dpp v110, v110, v110 row_half_mirror row_mask:0xf bank_mask:0xf bound_ctrl:1
	v_add_f32_dpp v112, v112, v112 row_half_mirror row_mask:0xf bank_mask:0xf bound_ctrl:1
	s_nop 0
	v_add_f32_dpp v110, v110, v110 row_ror:8 row_mask:0xf bank_mask:0xf bound_ctrl:1
	v_add_f32_dpp v112, v112, v112 row_ror:8 row_mask:0xf bank_mask:0xf bound_ctrl:1
	v_pk_mul_f32 v[114:115], v[34:35], v[110:111] op_sel_hi:[1,0]
	v_pk_mul_f32 v[116:117], v[34:35], v[112:113] op_sel_hi:[1,0]
	v_pk_mul_f32 v[118:119], v[36:37], v[110:111] op_sel_hi:[1,0]
	v_pk_mul_f32 v[120:121], v[36:37], v[112:113] op_sel_hi:[1,0]
	v_pk_fma_f32 v[114:115], v[46:47], v[80:81], v[114:115] op_sel_hi:[1,0,1]
	v_pk_fma_f32 v[116:117], v[46:47], v[80:81], v[116:117] op_sel:[0,1,0]
	v_pk_fma_f32 v[118:119], v[48:49], v[80:81], v[118:119] op_sel_hi:[1,0,1]
	v_pk_fma_f32 v[120:121], v[48:49], v[80:81], v[120:121] op_sel:[0,1,0]
	v_pk_fma_f32 v[72:73], v[72:73], v[38:39], v[114:115]
	v_pk_fma_f32 v[76:77], v[76:77], v[38:39], v[116:117]
	v_pk_fma_f32 v[74:75], v[74:75], v[40:41], v[118:119]
	v_pk_fma_f32 v[78:79], v[78:79], v[40:41], v[120:121]
	v_pk_mul_f32 v[122:123], v[72:73], v[42:43]
	v_pk_mul_f32 v[124:125], v[76:77], v[42:43]
	v_pk_fma_f32 v[122:123], v[74:75], v[44:45], v[122:123]
	v_pk_fma_f32 v[124:125], v[78:79], v[44:45], v[124:125]
	v_add_f32_e32 v126, v122, v123
	v_add_f32_e32 v127, v124, v125
	ds_write_b64 v187, v[126:127] offset:24576
	s_waitcnt lgkmcnt(8)
	ds_read_b128 v[30:33], v161 offset:12032
	ds_read_b128 v[34:37], v161 offset:20224
	ds_read_b128 v[46:49], v161 offset:28416
	ds_read_b64 v[80:81], v82 offset:44800
	ds_read_b128 v[38:41], v161 offset:3840
	ds_read_b128 v[42:45], v161 offset:36608
	v_pk_mul_f32 v[106:107], v[72:73], v[84:85]
	v_pk_mul_f32 v[108:109], v[76:77], v[84:85]
	v_pk_fma_f32 v[106:107], v[74:75], v[86:87], v[106:107]
	v_pk_fma_f32 v[108:109], v[78:79], v[86:87], v[108:109]
	v_add_f32_e32 v110, v106, v107
	v_add_f32_e32 v112, v108, v109
	s_nop 0
	v_add_f32_dpp v110, v110, v110 quad_perm:[1,0,3,2] row_mask:0xf bank_mask:0xf bound_ctrl:1
	v_add_f32_dpp v112, v112, v112 quad_perm:[1,0,3,2] row_mask:0xf bank_mask:0xf bound_ctrl:1
	s_nop 0
	v_add_f32_dpp v110, v110, v110 quad_perm:[2,3,0,1] row_mask:0xf bank_mask:0xf bound_ctrl:1
	v_add_f32_dpp v112, v112, v112 quad_perm:[2,3,0,1] row_mask:0xf bank_mask:0xf bound_ctrl:1
	s_nop 0
	v_add_f32_dpp v110, v110, v110 row_half_mirror row_mask:0xf bank_mask:0xf bound_ctrl:1
	v_add_f32_dpp v112, v112, v112 row_half_mirror row_mask:0xf bank_mask:0xf bound_ctrl:1
	s_nop 0
	v_add_f32_dpp v110, v110, v110 row_ror:8 row_mask:0xf bank_mask:0xf bound_ctrl:1
	v_add_f32_dpp v112, v112, v112 row_ror:8 row_mask:0xf bank_mask:0xf bound_ctrl:1
	v_pk_mul_f32 v[114:115], v[88:89], v[110:111] op_sel_hi:[1,0]
	v_pk_mul_f32 v[116:117], v[88:89], v[112:113] op_sel_hi:[1,0]
	v_pk_mul_f32 v[118:119], v[90:91], v[110:111] op_sel_hi:[1,0]
	v_pk_mul_f32 v[120:121], v[90:91], v[112:113] op_sel_hi:[1,0]
	v_pk_fma_f32 v[114:115], v[100:101], v[104:105], v[114:115] op_sel_hi:[1,0,1]
	v_pk_fma_f32 v[116:117], v[100:101], v[104:105], v[116:117] op_sel:[0,1,0]
	v_pk_fma_f32 v[118:119], v[102:103], v[104:105], v[118:119] op_sel_hi:[1,0,1]
	v_pk_fma_f32 v[120:121], v[102:103], v[104:105], v[120:121] op_sel:[0,1,0]
	v_pk_fma_f32 v[72:73], v[72:73], v[92:93], v[114:115]
	v_pk_fma_f32 v[76:77], v[76:77], v[92:93], v[116:117]
	v_pk_fma_f32 v[74:75], v[74:75], v[94:95], v[118:119]
	v_pk_fma_f32 v[78:79], v[78:79], v[94:95], v[120:121]
	v_pk_mul_f32 v[122:123], v[72:73], v[96:97]
	v_pk_mul_f32 v[124:125], v[76:77], v[96:97]
	v_pk_fma_f32 v[122:123], v[74:75], v[98:99], v[122:123]
	v_pk_fma_f32 v[124:125], v[78:79], v[98:99], v[124:125]
	v_add_f32_e32 v126, v122, v123
	v_add_f32_e32 v127, v124, v125
	ds_write_b64 v187, v[126:127] offset:26624
	s_waitcnt lgkmcnt(8)
	ds_read_b128 v[84:87], v161 offset:12288
	ds_read_b128 v[88:91], v161 offset:20480
	ds_read_b128 v[100:103], v161 offset:28672
	ds_read_b64 v[104:105], v82 offset:45056
	ds_read_b128 v[92:95], v161 offset:4096
	ds_read_b128 v[96:99], v161 offset:36864
	v_pk_mul_f32 v[106:107], v[72:73], v[128:129]
	v_pk_mul_f32 v[108:109], v[76:77], v[128:129]
	v_pk_fma_f32 v[106:107], v[74:75], v[130:131], v[106:107]
	v_pk_fma_f32 v[108:109], v[78:79], v[130:131], v[108:109]
	v_add_f32_e32 v110, v106, v107
	v_add_f32_e32 v112, v108, v109
	s_nop 0
	v_add_f32_dpp v110, v110, v110 quad_perm:[1,0,3,2] row_mask:0xf bank_mask:0xf bound_ctrl:1
	v_add_f32_dpp v112, v112, v112 quad_perm:[1,0,3,2] row_mask:0xf bank_mask:0xf bound_ctrl:1
	s_nop 0
	v_add_f32_dpp v110, v110, v110 quad_perm:[2,3,0,1] row_mask:0xf bank_mask:0xf bound_ctrl:1
	v_add_f32_dpp v112, v112, v112 quad_perm:[2,3,0,1] row_mask:0xf bank_mask:0xf bound_ctrl:1
	s_nop 0
	v_add_f32_dpp v110, v110, v110 row_half_mirror row_mask:0xf bank_mask:0xf bound_ctrl:1
	v_add_f32_dpp v112, v112, v112 row_half_mirror row_mask:0xf bank_mask:0xf bound_ctrl:1
	s_nop 0
	v_add_f32_dpp v110, v110, v110 row_ror:8 row_mask:0xf bank_mask:0xf bound_ctrl:1
	v_add_f32_dpp v112, v112, v112 row_ror:8 row_mask:0xf bank_mask:0xf bound_ctrl:1
	v_pk_mul_f32 v[114:115], v[132:133], v[110:111] op_sel_hi:[1,0]
	v_pk_mul_f32 v[116:117], v[132:133], v[112:113] op_sel_hi:[1,0]
	v_pk_mul_f32 v[118:119], v[134:135], v[110:111] op_sel_hi:[1,0]
	v_pk_mul_f32 v[120:121], v[134:135], v[112:113] op_sel_hi:[1,0]
	v_pk_fma_f32 v[114:115], v[194:195], v[198:199], v[114:115] op_sel_hi:[1,0,1]
	v_pk_fma_f32 v[116:117], v[194:195], v[198:199], v[116:117] op_sel:[0,1,0]
	v_pk_fma_f32 v[118:119], v[196:197], v[198:199], v[118:119] op_sel_hi:[1,0,1]
	v_pk_fma_f32 v[120:121], v[196:197], v[198:199], v[120:121] op_sel:[0,1,0]
	v_pk_fma_f32 v[72:73], v[72:73], v[136:137], v[114:115]
	v_pk_fma_f32 v[76:77], v[76:77], v[136:137], v[116:117]
	v_pk_fma_f32 v[74:75], v[74:75], v[138:139], v[118:119]
	v_pk_fma_f32 v[78:79], v[78:79], v[138:139], v[120:121]
	v_pk_mul_f32 v[122:123], v[72:73], v[140:141]
	v_pk_mul_f32 v[124:125], v[76:77], v[140:141]
	v_pk_fma_f32 v[122:123], v[74:75], v[142:143], v[122:123]
	v_pk_fma_f32 v[124:125], v[78:79], v[142:143], v[124:125]
	v_add_f32_e32 v126, v122, v123
	v_add_f32_e32 v127, v124, v125
	ds_write_b64 v187, v[126:127] offset:28672
	s_waitcnt lgkmcnt(8)
	ds_read_b128 v[128:131], v161 offset:12544
	ds_read_b128 v[132:135], v161 offset:20736
	ds_read_b128 v[194:197], v161 offset:28928
	ds_read_b64 v[198:199], v82 offset:45312
	ds_read_b128 v[136:139], v161 offset:4352
	ds_read_b128 v[140:143], v161 offset:37120
	v_pk_mul_f32 v[106:107], v[72:73], v[30:31]
	v_pk_mul_f32 v[108:109], v[76:77], v[30:31]
	v_pk_fma_f32 v[106:107], v[74:75], v[32:33], v[106:107]
	v_pk_fma_f32 v[108:109], v[78:79], v[32:33], v[108:109]
	v_add_f32_e32 v110, v106, v107
	v_add_f32_e32 v112, v108, v109
	s_nop 0
	v_add_f32_dpp v110, v110, v110 quad_perm:[1,0,3,2] row_mask:0xf bank_mask:0xf bound_ctrl:1
	v_add_f32_dpp v112, v112, v112 quad_perm:[1,0,3,2] row_mask:0xf bank_mask:0xf bound_ctrl:1
	s_nop 0
	v_add_f32_dpp v110, v110, v110 quad_perm:[2,3,0,1] row_mask:0xf bank_mask:0xf bound_ctrl:1
	v_add_f32_dpp v112, v112, v112 quad_perm:[2,3,0,1] row_mask:0xf bank_mask:0xf bound_ctrl:1
	s_nop 0
	v_add_f32_dpp v110, v110, v110 row_half_mirror row_mask:0xf bank_mask:0xf bound_ctrl:1
	v_add_f32_dpp v112, v112, v112 row_half_mirror row_mask:0xf bank_mask:0xf bound_ctrl:1
	s_nop 0
	v_add_f32_dpp v110, v110, v110 row_ror:8 row_mask:0xf bank_mask:0xf bound_ctrl:1
	v_add_f32_dpp v112, v112, v112 row_ror:8 row_mask:0xf bank_mask:0xf bound_ctrl:1
	v_pk_mul_f32 v[114:115], v[34:35], v[110:111] op_sel_hi:[1,0]
	v_pk_mul_f32 v[116:117], v[34:35], v[112:113] op_sel_hi:[1,0]
	v_pk_mul_f32 v[118:119], v[36:37], v[110:111] op_sel_hi:[1,0]
	v_pk_mul_f32 v[120:121], v[36:37], v[112:113] op_sel_hi:[1,0]
	v_pk_fma_f32 v[114:115], v[46:47], v[80:81], v[114:115] op_sel_hi:[1,0,1]
	v_pk_fma_f32 v[116:117], v[46:47], v[80:81], v[116:117] op_sel:[0,1,0]
	v_pk_fma_f32 v[118:119], v[48:49], v[80:81], v[118:119] op_sel_hi:[1,0,1]
	v_pk_fma_f32 v[120:121], v[48:49], v[80:81], v[120:121] op_sel:[0,1,0]
	v_pk_fma_f32 v[72:73], v[72:73], v[38:39], v[114:115]
	v_pk_fma_f32 v[76:77], v[76:77], v[38:39], v[116:117]
	v_pk_fma_f32 v[74:75], v[74:75], v[40:41], v[118:119]
	v_pk_fma_f32 v[78:79], v[78:79], v[40:41], v[120:121]
	v_pk_mul_f32 v[122:123], v[72:73], v[42:43]
	v_pk_mul_f32 v[124:125], v[76:77], v[42:43]
	v_pk_fma_f32 v[122:123], v[74:75], v[44:45], v[122:123]
	v_pk_fma_f32 v[124:125], v[78:79], v[44:45], v[124:125]
	v_add_f32_e32 v126, v122, v123
	v_add_f32_e32 v127, v124, v125
	ds_write_b64 v187, v[126:127] offset:30720
	s_waitcnt lgkmcnt(8)
	ds_read_b128 v[30:33], v161 offset:12800
	ds_read_b128 v[34:37], v161 offset:20992
	ds_read_b128 v[46:49], v161 offset:29184
	ds_read_b64 v[80:81], v82 offset:45568
	ds_read_b128 v[38:41], v161 offset:4608
	ds_read_b128 v[42:45], v161 offset:37376
	v_pk_mul_f32 v[106:107], v[72:73], v[84:85]
	v_pk_mul_f32 v[108:109], v[76:77], v[84:85]
	v_pk_fma_f32 v[106:107], v[74:75], v[86:87], v[106:107]
	v_pk_fma_f32 v[108:109], v[78:79], v[86:87], v[108:109]
	v_add_f32_e32 v110, v106, v107
	v_add_f32_e32 v112, v108, v109
	s_nop 0
	v_add_f32_dpp v110, v110, v110 quad_perm:[1,0,3,2] row_mask:0xf bank_mask:0xf bound_ctrl:1
	v_add_f32_dpp v112, v112, v112 quad_perm:[1,0,3,2] row_mask:0xf bank_mask:0xf bound_ctrl:1
	s_nop 0
	v_add_f32_dpp v110, v110, v110 quad_perm:[2,3,0,1] row_mask:0xf bank_mask:0xf bound_ctrl:1
	v_add_f32_dpp v112, v112, v112 quad_perm:[2,3,0,1] row_mask:0xf bank_mask:0xf bound_ctrl:1
	s_nop 0
	v_add_f32_dpp v110, v110, v110 row_half_mirror row_mask:0xf bank_mask:0xf bound_ctrl:1
	v_add_f32_dpp v112, v112, v112 row_half_mirror row_mask:0xf bank_mask:0xf bound_ctrl:1
	s_nop 0
	v_add_f32_dpp v110, v110, v110 row_ror:8 row_mask:0xf bank_mask:0xf bound_ctrl:1
	v_add_f32_dpp v112, v112, v112 row_ror:8 row_mask:0xf bank_mask:0xf bound_ctrl:1
	v_pk_mul_f32 v[114:115], v[88:89], v[110:111] op_sel_hi:[1,0]
	v_pk_mul_f32 v[116:117], v[88:89], v[112:113] op_sel_hi:[1,0]
	v_pk_mul_f32 v[118:119], v[90:91], v[110:111] op_sel_hi:[1,0]
	v_pk_mul_f32 v[120:121], v[90:91], v[112:113] op_sel_hi:[1,0]
	v_pk_fma_f32 v[114:115], v[100:101], v[104:105], v[114:115] op_sel_hi:[1,0,1]
	v_pk_fma_f32 v[116:117], v[100:101], v[104:105], v[116:117] op_sel:[0,1,0]
	v_pk_fma_f32 v[118:119], v[102:103], v[104:105], v[118:119] op_sel_hi:[1,0,1]
	v_pk_fma_f32 v[120:121], v[102:103], v[104:105], v[120:121] op_sel:[0,1,0]
	v_pk_fma_f32 v[72:73], v[72:73], v[92:93], v[114:115]
	v_pk_fma_f32 v[76:77], v[76:77], v[92:93], v[116:117]
	v_pk_fma_f32 v[74:75], v[74:75], v[94:95], v[118:119]
	v_pk_fma_f32 v[78:79], v[78:79], v[94:95], v[120:121]
	v_pk_mul_f32 v[122:123], v[72:73], v[96:97]
	v_pk_mul_f32 v[124:125], v[76:77], v[96:97]
	v_pk_fma_f32 v[122:123], v[74:75], v[98:99], v[122:123]
	v_pk_fma_f32 v[124:125], v[78:79], v[98:99], v[124:125]
	v_add_f32_e32 v126, v122, v123
	v_add_f32_e32 v127, v124, v125
	ds_write_b64 v187, v[126:127] offset:32768
	s_waitcnt lgkmcnt(8)
	ds_read_b128 v[84:87], v161 offset:13056
	ds_read_b128 v[88:91], v161 offset:21248
	ds_read_b128 v[100:103], v161 offset:29440
	ds_read_b64 v[104:105], v82 offset:45824
	ds_read_b128 v[92:95], v161 offset:4864
	ds_read_b128 v[96:99], v161 offset:37632
	v_pk_mul_f32 v[106:107], v[72:73], v[128:129]
	v_pk_mul_f32 v[108:109], v[76:77], v[128:129]
	v_pk_fma_f32 v[106:107], v[74:75], v[130:131], v[106:107]
	v_pk_fma_f32 v[108:109], v[78:79], v[130:131], v[108:109]
	v_add_f32_e32 v110, v106, v107
	v_add_f32_e32 v112, v108, v109
	s_nop 0
	v_add_f32_dpp v110, v110, v110 quad_perm:[1,0,3,2] row_mask:0xf bank_mask:0xf bound_ctrl:1
	v_add_f32_dpp v112, v112, v112 quad_perm:[1,0,3,2] row_mask:0xf bank_mask:0xf bound_ctrl:1
	s_nop 0
	v_add_f32_dpp v110, v110, v110 quad_perm:[2,3,0,1] row_mask:0xf bank_mask:0xf bound_ctrl:1
	v_add_f32_dpp v112, v112, v112 quad_perm:[2,3,0,1] row_mask:0xf bank_mask:0xf bound_ctrl:1
	s_nop 0
	v_add_f32_dpp v110, v110, v110 row_half_mirror row_mask:0xf bank_mask:0xf bound_ctrl:1
	v_add_f32_dpp v112, v112, v112 row_half_mirror row_mask:0xf bank_mask:0xf bound_ctrl:1
	s_nop 0
	v_add_f32_dpp v110, v110, v110 row_ror:8 row_mask:0xf bank_mask:0xf bound_ctrl:1
	v_add_f32_dpp v112, v112, v112 row_ror:8 row_mask:0xf bank_mask:0xf bound_ctrl:1
	v_pk_mul_f32 v[114:115], v[132:133], v[110:111] op_sel_hi:[1,0]
	v_pk_mul_f32 v[116:117], v[132:133], v[112:113] op_sel_hi:[1,0]
	v_pk_mul_f32 v[118:119], v[134:135], v[110:111] op_sel_hi:[1,0]
	v_pk_mul_f32 v[120:121], v[134:135], v[112:113] op_sel_hi:[1,0]
	v_pk_fma_f32 v[114:115], v[194:195], v[198:199], v[114:115] op_sel_hi:[1,0,1]
	v_pk_fma_f32 v[116:117], v[194:195], v[198:199], v[116:117] op_sel:[0,1,0]
	v_pk_fma_f32 v[118:119], v[196:197], v[198:199], v[118:119] op_sel_hi:[1,0,1]
	v_pk_fma_f32 v[120:121], v[196:197], v[198:199], v[120:121] op_sel:[0,1,0]
	v_pk_fma_f32 v[72:73], v[72:73], v[136:137], v[114:115]
	v_pk_fma_f32 v[76:77], v[76:77], v[136:137], v[116:117]
	v_pk_fma_f32 v[74:75], v[74:75], v[138:139], v[118:119]
	v_pk_fma_f32 v[78:79], v[78:79], v[138:139], v[120:121]
	v_pk_mul_f32 v[122:123], v[72:73], v[140:141]
	v_pk_mul_f32 v[124:125], v[76:77], v[140:141]
	v_pk_fma_f32 v[122:123], v[74:75], v[142:143], v[122:123]
	v_pk_fma_f32 v[124:125], v[78:79], v[142:143], v[124:125]
	v_add_f32_e32 v126, v122, v123
	v_add_f32_e32 v127, v124, v125
	ds_write_b64 v187, v[126:127] offset:34816
	s_waitcnt lgkmcnt(8)
	ds_read_b128 v[128:131], v161 offset:13312
	ds_read_b128 v[132:135], v161 offset:21504
	ds_read_b128 v[194:197], v161 offset:29696
	ds_read_b64 v[198:199], v82 offset:46080
	ds_read_b128 v[136:139], v161 offset:5120
	ds_read_b128 v[140:143], v161 offset:37888
	v_pk_mul_f32 v[106:107], v[72:73], v[30:31]
	v_pk_mul_f32 v[108:109], v[76:77], v[30:31]
	v_pk_fma_f32 v[106:107], v[74:75], v[32:33], v[106:107]
	v_pk_fma_f32 v[108:109], v[78:79], v[32:33], v[108:109]
	v_add_f32_e32 v110, v106, v107
	v_add_f32_e32 v112, v108, v109
	s_nop 0
	v_add_f32_dpp v110, v110, v110 quad_perm:[1,0,3,2] row_mask:0xf bank_mask:0xf bound_ctrl:1
	v_add_f32_dpp v112, v112, v112 quad_perm:[1,0,3,2] row_mask:0xf bank_mask:0xf bound_ctrl:1
	s_nop 0
	v_add_f32_dpp v110, v110, v110 quad_perm:[2,3,0,1] row_mask:0xf bank_mask:0xf bound_ctrl:1
	v_add_f32_dpp v112, v112, v112 quad_perm:[2,3,0,1] row_mask:0xf bank_mask:0xf bound_ctrl:1
	s_nop 0
	v_add_f32_dpp v110, v110, v110 row_half_mirror row_mask:0xf bank_mask:0xf bound_ctrl:1
	v_add_f32_dpp v112, v112, v112 row_half_mirror row_mask:0xf bank_mask:0xf bound_ctrl:1
	s_nop 0
	v_add_f32_dpp v110, v110, v110 row_ror:8 row_mask:0xf bank_mask:0xf bound_ctrl:1
	v_add_f32_dpp v112, v112, v112 row_ror:8 row_mask:0xf bank_mask:0xf bound_ctrl:1
	v_pk_mul_f32 v[114:115], v[34:35], v[110:111] op_sel_hi:[1,0]
	v_pk_mul_f32 v[116:117], v[34:35], v[112:113] op_sel_hi:[1,0]
	v_pk_mul_f32 v[118:119], v[36:37], v[110:111] op_sel_hi:[1,0]
	v_pk_mul_f32 v[120:121], v[36:37], v[112:113] op_sel_hi:[1,0]
	v_pk_fma_f32 v[114:115], v[46:47], v[80:81], v[114:115] op_sel_hi:[1,0,1]
	v_pk_fma_f32 v[116:117], v[46:47], v[80:81], v[116:117] op_sel:[0,1,0]
	v_pk_fma_f32 v[118:119], v[48:49], v[80:81], v[118:119] op_sel_hi:[1,0,1]
	v_pk_fma_f32 v[120:121], v[48:49], v[80:81], v[120:121] op_sel:[0,1,0]
	v_pk_fma_f32 v[72:73], v[72:73], v[38:39], v[114:115]
	v_pk_fma_f32 v[76:77], v[76:77], v[38:39], v[116:117]
	v_pk_fma_f32 v[74:75], v[74:75], v[40:41], v[118:119]
	v_pk_fma_f32 v[78:79], v[78:79], v[40:41], v[120:121]
	v_pk_mul_f32 v[122:123], v[72:73], v[42:43]
	v_pk_mul_f32 v[124:125], v[76:77], v[42:43]
	v_pk_fma_f32 v[122:123], v[74:75], v[44:45], v[122:123]
	v_pk_fma_f32 v[124:125], v[78:79], v[44:45], v[124:125]
	v_add_f32_e32 v126, v122, v123
	v_add_f32_e32 v127, v124, v125
	ds_write_b64 v187, v[126:127] offset:36864
	s_waitcnt lgkmcnt(8)
	ds_read_b128 v[30:33], v161 offset:13568
	ds_read_b128 v[34:37], v161 offset:21760
	ds_read_b128 v[46:49], v161 offset:29952
	ds_read_b64 v[80:81], v82 offset:46336
	ds_read_b128 v[38:41], v161 offset:5376
	ds_read_b128 v[42:45], v161 offset:38144
	v_pk_mul_f32 v[106:107], v[72:73], v[84:85]
	v_pk_mul_f32 v[108:109], v[76:77], v[84:85]
	v_pk_fma_f32 v[106:107], v[74:75], v[86:87], v[106:107]
	v_pk_fma_f32 v[108:109], v[78:79], v[86:87], v[108:109]
	v_add_f32_e32 v110, v106, v107
	v_add_f32_e32 v112, v108, v109
	s_nop 0
	v_add_f32_dpp v110, v110, v110 quad_perm:[1,0,3,2] row_mask:0xf bank_mask:0xf bound_ctrl:1
	v_add_f32_dpp v112, v112, v112 quad_perm:[1,0,3,2] row_mask:0xf bank_mask:0xf bound_ctrl:1
	s_nop 0
	v_add_f32_dpp v110, v110, v110 quad_perm:[2,3,0,1] row_mask:0xf bank_mask:0xf bound_ctrl:1
	v_add_f32_dpp v112, v112, v112 quad_perm:[2,3,0,1] row_mask:0xf bank_mask:0xf bound_ctrl:1
	s_nop 0
	v_add_f32_dpp v110, v110, v110 row_half_mirror row_mask:0xf bank_mask:0xf bound_ctrl:1
	v_add_f32_dpp v112, v112, v112 row_half_mirror row_mask:0xf bank_mask:0xf bound_ctrl:1
	s_nop 0
	v_add_f32_dpp v110, v110, v110 row_ror:8 row_mask:0xf bank_mask:0xf bound_ctrl:1
	v_add_f32_dpp v112, v112, v112 row_ror:8 row_mask:0xf bank_mask:0xf bound_ctrl:1
	v_pk_mul_f32 v[114:115], v[88:89], v[110:111] op_sel_hi:[1,0]
	v_pk_mul_f32 v[116:117], v[88:89], v[112:113] op_sel_hi:[1,0]
	v_pk_mul_f32 v[118:119], v[90:91], v[110:111] op_sel_hi:[1,0]
	v_pk_mul_f32 v[120:121], v[90:91], v[112:113] op_sel_hi:[1,0]
	v_pk_fma_f32 v[114:115], v[100:101], v[104:105], v[114:115] op_sel_hi:[1,0,1]
	v_pk_fma_f32 v[116:117], v[100:101], v[104:105], v[116:117] op_sel:[0,1,0]
	v_pk_fma_f32 v[118:119], v[102:103], v[104:105], v[118:119] op_sel_hi:[1,0,1]
	v_pk_fma_f32 v[120:121], v[102:103], v[104:105], v[120:121] op_sel:[0,1,0]
	v_pk_fma_f32 v[72:73], v[72:73], v[92:93], v[114:115]
	v_pk_fma_f32 v[76:77], v[76:77], v[92:93], v[116:117]
	v_pk_fma_f32 v[74:75], v[74:75], v[94:95], v[118:119]
	v_pk_fma_f32 v[78:79], v[78:79], v[94:95], v[120:121]
	v_pk_mul_f32 v[122:123], v[72:73], v[96:97]
	v_pk_mul_f32 v[124:125], v[76:77], v[96:97]
	v_pk_fma_f32 v[122:123], v[74:75], v[98:99], v[122:123]
	v_pk_fma_f32 v[124:125], v[78:79], v[98:99], v[124:125]
	v_add_f32_e32 v126, v122, v123
	v_add_f32_e32 v127, v124, v125
	ds_write_b64 v187, v[126:127] offset:38912
	s_waitcnt lgkmcnt(8)
	ds_read_b128 v[84:87], v161 offset:13824
	ds_read_b128 v[88:91], v161 offset:22016
	ds_read_b128 v[100:103], v161 offset:30208
	ds_read_b64 v[104:105], v82 offset:46592
	ds_read_b128 v[92:95], v161 offset:5632
	ds_read_b128 v[96:99], v161 offset:38400
	v_pk_mul_f32 v[106:107], v[72:73], v[128:129]
	v_pk_mul_f32 v[108:109], v[76:77], v[128:129]
	v_pk_fma_f32 v[106:107], v[74:75], v[130:131], v[106:107]
	v_pk_fma_f32 v[108:109], v[78:79], v[130:131], v[108:109]
	v_add_f32_e32 v110, v106, v107
	v_add_f32_e32 v112, v108, v109
	s_nop 0
	v_add_f32_dpp v110, v110, v110 quad_perm:[1,0,3,2] row_mask:0xf bank_mask:0xf bound_ctrl:1
	v_add_f32_dpp v112, v112, v112 quad_perm:[1,0,3,2] row_mask:0xf bank_mask:0xf bound_ctrl:1
	s_nop 0
	v_add_f32_dpp v110, v110, v110 quad_perm:[2,3,0,1] row_mask:0xf bank_mask:0xf bound_ctrl:1
	v_add_f32_dpp v112, v112, v112 quad_perm:[2,3,0,1] row_mask:0xf bank_mask:0xf bound_ctrl:1
	s_nop 0
	v_add_f32_dpp v110, v110, v110 row_half_mirror row_mask:0xf bank_mask:0xf bound_ctrl:1
	v_add_f32_dpp v112, v112, v112 row_half_mirror row_mask:0xf bank_mask:0xf bound_ctrl:1
	s_nop 0
	v_add_f32_dpp v110, v110, v110 row_ror:8 row_mask:0xf bank_mask:0xf bound_ctrl:1
	v_add_f32_dpp v112, v112, v112 row_ror:8 row_mask:0xf bank_mask:0xf bound_ctrl:1
	v_pk_mul_f32 v[114:115], v[132:133], v[110:111] op_sel_hi:[1,0]
	v_pk_mul_f32 v[116:117], v[132:133], v[112:113] op_sel_hi:[1,0]
	v_pk_mul_f32 v[118:119], v[134:135], v[110:111] op_sel_hi:[1,0]
	v_pk_mul_f32 v[120:121], v[134:135], v[112:113] op_sel_hi:[1,0]
	v_pk_fma_f32 v[114:115], v[194:195], v[198:199], v[114:115] op_sel_hi:[1,0,1]
	v_pk_fma_f32 v[116:117], v[194:195], v[198:199], v[116:117] op_sel:[0,1,0]
	v_pk_fma_f32 v[118:119], v[196:197], v[198:199], v[118:119] op_sel_hi:[1,0,1]
	v_pk_fma_f32 v[120:121], v[196:197], v[198:199], v[120:121] op_sel:[0,1,0]
	v_pk_fma_f32 v[72:73], v[72:73], v[136:137], v[114:115]
	v_pk_fma_f32 v[76:77], v[76:77], v[136:137], v[116:117]
	v_pk_fma_f32 v[74:75], v[74:75], v[138:139], v[118:119]
	v_pk_fma_f32 v[78:79], v[78:79], v[138:139], v[120:121]
	v_pk_mul_f32 v[122:123], v[72:73], v[140:141]
	v_pk_mul_f32 v[124:125], v[76:77], v[140:141]
	v_pk_fma_f32 v[122:123], v[74:75], v[142:143], v[122:123]
	v_pk_fma_f32 v[124:125], v[78:79], v[142:143], v[124:125]
	v_add_f32_e32 v126, v122, v123
	v_add_f32_e32 v127, v124, v125
	ds_write_b64 v187, v[126:127] offset:40960
	s_waitcnt lgkmcnt(8)
	ds_read_b128 v[128:131], v161 offset:14080
	ds_read_b128 v[132:135], v161 offset:22272
	ds_read_b128 v[194:197], v161 offset:30464
	ds_read_b64 v[198:199], v82 offset:46848
	ds_read_b128 v[136:139], v161 offset:5888
	ds_read_b128 v[140:143], v161 offset:38656
	v_pk_mul_f32 v[106:107], v[72:73], v[30:31]
	v_pk_mul_f32 v[108:109], v[76:77], v[30:31]
	v_pk_fma_f32 v[106:107], v[74:75], v[32:33], v[106:107]
	v_pk_fma_f32 v[108:109], v[78:79], v[32:33], v[108:109]
	v_add_f32_e32 v110, v106, v107
	v_add_f32_e32 v112, v108, v109
	s_nop 0
	v_add_f32_dpp v110, v110, v110 quad_perm:[1,0,3,2] row_mask:0xf bank_mask:0xf bound_ctrl:1
	v_add_f32_dpp v112, v112, v112 quad_perm:[1,0,3,2] row_mask:0xf bank_mask:0xf bound_ctrl:1
	s_nop 0
	v_add_f32_dpp v110, v110, v110 quad_perm:[2,3,0,1] row_mask:0xf bank_mask:0xf bound_ctrl:1
	v_add_f32_dpp v112, v112, v112 quad_perm:[2,3,0,1] row_mask:0xf bank_mask:0xf bound_ctrl:1
	s_nop 0
	v_add_f32_dpp v110, v110, v110 row_half_mirror row_mask:0xf bank_mask:0xf bound_ctrl:1
	v_add_f32_dpp v112, v112, v112 row_half_mirror row_mask:0xf bank_mask:0xf bound_ctrl:1
	s_nop 0
	v_add_f32_dpp v110, v110, v110 row_ror:8 row_mask:0xf bank_mask:0xf bound_ctrl:1
	v_add_f32_dpp v112, v112, v112 row_ror:8 row_mask:0xf bank_mask:0xf bound_ctrl:1
	v_pk_mul_f32 v[114:115], v[34:35], v[110:111] op_sel_hi:[1,0]
	v_pk_mul_f32 v[116:117], v[34:35], v[112:113] op_sel_hi:[1,0]
	v_pk_mul_f32 v[118:119], v[36:37], v[110:111] op_sel_hi:[1,0]
	v_pk_mul_f32 v[120:121], v[36:37], v[112:113] op_sel_hi:[1,0]
	v_pk_fma_f32 v[114:115], v[46:47], v[80:81], v[114:115] op_sel_hi:[1,0,1]
	v_pk_fma_f32 v[116:117], v[46:47], v[80:81], v[116:117] op_sel:[0,1,0]
	v_pk_fma_f32 v[118:119], v[48:49], v[80:81], v[118:119] op_sel_hi:[1,0,1]
	v_pk_fma_f32 v[120:121], v[48:49], v[80:81], v[120:121] op_sel:[0,1,0]
	v_pk_fma_f32 v[72:73], v[72:73], v[38:39], v[114:115]
	v_pk_fma_f32 v[76:77], v[76:77], v[38:39], v[116:117]
	v_pk_fma_f32 v[74:75], v[74:75], v[40:41], v[118:119]
	v_pk_fma_f32 v[78:79], v[78:79], v[40:41], v[120:121]
	v_pk_mul_f32 v[122:123], v[72:73], v[42:43]
	v_pk_mul_f32 v[124:125], v[76:77], v[42:43]
	v_pk_fma_f32 v[122:123], v[74:75], v[44:45], v[122:123]
	v_pk_fma_f32 v[124:125], v[78:79], v[44:45], v[124:125]
	v_add_f32_e32 v126, v122, v123
	v_add_f32_e32 v127, v124, v125
	ds_write_b64 v187, v[126:127] offset:43008
	s_waitcnt lgkmcnt(8)
	ds_read_b128 v[30:33], v161 offset:14336
	ds_read_b128 v[34:37], v161 offset:22528
	ds_read_b128 v[46:49], v161 offset:30720
	ds_read_b64 v[80:81], v82 offset:47104
	ds_read_b128 v[38:41], v161 offset:6144
	ds_read_b128 v[42:45], v161 offset:38912
	v_pk_mul_f32 v[106:107], v[72:73], v[84:85]
	v_pk_mul_f32 v[108:109], v[76:77], v[84:85]
	v_pk_fma_f32 v[106:107], v[74:75], v[86:87], v[106:107]
	v_pk_fma_f32 v[108:109], v[78:79], v[86:87], v[108:109]
	v_add_f32_e32 v110, v106, v107
	v_add_f32_e32 v112, v108, v109
	s_nop 0
	v_add_f32_dpp v110, v110, v110 quad_perm:[1,0,3,2] row_mask:0xf bank_mask:0xf bound_ctrl:1
	v_add_f32_dpp v112, v112, v112 quad_perm:[1,0,3,2] row_mask:0xf bank_mask:0xf bound_ctrl:1
	s_nop 0
	v_add_f32_dpp v110, v110, v110 quad_perm:[2,3,0,1] row_mask:0xf bank_mask:0xf bound_ctrl:1
	v_add_f32_dpp v112, v112, v112 quad_perm:[2,3,0,1] row_mask:0xf bank_mask:0xf bound_ctrl:1
	s_nop 0
	v_add_f32_dpp v110, v110, v110 row_half_mirror row_mask:0xf bank_mask:0xf bound_ctrl:1
	v_add_f32_dpp v112, v112, v112 row_half_mirror row_mask:0xf bank_mask:0xf bound_ctrl:1
	s_nop 0
	v_add_f32_dpp v110, v110, v110 row_ror:8 row_mask:0xf bank_mask:0xf bound_ctrl:1
	v_add_f32_dpp v112, v112, v112 row_ror:8 row_mask:0xf bank_mask:0xf bound_ctrl:1
	v_pk_mul_f32 v[114:115], v[88:89], v[110:111] op_sel_hi:[1,0]
	v_pk_mul_f32 v[116:117], v[88:89], v[112:113] op_sel_hi:[1,0]
	v_pk_mul_f32 v[118:119], v[90:91], v[110:111] op_sel_hi:[1,0]
	v_pk_mul_f32 v[120:121], v[90:91], v[112:113] op_sel_hi:[1,0]
	v_pk_fma_f32 v[114:115], v[100:101], v[104:105], v[114:115] op_sel_hi:[1,0,1]
	v_pk_fma_f32 v[116:117], v[100:101], v[104:105], v[116:117] op_sel:[0,1,0]
	v_pk_fma_f32 v[118:119], v[102:103], v[104:105], v[118:119] op_sel_hi:[1,0,1]
	v_pk_fma_f32 v[120:121], v[102:103], v[104:105], v[120:121] op_sel:[0,1,0]
	v_pk_fma_f32 v[72:73], v[72:73], v[92:93], v[114:115]
	v_pk_fma_f32 v[76:77], v[76:77], v[92:93], v[116:117]
	v_pk_fma_f32 v[74:75], v[74:75], v[94:95], v[118:119]
	v_pk_fma_f32 v[78:79], v[78:79], v[94:95], v[120:121]
	v_pk_mul_f32 v[122:123], v[72:73], v[96:97]
	v_pk_mul_f32 v[124:125], v[76:77], v[96:97]
	v_pk_fma_f32 v[122:123], v[74:75], v[98:99], v[122:123]
	v_pk_fma_f32 v[124:125], v[78:79], v[98:99], v[124:125]
	v_add_f32_e32 v126, v122, v123
	v_add_f32_e32 v127, v124, v125
	ds_write_b64 v187, v[126:127] offset:45056
	s_waitcnt lgkmcnt(8)
	ds_read_b128 v[84:87], v161 offset:14592
	ds_read_b128 v[88:91], v161 offset:22784
	ds_read_b128 v[100:103], v161 offset:30976
	ds_read_b64 v[104:105], v82 offset:47360
	ds_read_b128 v[92:95], v161 offset:6400
	ds_read_b128 v[96:99], v161 offset:39168
	v_pk_mul_f32 v[106:107], v[72:73], v[128:129]
	v_pk_mul_f32 v[108:109], v[76:77], v[128:129]
	v_pk_fma_f32 v[106:107], v[74:75], v[130:131], v[106:107]
	v_pk_fma_f32 v[108:109], v[78:79], v[130:131], v[108:109]
	v_add_f32_e32 v110, v106, v107
	v_add_f32_e32 v112, v108, v109
	s_nop 0
	v_add_f32_dpp v110, v110, v110 quad_perm:[1,0,3,2] row_mask:0xf bank_mask:0xf bound_ctrl:1
	v_add_f32_dpp v112, v112, v112 quad_perm:[1,0,3,2] row_mask:0xf bank_mask:0xf bound_ctrl:1
	s_nop 0
	v_add_f32_dpp v110, v110, v110 quad_perm:[2,3,0,1] row_mask:0xf bank_mask:0xf bound_ctrl:1
	v_add_f32_dpp v112, v112, v112 quad_perm:[2,3,0,1] row_mask:0xf bank_mask:0xf bound_ctrl:1
	s_nop 0
	v_add_f32_dpp v110, v110, v110 row_half_mirror row_mask:0xf bank_mask:0xf bound_ctrl:1
	v_add_f32_dpp v112, v112, v112 row_half_mirror row_mask:0xf bank_mask:0xf bound_ctrl:1
	s_nop 0
	v_add_f32_dpp v110, v110, v110 row_ror:8 row_mask:0xf bank_mask:0xf bound_ctrl:1
	v_add_f32_dpp v112, v112, v112 row_ror:8 row_mask:0xf bank_mask:0xf bound_ctrl:1
	v_pk_mul_f32 v[114:115], v[132:133], v[110:111] op_sel_hi:[1,0]
	v_pk_mul_f32 v[116:117], v[132:133], v[112:113] op_sel_hi:[1,0]
	v_pk_mul_f32 v[118:119], v[134:135], v[110:111] op_sel_hi:[1,0]
	v_pk_mul_f32 v[120:121], v[134:135], v[112:113] op_sel_hi:[1,0]
	v_pk_fma_f32 v[114:115], v[194:195], v[198:199], v[114:115] op_sel_hi:[1,0,1]
	v_pk_fma_f32 v[116:117], v[194:195], v[198:199], v[116:117] op_sel:[0,1,0]
	v_pk_fma_f32 v[118:119], v[196:197], v[198:199], v[118:119] op_sel_hi:[1,0,1]
	v_pk_fma_f32 v[120:121], v[196:197], v[198:199], v[120:121] op_sel:[0,1,0]
	v_pk_fma_f32 v[72:73], v[72:73], v[136:137], v[114:115]
	v_pk_fma_f32 v[76:77], v[76:77], v[136:137], v[116:117]
	v_pk_fma_f32 v[74:75], v[74:75], v[138:139], v[118:119]
	v_pk_fma_f32 v[78:79], v[78:79], v[138:139], v[120:121]
	v_pk_mul_f32 v[122:123], v[72:73], v[140:141]
	v_pk_mul_f32 v[124:125], v[76:77], v[140:141]
	v_pk_fma_f32 v[122:123], v[74:75], v[142:143], v[122:123]
	v_pk_fma_f32 v[124:125], v[78:79], v[142:143], v[124:125]
	v_add_f32_e32 v126, v122, v123
	v_add_f32_e32 v127, v124, v125
	ds_write_b64 v187, v[126:127] offset:47104
	s_waitcnt lgkmcnt(8)
	ds_read_b128 v[128:131], v161 offset:14848
	ds_read_b128 v[132:135], v161 offset:23040
	ds_read_b128 v[194:197], v161 offset:31232
	ds_read_b64 v[198:199], v82 offset:47616
	ds_read_b128 v[136:139], v161 offset:6656
	ds_read_b128 v[140:143], v161 offset:39424
	v_pk_mul_f32 v[106:107], v[72:73], v[30:31]
	v_pk_mul_f32 v[108:109], v[76:77], v[30:31]
	v_pk_fma_f32 v[106:107], v[74:75], v[32:33], v[106:107]
	v_pk_fma_f32 v[108:109], v[78:79], v[32:33], v[108:109]
	v_add_f32_e32 v110, v106, v107
	v_add_f32_e32 v112, v108, v109
	s_nop 0
	v_add_f32_dpp v110, v110, v110 quad_perm:[1,0,3,2] row_mask:0xf bank_mask:0xf bound_ctrl:1
	v_add_f32_dpp v112, v112, v112 quad_perm:[1,0,3,2] row_mask:0xf bank_mask:0xf bound_ctrl:1
	s_nop 0
	v_add_f32_dpp v110, v110, v110 quad_perm:[2,3,0,1] row_mask:0xf bank_mask:0xf bound_ctrl:1
	v_add_f32_dpp v112, v112, v112 quad_perm:[2,3,0,1] row_mask:0xf bank_mask:0xf bound_ctrl:1
	s_nop 0
	v_add_f32_dpp v110, v110, v110 row_half_mirror row_mask:0xf bank_mask:0xf bound_ctrl:1
	v_add_f32_dpp v112, v112, v112 row_half_mirror row_mask:0xf bank_mask:0xf bound_ctrl:1
	s_nop 0
	v_add_f32_dpp v110, v110, v110 row_ror:8 row_mask:0xf bank_mask:0xf bound_ctrl:1
	v_add_f32_dpp v112, v112, v112 row_ror:8 row_mask:0xf bank_mask:0xf bound_ctrl:1
	v_pk_mul_f32 v[114:115], v[34:35], v[110:111] op_sel_hi:[1,0]
	v_pk_mul_f32 v[116:117], v[34:35], v[112:113] op_sel_hi:[1,0]
	v_pk_mul_f32 v[118:119], v[36:37], v[110:111] op_sel_hi:[1,0]
	v_pk_mul_f32 v[120:121], v[36:37], v[112:113] op_sel_hi:[1,0]
	v_pk_fma_f32 v[114:115], v[46:47], v[80:81], v[114:115] op_sel_hi:[1,0,1]
	v_pk_fma_f32 v[116:117], v[46:47], v[80:81], v[116:117] op_sel:[0,1,0]
	v_pk_fma_f32 v[118:119], v[48:49], v[80:81], v[118:119] op_sel_hi:[1,0,1]
	v_pk_fma_f32 v[120:121], v[48:49], v[80:81], v[120:121] op_sel:[0,1,0]
	v_pk_fma_f32 v[72:73], v[72:73], v[38:39], v[114:115]
	v_pk_fma_f32 v[76:77], v[76:77], v[38:39], v[116:117]
	v_pk_fma_f32 v[74:75], v[74:75], v[40:41], v[118:119]
	v_pk_fma_f32 v[78:79], v[78:79], v[40:41], v[120:121]
	v_pk_mul_f32 v[122:123], v[72:73], v[42:43]
	v_pk_mul_f32 v[124:125], v[76:77], v[42:43]
	v_pk_fma_f32 v[122:123], v[74:75], v[44:45], v[122:123]
	v_pk_fma_f32 v[124:125], v[78:79], v[44:45], v[124:125]
	v_add_f32_e32 v126, v122, v123
	v_add_f32_e32 v127, v124, v125
	ds_write_b64 v187, v[126:127] offset:49152
	s_waitcnt lgkmcnt(8)
	ds_read_b128 v[30:33], v161 offset:15104
	ds_read_b128 v[34:37], v161 offset:23296
	ds_read_b128 v[46:49], v161 offset:31488
	ds_read_b64 v[80:81], v82 offset:47872
	ds_read_b128 v[38:41], v161 offset:6912
	ds_read_b128 v[42:45], v161 offset:39680
	v_pk_mul_f32 v[106:107], v[72:73], v[84:85]
	v_pk_mul_f32 v[108:109], v[76:77], v[84:85]
	v_pk_fma_f32 v[106:107], v[74:75], v[86:87], v[106:107]
	v_pk_fma_f32 v[108:109], v[78:79], v[86:87], v[108:109]
	v_add_f32_e32 v110, v106, v107
	v_add_f32_e32 v112, v108, v109
	s_nop 0
	v_add_f32_dpp v110, v110, v110 quad_perm:[1,0,3,2] row_mask:0xf bank_mask:0xf bound_ctrl:1
	v_add_f32_dpp v112, v112, v112 quad_perm:[1,0,3,2] row_mask:0xf bank_mask:0xf bound_ctrl:1
	s_nop 0
	v_add_f32_dpp v110, v110, v110 quad_perm:[2,3,0,1] row_mask:0xf bank_mask:0xf bound_ctrl:1
	v_add_f32_dpp v112, v112, v112 quad_perm:[2,3,0,1] row_mask:0xf bank_mask:0xf bound_ctrl:1
	s_nop 0
	v_add_f32_dpp v110, v110, v110 row_half_mirror row_mask:0xf bank_mask:0xf bound_ctrl:1
	v_add_f32_dpp v112, v112, v112 row_half_mirror row_mask:0xf bank_mask:0xf bound_ctrl:1
	s_nop 0
	v_add_f32_dpp v110, v110, v110 row_ror:8 row_mask:0xf bank_mask:0xf bound_ctrl:1
	v_add_f32_dpp v112, v112, v112 row_ror:8 row_mask:0xf bank_mask:0xf bound_ctrl:1
	v_pk_mul_f32 v[114:115], v[88:89], v[110:111] op_sel_hi:[1,0]
	v_pk_mul_f32 v[116:117], v[88:89], v[112:113] op_sel_hi:[1,0]
	v_pk_mul_f32 v[118:119], v[90:91], v[110:111] op_sel_hi:[1,0]
	v_pk_mul_f32 v[120:121], v[90:91], v[112:113] op_sel_hi:[1,0]
	v_pk_fma_f32 v[114:115], v[100:101], v[104:105], v[114:115] op_sel_hi:[1,0,1]
	v_pk_fma_f32 v[116:117], v[100:101], v[104:105], v[116:117] op_sel:[0,1,0]
	v_pk_fma_f32 v[118:119], v[102:103], v[104:105], v[118:119] op_sel_hi:[1,0,1]
	v_pk_fma_f32 v[120:121], v[102:103], v[104:105], v[120:121] op_sel:[0,1,0]
	v_pk_fma_f32 v[72:73], v[72:73], v[92:93], v[114:115]
	v_pk_fma_f32 v[76:77], v[76:77], v[92:93], v[116:117]
	v_pk_fma_f32 v[74:75], v[74:75], v[94:95], v[118:119]
	v_pk_fma_f32 v[78:79], v[78:79], v[94:95], v[120:121]
	v_pk_mul_f32 v[122:123], v[72:73], v[96:97]
	v_pk_mul_f32 v[124:125], v[76:77], v[96:97]
	v_pk_fma_f32 v[122:123], v[74:75], v[98:99], v[122:123]
	v_pk_fma_f32 v[124:125], v[78:79], v[98:99], v[124:125]
	v_add_f32_e32 v126, v122, v123
	v_add_f32_e32 v127, v124, v125
	ds_write_b64 v187, v[126:127] offset:51200
	s_waitcnt lgkmcnt(8)
	ds_read_b128 v[84:87], v161 offset:15360
	ds_read_b128 v[88:91], v161 offset:23552
	ds_read_b128 v[100:103], v161 offset:31744
	ds_read_b64 v[104:105], v82 offset:48128
	ds_read_b128 v[92:95], v161 offset:7168
	ds_read_b128 v[96:99], v161 offset:39936
	v_pk_mul_f32 v[106:107], v[72:73], v[128:129]
	v_pk_mul_f32 v[108:109], v[76:77], v[128:129]
	v_pk_fma_f32 v[106:107], v[74:75], v[130:131], v[106:107]
	v_pk_fma_f32 v[108:109], v[78:79], v[130:131], v[108:109]
	v_add_f32_e32 v110, v106, v107
	v_add_f32_e32 v112, v108, v109
	s_nop 0
	v_add_f32_dpp v110, v110, v110 quad_perm:[1,0,3,2] row_mask:0xf bank_mask:0xf bound_ctrl:1
	v_add_f32_dpp v112, v112, v112 quad_perm:[1,0,3,2] row_mask:0xf bank_mask:0xf bound_ctrl:1
	s_nop 0
	v_add_f32_dpp v110, v110, v110 quad_perm:[2,3,0,1] row_mask:0xf bank_mask:0xf bound_ctrl:1
	v_add_f32_dpp v112, v112, v112 quad_perm:[2,3,0,1] row_mask:0xf bank_mask:0xf bound_ctrl:1
	s_nop 0
	v_add_f32_dpp v110, v110, v110 row_half_mirror row_mask:0xf bank_mask:0xf bound_ctrl:1
	v_add_f32_dpp v112, v112, v112 row_half_mirror row_mask:0xf bank_mask:0xf bound_ctrl:1
	s_nop 0
	v_add_f32_dpp v110, v110, v110 row_ror:8 row_mask:0xf bank_mask:0xf bound_ctrl:1
	v_add_f32_dpp v112, v112, v112 row_ror:8 row_mask:0xf bank_mask:0xf bound_ctrl:1
	v_pk_mul_f32 v[114:115], v[132:133], v[110:111] op_sel_hi:[1,0]
	v_pk_mul_f32 v[116:117], v[132:133], v[112:113] op_sel_hi:[1,0]
	v_pk_mul_f32 v[118:119], v[134:135], v[110:111] op_sel_hi:[1,0]
	v_pk_mul_f32 v[120:121], v[134:135], v[112:113] op_sel_hi:[1,0]
	v_pk_fma_f32 v[114:115], v[194:195], v[198:199], v[114:115] op_sel_hi:[1,0,1]
	v_pk_fma_f32 v[116:117], v[194:195], v[198:199], v[116:117] op_sel:[0,1,0]
	v_pk_fma_f32 v[118:119], v[196:197], v[198:199], v[118:119] op_sel_hi:[1,0,1]
	v_pk_fma_f32 v[120:121], v[196:197], v[198:199], v[120:121] op_sel:[0,1,0]
	v_pk_fma_f32 v[72:73], v[72:73], v[136:137], v[114:115]
	v_pk_fma_f32 v[76:77], v[76:77], v[136:137], v[116:117]
	v_pk_fma_f32 v[74:75], v[74:75], v[138:139], v[118:119]
	v_pk_fma_f32 v[78:79], v[78:79], v[138:139], v[120:121]
	v_pk_mul_f32 v[122:123], v[72:73], v[140:141]
	v_pk_mul_f32 v[124:125], v[76:77], v[140:141]
	v_pk_fma_f32 v[122:123], v[74:75], v[142:143], v[122:123]
	v_pk_fma_f32 v[124:125], v[78:79], v[142:143], v[124:125]
	v_add_f32_e32 v126, v122, v123
	v_add_f32_e32 v127, v124, v125
	ds_write_b64 v187, v[126:127] offset:53248
	s_waitcnt lgkmcnt(8)
	ds_read_b128 v[128:131], v161 offset:15616
	ds_read_b128 v[132:135], v161 offset:23808
	ds_read_b128 v[194:197], v161 offset:32000
	ds_read_b64 v[198:199], v82 offset:48384
	ds_read_b128 v[136:139], v161 offset:7424
	ds_read_b128 v[140:143], v161 offset:40192
	v_pk_mul_f32 v[106:107], v[72:73], v[30:31]
	v_pk_mul_f32 v[108:109], v[76:77], v[30:31]
	v_pk_fma_f32 v[106:107], v[74:75], v[32:33], v[106:107]
	v_pk_fma_f32 v[108:109], v[78:79], v[32:33], v[108:109]
	v_add_f32_e32 v110, v106, v107
	v_add_f32_e32 v112, v108, v109
	s_nop 0
	v_add_f32_dpp v110, v110, v110 quad_perm:[1,0,3,2] row_mask:0xf bank_mask:0xf bound_ctrl:1
	v_add_f32_dpp v112, v112, v112 quad_perm:[1,0,3,2] row_mask:0xf bank_mask:0xf bound_ctrl:1
	s_nop 0
	v_add_f32_dpp v110, v110, v110 quad_perm:[2,3,0,1] row_mask:0xf bank_mask:0xf bound_ctrl:1
	v_add_f32_dpp v112, v112, v112 quad_perm:[2,3,0,1] row_mask:0xf bank_mask:0xf bound_ctrl:1
	s_nop 0
	v_add_f32_dpp v110, v110, v110 row_half_mirror row_mask:0xf bank_mask:0xf bound_ctrl:1
	v_add_f32_dpp v112, v112, v112 row_half_mirror row_mask:0xf bank_mask:0xf bound_ctrl:1
	s_nop 0
	v_add_f32_dpp v110, v110, v110 row_ror:8 row_mask:0xf bank_mask:0xf bound_ctrl:1
	v_add_f32_dpp v112, v112, v112 row_ror:8 row_mask:0xf bank_mask:0xf bound_ctrl:1
	v_pk_mul_f32 v[114:115], v[34:35], v[110:111] op_sel_hi:[1,0]
	v_pk_mul_f32 v[116:117], v[34:35], v[112:113] op_sel_hi:[1,0]
	v_pk_mul_f32 v[118:119], v[36:37], v[110:111] op_sel_hi:[1,0]
	v_pk_mul_f32 v[120:121], v[36:37], v[112:113] op_sel_hi:[1,0]
	v_pk_fma_f32 v[114:115], v[46:47], v[80:81], v[114:115] op_sel_hi:[1,0,1]
	v_pk_fma_f32 v[116:117], v[46:47], v[80:81], v[116:117] op_sel:[0,1,0]
	v_pk_fma_f32 v[118:119], v[48:49], v[80:81], v[118:119] op_sel_hi:[1,0,1]
	v_pk_fma_f32 v[120:121], v[48:49], v[80:81], v[120:121] op_sel:[0,1,0]
	v_pk_fma_f32 v[72:73], v[72:73], v[38:39], v[114:115]
	v_pk_fma_f32 v[76:77], v[76:77], v[38:39], v[116:117]
	v_pk_fma_f32 v[74:75], v[74:75], v[40:41], v[118:119]
	v_pk_fma_f32 v[78:79], v[78:79], v[40:41], v[120:121]
	v_pk_mul_f32 v[122:123], v[72:73], v[42:43]
	v_pk_mul_f32 v[124:125], v[76:77], v[42:43]
	v_pk_fma_f32 v[122:123], v[74:75], v[44:45], v[122:123]
	v_pk_fma_f32 v[124:125], v[78:79], v[44:45], v[124:125]
	v_add_f32_e32 v126, v122, v123
	v_add_f32_e32 v127, v124, v125
	ds_write_b64 v187, v[126:127] offset:55296
	s_waitcnt lgkmcnt(8)
	ds_read_b128 v[30:33], v161 offset:15872
	ds_read_b128 v[34:37], v161 offset:24064
	ds_read_b128 v[46:49], v161 offset:32256
	ds_read_b64 v[80:81], v82 offset:48640
	ds_read_b128 v[38:41], v161 offset:7680
	ds_read_b128 v[42:45], v161 offset:40448
	v_pk_mul_f32 v[106:107], v[72:73], v[84:85]
	v_pk_mul_f32 v[108:109], v[76:77], v[84:85]
	v_pk_fma_f32 v[106:107], v[74:75], v[86:87], v[106:107]
	v_pk_fma_f32 v[108:109], v[78:79], v[86:87], v[108:109]
	v_add_f32_e32 v110, v106, v107
	v_add_f32_e32 v112, v108, v109
	s_nop 0
	v_add_f32_dpp v110, v110, v110 quad_perm:[1,0,3,2] row_mask:0xf bank_mask:0xf bound_ctrl:1
	v_add_f32_dpp v112, v112, v112 quad_perm:[1,0,3,2] row_mask:0xf bank_mask:0xf bound_ctrl:1
	s_nop 0
	v_add_f32_dpp v110, v110, v110 quad_perm:[2,3,0,1] row_mask:0xf bank_mask:0xf bound_ctrl:1
	v_add_f32_dpp v112, v112, v112 quad_perm:[2,3,0,1] row_mask:0xf bank_mask:0xf bound_ctrl:1
	s_nop 0
	v_add_f32_dpp v110, v110, v110 row_half_mirror row_mask:0xf bank_mask:0xf bound_ctrl:1
	v_add_f32_dpp v112, v112, v112 row_half_mirror row_mask:0xf bank_mask:0xf bound_ctrl:1
	s_nop 0
	v_add_f32_dpp v110, v110, v110 row_ror:8 row_mask:0xf bank_mask:0xf bound_ctrl:1
	v_add_f32_dpp v112, v112, v112 row_ror:8 row_mask:0xf bank_mask:0xf bound_ctrl:1
	v_pk_mul_f32 v[114:115], v[88:89], v[110:111] op_sel_hi:[1,0]
	v_pk_mul_f32 v[116:117], v[88:89], v[112:113] op_sel_hi:[1,0]
	v_pk_mul_f32 v[118:119], v[90:91], v[110:111] op_sel_hi:[1,0]
	v_pk_mul_f32 v[120:121], v[90:91], v[112:113] op_sel_hi:[1,0]
	v_pk_fma_f32 v[114:115], v[100:101], v[104:105], v[114:115] op_sel_hi:[1,0,1]
	v_pk_fma_f32 v[116:117], v[100:101], v[104:105], v[116:117] op_sel:[0,1,0]
	v_pk_fma_f32 v[118:119], v[102:103], v[104:105], v[118:119] op_sel_hi:[1,0,1]
	v_pk_fma_f32 v[120:121], v[102:103], v[104:105], v[120:121] op_sel:[0,1,0]
	v_pk_fma_f32 v[72:73], v[72:73], v[92:93], v[114:115]
	v_pk_fma_f32 v[76:77], v[76:77], v[92:93], v[116:117]
	v_pk_fma_f32 v[74:75], v[74:75], v[94:95], v[118:119]
	v_pk_fma_f32 v[78:79], v[78:79], v[94:95], v[120:121]
	v_pk_mul_f32 v[122:123], v[72:73], v[96:97]
	v_pk_mul_f32 v[124:125], v[76:77], v[96:97]
	v_pk_fma_f32 v[122:123], v[74:75], v[98:99], v[122:123]
	v_pk_fma_f32 v[124:125], v[78:79], v[98:99], v[124:125]
	v_add_f32_e32 v126, v122, v123
	v_add_f32_e32 v127, v124, v125
	ds_write_b64 v187, v[126:127] offset:57344
	s_waitcnt lgkmcnt(8)
	ds_read_b128 v[84:87], v161 offset:16128
	ds_read_b128 v[88:91], v161 offset:24320
	ds_read_b128 v[100:103], v161 offset:32512
	ds_read_b64 v[104:105], v82 offset:48896
	ds_read_b128 v[92:95], v161 offset:7936
	ds_read_b128 v[96:99], v161 offset:40704
	v_pk_mul_f32 v[106:107], v[72:73], v[128:129]
	v_pk_mul_f32 v[108:109], v[76:77], v[128:129]
	v_pk_fma_f32 v[106:107], v[74:75], v[130:131], v[106:107]
	v_pk_fma_f32 v[108:109], v[78:79], v[130:131], v[108:109]
	v_add_f32_e32 v110, v106, v107
	v_add_f32_e32 v112, v108, v109
	s_nop 0
	v_add_f32_dpp v110, v110, v110 quad_perm:[1,0,3,2] row_mask:0xf bank_mask:0xf bound_ctrl:1
	v_add_f32_dpp v112, v112, v112 quad_perm:[1,0,3,2] row_mask:0xf bank_mask:0xf bound_ctrl:1
	s_nop 0
	v_add_f32_dpp v110, v110, v110 quad_perm:[2,3,0,1] row_mask:0xf bank_mask:0xf bound_ctrl:1
	v_add_f32_dpp v112, v112, v112 quad_perm:[2,3,0,1] row_mask:0xf bank_mask:0xf bound_ctrl:1
	s_nop 0
	v_add_f32_dpp v110, v110, v110 row_half_mirror row_mask:0xf bank_mask:0xf bound_ctrl:1
	v_add_f32_dpp v112, v112, v112 row_half_mirror row_mask:0xf bank_mask:0xf bound_ctrl:1
	s_nop 0
	v_add_f32_dpp v110, v110, v110 row_ror:8 row_mask:0xf bank_mask:0xf bound_ctrl:1
	v_add_f32_dpp v112, v112, v112 row_ror:8 row_mask:0xf bank_mask:0xf bound_ctrl:1
	v_pk_mul_f32 v[114:115], v[132:133], v[110:111] op_sel_hi:[1,0]
	v_pk_mul_f32 v[116:117], v[132:133], v[112:113] op_sel_hi:[1,0]
	v_pk_mul_f32 v[118:119], v[134:135], v[110:111] op_sel_hi:[1,0]
	v_pk_mul_f32 v[120:121], v[134:135], v[112:113] op_sel_hi:[1,0]
	v_pk_fma_f32 v[114:115], v[194:195], v[198:199], v[114:115] op_sel_hi:[1,0,1]
	v_pk_fma_f32 v[116:117], v[194:195], v[198:199], v[116:117] op_sel:[0,1,0]
	v_pk_fma_f32 v[118:119], v[196:197], v[198:199], v[118:119] op_sel_hi:[1,0,1]
	v_pk_fma_f32 v[120:121], v[196:197], v[198:199], v[120:121] op_sel:[0,1,0]
	v_pk_fma_f32 v[72:73], v[72:73], v[136:137], v[114:115]
	v_pk_fma_f32 v[76:77], v[76:77], v[136:137], v[116:117]
	v_pk_fma_f32 v[74:75], v[74:75], v[138:139], v[118:119]
	v_pk_fma_f32 v[78:79], v[78:79], v[138:139], v[120:121]
	v_pk_mul_f32 v[122:123], v[72:73], v[140:141]
	v_pk_mul_f32 v[124:125], v[76:77], v[140:141]
	v_pk_fma_f32 v[122:123], v[74:75], v[142:143], v[122:123]
	v_pk_fma_f32 v[124:125], v[78:79], v[142:143], v[124:125]
	v_add_f32_e32 v126, v122, v123
	v_add_f32_e32 v127, v124, v125
	ds_write_b64 v187, v[126:127] offset:59392
	s_waitcnt lgkmcnt(8)
	v_pk_mul_f32 v[106:107], v[72:73], v[30:31]
	v_pk_mul_f32 v[108:109], v[76:77], v[30:31]
	v_pk_fma_f32 v[106:107], v[74:75], v[32:33], v[106:107]
	v_pk_fma_f32 v[108:109], v[78:79], v[32:33], v[108:109]
	v_add_f32_e32 v110, v106, v107
	v_add_f32_e32 v112, v108, v109
	s_nop 0
	v_add_f32_dpp v110, v110, v110 quad_perm:[1,0,3,2] row_mask:0xf bank_mask:0xf bound_ctrl:1
	v_add_f32_dpp v112, v112, v112 quad_perm:[1,0,3,2] row_mask:0xf bank_mask:0xf bound_ctrl:1
	s_nop 0
	v_add_f32_dpp v110, v110, v110 quad_perm:[2,3,0,1] row_mask:0xf bank_mask:0xf bound_ctrl:1
	v_add_f32_dpp v112, v112, v112 quad_perm:[2,3,0,1] row_mask:0xf bank_mask:0xf bound_ctrl:1
	s_nop 0
	v_add_f32_dpp v110, v110, v110 row_half_mirror row_mask:0xf bank_mask:0xf bound_ctrl:1
	v_add_f32_dpp v112, v112, v112 row_half_mirror row_mask:0xf bank_mask:0xf bound_ctrl:1
	s_nop 0
	v_add_f32_dpp v110, v110, v110 row_ror:8 row_mask:0xf bank_mask:0xf bound_ctrl:1
	v_add_f32_dpp v112, v112, v112 row_ror:8 row_mask:0xf bank_mask:0xf bound_ctrl:1
	v_pk_mul_f32 v[114:115], v[34:35], v[110:111] op_sel_hi:[1,0]
	v_pk_mul_f32 v[116:117], v[34:35], v[112:113] op_sel_hi:[1,0]
	v_pk_mul_f32 v[118:119], v[36:37], v[110:111] op_sel_hi:[1,0]
	v_pk_mul_f32 v[120:121], v[36:37], v[112:113] op_sel_hi:[1,0]
	v_pk_fma_f32 v[114:115], v[46:47], v[80:81], v[114:115] op_sel_hi:[1,0,1]
	v_pk_fma_f32 v[116:117], v[46:47], v[80:81], v[116:117] op_sel:[0,1,0]
	v_pk_fma_f32 v[118:119], v[48:49], v[80:81], v[118:119] op_sel_hi:[1,0,1]
	v_pk_fma_f32 v[120:121], v[48:49], v[80:81], v[120:121] op_sel:[0,1,0]
	v_pk_fma_f32 v[72:73], v[72:73], v[38:39], v[114:115]
	v_pk_fma_f32 v[76:77], v[76:77], v[38:39], v[116:117]
	v_pk_fma_f32 v[74:75], v[74:75], v[40:41], v[118:119]
	v_pk_fma_f32 v[78:79], v[78:79], v[40:41], v[120:121]
	v_pk_mul_f32 v[122:123], v[72:73], v[42:43]
	v_pk_mul_f32 v[124:125], v[76:77], v[42:43]
	v_pk_fma_f32 v[122:123], v[74:75], v[44:45], v[122:123]
	v_pk_fma_f32 v[124:125], v[78:79], v[44:45], v[124:125]
	v_add_f32_e32 v126, v122, v123
	v_add_f32_e32 v127, v124, v125
	ds_write_b64 v187, v[126:127] offset:61440
	s_waitcnt lgkmcnt(2)
	v_pk_mul_f32 v[106:107], v[72:73], v[84:85]
	v_pk_mul_f32 v[108:109], v[76:77], v[84:85]
	v_pk_fma_f32 v[106:107], v[74:75], v[86:87], v[106:107]
	v_pk_fma_f32 v[108:109], v[78:79], v[86:87], v[108:109]
	v_add_f32_e32 v110, v106, v107
	v_add_f32_e32 v112, v108, v109
	s_nop 0
	v_add_f32_dpp v110, v110, v110 quad_perm:[1,0,3,2] row_mask:0xf bank_mask:0xf bound_ctrl:1
	v_add_f32_dpp v112, v112, v112 quad_perm:[1,0,3,2] row_mask:0xf bank_mask:0xf bound_ctrl:1
	s_nop 0
	v_add_f32_dpp v110, v110, v110 quad_perm:[2,3,0,1] row_mask:0xf bank_mask:0xf bound_ctrl:1
	v_add_f32_dpp v112, v112, v112 quad_perm:[2,3,0,1] row_mask:0xf bank_mask:0xf bound_ctrl:1
	s_nop 0
	v_add_f32_dpp v110, v110, v110 row_half_mirror row_mask:0xf bank_mask:0xf bound_ctrl:1
	v_add_f32_dpp v112, v112, v112 row_half_mirror row_mask:0xf bank_mask:0xf bound_ctrl:1
	s_nop 0
	v_add_f32_dpp v110, v110, v110 row_ror:8 row_mask:0xf bank_mask:0xf bound_ctrl:1
	v_add_f32_dpp v112, v112, v112 row_ror:8 row_mask:0xf bank_mask:0xf bound_ctrl:1
	v_pk_mul_f32 v[114:115], v[88:89], v[110:111] op_sel_hi:[1,0]
	v_pk_mul_f32 v[116:117], v[88:89], v[112:113] op_sel_hi:[1,0]
	v_pk_mul_f32 v[118:119], v[90:91], v[110:111] op_sel_hi:[1,0]
	v_pk_mul_f32 v[120:121], v[90:91], v[112:113] op_sel_hi:[1,0]
	v_pk_fma_f32 v[114:115], v[100:101], v[104:105], v[114:115] op_sel_hi:[1,0,1]
	v_pk_fma_f32 v[116:117], v[100:101], v[104:105], v[116:117] op_sel:[0,1,0]
	v_pk_fma_f32 v[118:119], v[102:103], v[104:105], v[118:119] op_sel_hi:[1,0,1]
	v_pk_fma_f32 v[120:121], v[102:103], v[104:105], v[120:121] op_sel:[0,1,0]
	v_pk_fma_f32 v[72:73], v[72:73], v[92:93], v[114:115]
	v_pk_fma_f32 v[76:77], v[76:77], v[92:93], v[116:117]
	v_pk_fma_f32 v[74:75], v[74:75], v[94:95], v[118:119]
	v_pk_fma_f32 v[78:79], v[78:79], v[94:95], v[120:121]
	v_pk_mul_f32 v[122:123], v[72:73], v[96:97]
	v_pk_mul_f32 v[124:125], v[76:77], v[96:97]
	v_pk_fma_f32 v[122:123], v[74:75], v[98:99], v[122:123]
	v_pk_fma_f32 v[124:125], v[78:79], v[98:99], v[124:125]
	v_add_f32_e32 v126, v122, v123
	v_add_f32_e32 v127, v124, v125
	ds_write_b64 v187, v[126:127] offset:63488
